# GEMM rolled K-loops: first K iteration peeled with srcC=0 MFMAs, 128 per-tile accumulator zero-init v_movs deleted (on v32)
# speedup vs baseline: 1.0107x; 1.0107x over previous
; #define PG8_STAGE(bufoff, gbase, voff) do { _Pragma("unroll") for (int _i = 0; _i < 2; ++_i) \
;         __builtin_amdgcn_global_load_lds((const unsigned*)((const char*)(gbase) + (voff)[_i]), (LAS unsigned*)(lds + (bufoff) + ldsw + _i * 8192), 16, 0, 0); } while (0)
; #define PG8_LDA(dst, b, h) do { _Pragma("unroll") for (int m = 0; m < 4; ++m) _Pragma("unroll") for (int k = 0; k < 2; ++k) dst[m][k] = *(const LAS bf16x8*)(lds + PG8_SA(b, h) + aoff + m * 2048 + k * 1024); } while (0)
; #define PG8_LDB(dst, b, h) do { _Pragma("unroll") for (int n = 0; n < 2; ++n) _Pragma("unroll") for (int k = 0; k < 2; ++k) dst[n][k] = *(const LAS bf16x8*)(lds + PG8_SB(b, h) + boff + n * 2048 + k * 1024); } while (0)
; #define PG8_MMA(ai, bj, At, Bt) do { __builtin_amdgcn_s_setprio(1); _Pragma("unroll") for (int m = 0; m < 4; ++m) _Pragma("unroll") for (int n = 0; n < 2; ++n) _Pragma("unroll") for (int k = 0; k < 2; ++k) \
;         acc[ai][bj][m][n] = __builtin_amdgcn_mfma_f32_16x16x32_bf16(Bt[n][k], At[m][k], acc[ai][bj][m][n], 0, 0, 0); __builtin_amdgcn_s_setprio(0); } while (0)
; template <class Epi, bool ALIGN_EPI, int K, int LDA, int LDB>
; __device__ __forceinline__ void gemm_phase(LAS unsigned char* lds, const int wid, const Gemm g, const StaticOrder& S, const Epi& E) {
;     ...
;         const bool has_next = S.next(ui + 1, nxt);
;         const char* nA = has_next ? (const char*)g.A + (size_t)nxt.pm * tA : cA; const char* nB = has_next ? (const char*)g.Bt + (size_t)nxt.pn * tB : cB;
;         for (int t = 0; t < nt; t += 2) {
;             const bool last = (t == nt - 2);
;             const char* a1 = cA + (size_t)(t + 1) * kstep;
;             const char* a2 = last ? nA : cA + (size_t)(t + 2) * kstep; const char* b2 = last ? nB : cB + (size_t)(t + 2) * kstep;
;             const char* a3 = a2 + kstep; const char* b3 = b2 + kstep;
;             PG8_LDB(B0, 0, 0); PG8_LDB(B1, 0, 1); PG8_SCHED; PG8_LDA(At, 0, 0); PG8_STAGE(PG8_SA(1, 1), a1 + hA, voffA);
;             PG8_WAIT_V(8); PG8_WAIT_L(0); PG8_BAR; PG8_MMA(0, 0, At, B0); PG8_MMA(0, 1, At, B1); PG8_BAR; PG8_SCHED;
;             PG8_LDA(At, 0, 1); PG8_STAGE(PG8_SB(0, 0), b2, voffB); PG8_STAGE(PG8_SB(0, 1), b2 + hB, voffB); PG8_STAGE(PG8_SA(0, 0), a2, voffA);
;             PG8_WAIT_V(8); PG8_WAIT_L(0); PG8_BAR; PG8_MMA(1, 0, At, B0); PG8_MMA(1, 1, At, B1); PG8_BAR; PG8_SCHED;
.LBB0_231:
	s_ashr_i32 s17, s16, 31
	s_lshl_b64 s[18:19], s[16:17], 19
	v_readlane_b32 s15, v254, 0
	s_add_u32 s18, s15, s18
	v_readlane_b32 s15, v254, 1
	s_addc_u32 s19, s15, s19
	s_and_b64 s[20:21], s[4:5], exec
	s_cselect_b32 s17, s19, s23
	s_cselect_b32 s48, s18, s22
	s_ashr_i32 s15, s14, 31
	s_lshl_b64 s[20:21], s[14:15], 19
	s_add_u32 s20, s0, s20
	s_addc_u32 s21, s1, s21
	s_and_b64 s[26:27], s[4:5], exec
	s_cselect_b32 s15, s21, s25
	s_cselect_b32 s49, s20, s24
	s_add_u32 s22, s22, 0x40080
	s_addc_u32 s23, s23, 0
	s_add_u32 s51, s24, 0x100
	s_addc_u32 s54, s25, 0
	s_mov_b32 s55, -2
	ds_read_b128 v[148:151], v145
	ds_read_b128 v[152:155], v145 offset:1024
	ds_read_b128 v[156:159], v145 offset:2048
	ds_read_b128 v[160:163], v145 offset:3072
	ds_read_b128 v[164:167], v146
	ds_read_b128 v[168:171], v146 offset:1024
	ds_read_b128 v[172:175], v146 offset:2048
	ds_read_b128 v[176:179], v146 offset:3072
	s_add_u32 s24, s22, 0xfffc0080
	s_addc_u32 s25, s23, -1
	s_cmp_eq_u32 s55, 12
	s_cselect_b32 s27, s17, s25
	s_cselect_b32 s26, s48, s24
	s_cselect_b32 s25, s15, s54
	s_cselect_b32 s24, s49, s51
	s_add_i32 m0, s13, 0xc000
	ds_read_b128 v[180:183], v147
	ds_read_b128 v[184:187], v147 offset:1024
	ds_read_b128 v[188:191], v147 offset:2048
	ds_read_b128 v[192:195], v147 offset:3072
	ds_read_b128 v[196:199], v147 offset:4096
	ds_read_b128 v[200:203], v147 offset:5120
	ds_read_b128 v[204:207], v147 offset:6144
	ds_read_b128 v[208:211], v147 offset:7168
	global_load_lds_dwordx4 v136, s[22:23]
	s_add_i32 m0, s13, 0xe000
	s_nop 0
	global_load_lds_dwordx4 v138, s[22:23]
	s_waitcnt vmcnt(8)
	s_waitcnt lgkmcnt(0)
	s_barrier
	s_setprio 1
	s_waitcnt lgkmcnt(0)
	v_mfma_f32_16x16x32_bf16 v[124:127], v[148:151], v[180:183], 0
	v_mfma_f32_16x16x32_bf16 v[120:123], v[156:159], v[180:183], 0
	v_mfma_f32_16x16x32_bf16 v[116:119], v[148:151], v[188:191], 0
	v_mfma_f32_16x16x32_bf16 v[112:115], v[156:159], v[188:191], 0
	v_mfma_f32_16x16x32_bf16 v[100:103], v[148:151], v[196:199], 0
	v_mfma_f32_16x16x32_bf16 v[96:99], v[156:159], v[196:199], 0
	v_mfma_f32_16x16x32_bf16 v[84:87], v[148:151], v[204:207], 0
	v_mfma_f32_16x16x32_bf16 v[80:83], v[156:159], v[204:207], 0
	v_mfma_f32_16x16x32_bf16 v[124:127], v[152:155], v[184:187], v[124:127]
	v_mfma_f32_16x16x32_bf16 v[120:123], v[160:163], v[184:187], v[120:123]
	v_mfma_f32_16x16x32_bf16 v[116:119], v[152:155], v[192:195], v[116:119]
	v_mfma_f32_16x16x32_bf16 v[112:115], v[160:163], v[192:195], v[112:115]
	v_mfma_f32_16x16x32_bf16 v[100:103], v[152:155], v[200:203], v[100:103]
	v_mfma_f32_16x16x32_bf16 v[96:99], v[160:163], v[200:203], v[96:99]
	v_mfma_f32_16x16x32_bf16 v[84:87], v[152:155], v[208:211], v[84:87]
	v_mfma_f32_16x16x32_bf16 v[80:83], v[160:163], v[208:211], v[80:83]
	v_mfma_f32_16x16x32_bf16 v[108:111], v[164:167], v[180:183], 0
	v_mfma_f32_16x16x32_bf16 v[104:107], v[172:175], v[180:183], 0
	v_mfma_f32_16x16x32_bf16 v[92:95], v[164:167], v[188:191], 0
	v_mfma_f32_16x16x32_bf16 v[88:91], v[172:175], v[188:191], 0
	v_mfma_f32_16x16x32_bf16 v[76:79], v[164:167], v[196:199], 0
	v_mfma_f32_16x16x32_bf16 v[72:75], v[172:175], v[196:199], 0
	v_mfma_f32_16x16x32_bf16 v[68:71], v[164:167], v[204:207], 0
	v_mfma_f32_16x16x32_bf16 v[64:67], v[172:175], v[204:207], 0
	v_mfma_f32_16x16x32_bf16 v[108:111], v[168:171], v[184:187], v[108:111]
	v_mfma_f32_16x16x32_bf16 v[104:107], v[176:179], v[184:187], v[104:107]
	v_mfma_f32_16x16x32_bf16 v[92:95], v[168:171], v[192:195], v[92:95]
	v_mfma_f32_16x16x32_bf16 v[88:91], v[176:179], v[192:195], v[88:91]
	v_mfma_f32_16x16x32_bf16 v[76:79], v[168:171], v[200:203], v[76:79]
	v_mfma_f32_16x16x32_bf16 v[72:75], v[176:179], v[200:203], v[72:75]
	v_mfma_f32_16x16x32_bf16 v[68:71], v[168:171], v[208:211], v[68:71]
	v_mfma_f32_16x16x32_bf16 v[64:67], v[176:179], v[208:211], v[64:67]
	s_setprio 0
	s_barrier
	s_add_u32 s98, s24, s10
	s_addc_u32 s99, s25, s11
	s_add_u32 s100, s26, s10
	s_addc_u32 s101, s27, s11
	s_add_i32 s56, s40, s3
	s_mov_b32 m0, s56
	ds_read_b128 v[180:183], v147 offset:16384
	ds_read_b128 v[184:187], v147 offset:17408
	ds_read_b128 v[188:191], v147 offset:18432
	ds_read_b128 v[192:195], v147 offset:19456
	ds_read_b128 v[196:199], v147 offset:20480
	ds_read_b128 v[200:203], v147 offset:21504
	ds_read_b128 v[204:207], v147 offset:22528
	ds_read_b128 v[208:211], v147 offset:23552
	global_load_lds_dwordx4 v132, s[24:25]
	s_add_i32 m0, s56, 0x2000
	s_add_u32 s56, s24, 0x40000
	s_addc_u32 s57, s25, 0
	s_add_i32 s58, s41, s3
	global_load_lds_dwordx4 v128, s[24:25]
	s_mov_b32 m0, s58
	s_nop 0
	global_load_lds_dwordx4 v132, s[56:57]
	s_add_i32 m0, s58, 0x2000
	s_nop 0
	global_load_lds_dwordx4 v128, s[56:57]
	s_mov_b32 m0, s13
	s_nop 0
	global_load_lds_dwordx4 v134, s[26:27]
	s_mov_b32 m0, s30
	s_nop 0
	global_load_lds_dwordx4 v130, s[26:27]
	s_waitcnt vmcnt(8)
	s_waitcnt lgkmcnt(0)
	s_barrier
; #define PG8_STAGE(bufoff, gbase, voff) do { _Pragma("unroll") for (int _i = 0; _i < 2; ++_i) \
;         __builtin_amdgcn_global_load_lds((const unsigned*)((const char*)(gbase) + (voff)[_i]), (LAS unsigned*)(lds + (bufoff) + ldsw + _i * 8192), 16, 0, 0); } while (0)
; #define PG8_LDA(dst, b, h) do { _Pragma("unroll") for (int m = 0; m < 4; ++m) _Pragma("unroll") for (int k = 0; k < 2; ++k) dst[m][k] = *(const LAS bf16x8*)(lds + PG8_SA(b, h) + aoff + m * 2048 + k * 1024); } while (0)
; #define PG8_LDB(dst, b, h) do { _Pragma("unroll") for (int n = 0; n < 2; ++n) _Pragma("unroll") for (int k = 0; k < 2; ++k) dst[n][k] = *(const LAS bf16x8*)(lds + PG8_SB(b, h) + boff + n * 2048 + k * 1024); } while (0)
; #define PG8_MMA(ai, bj, At, Bt) do { __builtin_amdgcn_s_setprio(1); _Pragma("unroll") for (int m = 0; m < 4; ++m) _Pragma("unroll") for (int n = 0; n < 2; ++n) _Pragma("unroll") for (int k = 0; k < 2; ++k) \
;         acc[ai][bj][m][n] = __builtin_amdgcn_mfma_f32_16x16x32_bf16(Bt[n][k], At[m][k], acc[ai][bj][m][n], 0, 0, 0); __builtin_amdgcn_s_setprio(0); } while (0)
; #define PG8_WAIT_V(n) asm volatile("s_waitcnt vmcnt(" #n ")" ::: "memory")
; #define PG8_WAIT_L(n) asm volatile("s_waitcnt lgkmcnt(" #n ")" ::: "memory")
; #define PG8_BAR __builtin_amdgcn_s_barrier()
; #define PG8_SCHED __builtin_amdgcn_sched_barrier(0)
; template <class Epi, bool ALIGN_EPI, int K, int LDA, int LDB>
; __device__ __forceinline__ void gemm_phase(LAS unsigned char* lds, const int wid, const Gemm g, const StaticOrder& S, const Epi& E) {
;     ...
;             PG8_WAIT_V(8); PG8_WAIT_L(0); PG8_BAR; PG8_MMA(1, 0, At, B0); PG8_MMA(1, 1, At, B1); PG8_BAR; PG8_SCHED;
;             PG8_LDB(B0, 1, 0); PG8_LDB(B1, 1, 1); PG8_SCHED; PG8_LDA(At, 1, 0); PG8_STAGE(PG8_SA(0, 1), a2 + hA, voffA);
;             PG8_WAIT_V(8); PG8_WAIT_L(0); PG8_BAR; PG8_MMA(0, 0, At, B0); PG8_MMA(0, 1, At, B1); PG8_BAR; PG8_SCHED;
;             PG8_LDA(At, 1, 1); PG8_STAGE(PG8_SB(1, 0), b3, voffB); PG8_STAGE(PG8_SB(1, 1), b3 + hB, voffB); PG8_STAGE(PG8_SA(1, 0), a3, voffA);
;             PG8_WAIT_V(8); PG8_WAIT_L(0); PG8_BAR; PG8_MMA(1, 0, At, B0); PG8_MMA(1, 1, At, B1); PG8_BAR; PG8_SCHED;
	s_setprio 1
	s_waitcnt lgkmcnt(0)
	v_mfma_f32_16x16x32_bf16 v[60:63], v[148:151], v[180:183], 0
	v_mfma_f32_16x16x32_bf16 v[56:59], v[156:159], v[180:183], 0
	v_mfma_f32_16x16x32_bf16 v[52:55], v[148:151], v[188:191], 0
	v_mfma_f32_16x16x32_bf16 v[48:51], v[156:159], v[188:191], 0
	v_mfma_f32_16x16x32_bf16 v[36:39], v[148:151], v[196:199], 0
	v_mfma_f32_16x16x32_bf16 v[32:35], v[156:159], v[196:199], 0
	v_mfma_f32_16x16x32_bf16 v[20:23], v[148:151], v[204:207], 0
	v_mfma_f32_16x16x32_bf16 v[16:19], v[156:159], v[204:207], 0
	v_mfma_f32_16x16x32_bf16 v[60:63], v[152:155], v[184:187], v[60:63]
	v_mfma_f32_16x16x32_bf16 v[56:59], v[160:163], v[184:187], v[56:59]
	v_mfma_f32_16x16x32_bf16 v[52:55], v[152:155], v[192:195], v[52:55]
	v_mfma_f32_16x16x32_bf16 v[48:51], v[160:163], v[192:195], v[48:51]
	v_mfma_f32_16x16x32_bf16 v[36:39], v[152:155], v[200:203], v[36:39]
	v_mfma_f32_16x16x32_bf16 v[32:35], v[160:163], v[200:203], v[32:35]
	v_mfma_f32_16x16x32_bf16 v[20:23], v[152:155], v[208:211], v[20:23]
	v_mfma_f32_16x16x32_bf16 v[16:19], v[160:163], v[208:211], v[16:19]
	v_mfma_f32_16x16x32_bf16 v[44:47], v[164:167], v[180:183], 0
	v_mfma_f32_16x16x32_bf16 v[40:43], v[172:175], v[180:183], 0
	v_mfma_f32_16x16x32_bf16 v[28:31], v[164:167], v[188:191], 0
	v_mfma_f32_16x16x32_bf16 v[24:27], v[172:175], v[188:191], 0
	v_mfma_f32_16x16x32_bf16 v[12:15], v[164:167], v[196:199], 0
	v_mfma_f32_16x16x32_bf16 v[8:11], v[172:175], v[196:199], 0
	v_mfma_f32_16x16x32_bf16 v[4:7], v[164:167], v[204:207], 0
	v_mfma_f32_16x16x32_bf16 v[0:3], v[172:175], v[204:207], 0
	v_mfma_f32_16x16x32_bf16 v[44:47], v[168:171], v[184:187], v[44:47]
	v_mfma_f32_16x16x32_bf16 v[40:43], v[176:179], v[184:187], v[40:43]
	v_mfma_f32_16x16x32_bf16 v[28:31], v[168:171], v[192:195], v[28:31]
	v_mfma_f32_16x16x32_bf16 v[24:27], v[176:179], v[192:195], v[24:27]
	v_mfma_f32_16x16x32_bf16 v[12:15], v[168:171], v[200:203], v[12:15]
	v_mfma_f32_16x16x32_bf16 v[8:11], v[176:179], v[200:203], v[8:11]
	v_mfma_f32_16x16x32_bf16 v[4:7], v[168:171], v[208:211], v[4:7]
	v_mfma_f32_16x16x32_bf16 v[0:3], v[176:179], v[208:211], v[0:3]
	s_setprio 0
	s_barrier
	s_add_i32 s56, 0, 0x18000
	s_add_i32 s57, 0, 0x1c000
	v_add_u32_e32 v160, s56, v144
	v_add_u32_e32 v176, s57, v144
	ds_read_b128 v[148:151], v160
	ds_read_b128 v[152:155], v160 offset:1024
	ds_read_b128 v[156:159], v160 offset:2048
	ds_read_b128 v[160:163], v160 offset:3072
	ds_read_b128 v[164:167], v176
	ds_read_b128 v[168:171], v176 offset:1024
	ds_read_b128 v[172:175], v176 offset:2048
	ds_read_b128 v[176:179], v176 offset:3072
	s_add_u32 s26, s26, 0x40000
	s_addc_u32 s27, s27, 0
	s_mov_b32 m0, s31
	ds_read_b128 v[180:183], v147 offset:32768
	ds_read_b128 v[184:187], v147 offset:33792
	ds_read_b128 v[188:191], v147 offset:34816
	ds_read_b128 v[192:195], v147 offset:35840
	ds_read_b128 v[196:199], v147 offset:36864
	ds_read_b128 v[200:203], v147 offset:37888
	ds_read_b128 v[204:207], v147 offset:38912
	ds_read_b128 v[208:211], v147 offset:39936
	global_load_lds_dwordx4 v134, s[26:27]
	s_mov_b32 m0, s33
	s_nop 0
	global_load_lds_dwordx4 v130, s[26:27]
	s_waitcnt vmcnt(8)
	s_waitcnt lgkmcnt(0)
	s_barrier
	s_setprio 1
	s_waitcnt lgkmcnt(0)
	v_mfma_f32_16x16x32_bf16 v[124:127], v[148:151], v[180:183], v[124:127]
	v_mfma_f32_16x16x32_bf16 v[120:123], v[156:159], v[180:183], v[120:123]
	v_mfma_f32_16x16x32_bf16 v[116:119], v[148:151], v[188:191], v[116:119]
	v_mfma_f32_16x16x32_bf16 v[112:115], v[156:159], v[188:191], v[112:115]
	v_mfma_f32_16x16x32_bf16 v[100:103], v[148:151], v[196:199], v[100:103]
	v_mfma_f32_16x16x32_bf16 v[96:99], v[156:159], v[196:199], v[96:99]
	v_mfma_f32_16x16x32_bf16 v[84:87], v[148:151], v[204:207], v[84:87]
	v_mfma_f32_16x16x32_bf16 v[80:83], v[156:159], v[204:207], v[80:83]
	v_mfma_f32_16x16x32_bf16 v[124:127], v[152:155], v[184:187], v[124:127]
	v_mfma_f32_16x16x32_bf16 v[120:123], v[160:163], v[184:187], v[120:123]
	v_mfma_f32_16x16x32_bf16 v[116:119], v[152:155], v[192:195], v[116:119]
	v_mfma_f32_16x16x32_bf16 v[112:115], v[160:163], v[192:195], v[112:115]
	v_mfma_f32_16x16x32_bf16 v[100:103], v[152:155], v[200:203], v[100:103]
	v_mfma_f32_16x16x32_bf16 v[96:99], v[160:163], v[200:203], v[96:99]
	v_mfma_f32_16x16x32_bf16 v[84:87], v[152:155], v[208:211], v[84:87]
	v_mfma_f32_16x16x32_bf16 v[80:83], v[160:163], v[208:211], v[80:83]
	v_mfma_f32_16x16x32_bf16 v[108:111], v[164:167], v[180:183], v[108:111]
	v_mfma_f32_16x16x32_bf16 v[104:107], v[172:175], v[180:183], v[104:107]
	v_mfma_f32_16x16x32_bf16 v[92:95], v[164:167], v[188:191], v[92:95]
	v_mfma_f32_16x16x32_bf16 v[88:91], v[172:175], v[188:191], v[88:91]
	v_mfma_f32_16x16x32_bf16 v[76:79], v[164:167], v[196:199], v[76:79]
	v_mfma_f32_16x16x32_bf16 v[72:75], v[172:175], v[196:199], v[72:75]
	v_mfma_f32_16x16x32_bf16 v[68:71], v[164:167], v[204:207], v[68:71]
	v_mfma_f32_16x16x32_bf16 v[64:67], v[172:175], v[204:207], v[64:67]
	v_mfma_f32_16x16x32_bf16 v[108:111], v[168:171], v[184:187], v[108:111]
	v_mfma_f32_16x16x32_bf16 v[104:107], v[176:179], v[184:187], v[104:107]
	v_mfma_f32_16x16x32_bf16 v[92:95], v[168:171], v[192:195], v[92:95]
	v_mfma_f32_16x16x32_bf16 v[88:91], v[176:179], v[192:195], v[88:91]
	v_mfma_f32_16x16x32_bf16 v[76:79], v[168:171], v[200:203], v[76:79]
	v_mfma_f32_16x16x32_bf16 v[72:75], v[176:179], v[200:203], v[72:75]
	v_mfma_f32_16x16x32_bf16 v[68:71], v[168:171], v[208:211], v[68:71]
	v_mfma_f32_16x16x32_bf16 v[64:67], v[176:179], v[208:211], v[64:67]
	s_setprio 0
	s_barrier
; #define PG8_STAGE(bufoff, gbase, voff) do { _Pragma("unroll") for (int _i = 0; _i < 2; ++_i) \
;         __builtin_amdgcn_global_load_lds((const unsigned*)((const char*)(gbase) + (voff)[_i]), (LAS unsigned*)(lds + (bufoff) + ldsw + _i * 8192), 16, 0, 0); } while (0)
; #define PG8_LDA(dst, b, h) do { _Pragma("unroll") for (int m = 0; m < 4; ++m) _Pragma("unroll") for (int k = 0; k < 2; ++k) dst[m][k] = *(const LAS bf16x8*)(lds + PG8_SA(b, h) + aoff + m * 2048 + k * 1024); } while (0)
; #define PG8_MMA(ai, bj, At, Bt) do { __builtin_amdgcn_s_setprio(1); _Pragma("unroll") for (int m = 0; m < 4; ++m) _Pragma("unroll") for (int n = 0; n < 2; ++n) _Pragma("unroll") for (int k = 0; k < 2; ++k) \
;         acc[ai][bj][m][n] = __builtin_amdgcn_mfma_f32_16x16x32_bf16(Bt[n][k], At[m][k], acc[ai][bj][m][n], 0, 0, 0); __builtin_amdgcn_s_setprio(0); } while (0)
; #define PG8_WAIT_V(n) asm volatile("s_waitcnt vmcnt(" #n ")" ::: "memory")
; #define PG8_WAIT_L(n) asm volatile("s_waitcnt lgkmcnt(" #n ")" ::: "memory")
; #define PG8_BAR __builtin_amdgcn_s_barrier()
; #define PG8_SCHED __builtin_amdgcn_sched_barrier(0)
; template <class Epi, bool ALIGN_EPI, int K, int LDA, int LDB>
; __device__ __forceinline__ void gemm_phase(LAS unsigned char* lds, const int wid, const Gemm g, const StaticOrder& S, const Epi& E) {
;     ...
;             PG8_LDA(At, 1, 1); PG8_STAGE(PG8_SB(1, 0), b3, voffB); PG8_STAGE(PG8_SB(1, 1), b3 + hB, voffB); PG8_STAGE(PG8_SA(1, 0), a3, voffA);
;             PG8_WAIT_V(8); PG8_WAIT_L(0); PG8_BAR; PG8_MMA(1, 0, At, B0); PG8_MMA(1, 1, At, B1); PG8_BAR; PG8_SCHED;
;         }
	s_add_i32 s26, s56, s3
	s_mov_b32 m0, s26
	ds_read_b128 v[180:183], v147 offset:49152
	ds_read_b128 v[184:187], v147 offset:50176
	ds_read_b128 v[188:191], v147 offset:51200
	ds_read_b128 v[192:195], v147 offset:52224
	ds_read_b128 v[196:199], v147 offset:53248
	ds_read_b128 v[200:203], v147 offset:54272
	ds_read_b128 v[204:207], v147 offset:55296
	ds_read_b128 v[208:211], v147 offset:56320
	global_load_lds_dwordx4 v132, s[98:99]
	s_add_i32 m0, s26, 0x2000
	s_add_u32 s24, s24, 0x40080
	s_addc_u32 s25, s25, 0
	s_add_i32 s26, s57, s3
	global_load_lds_dwordx4 v128, s[98:99]
	s_mov_b32 m0, s26
	s_nop 0
	global_load_lds_dwordx4 v132, s[24:25]
	s_add_i32 m0, s26, 0x2000
	s_nop 0
	global_load_lds_dwordx4 v128, s[24:25]
	s_mov_b32 m0, s38
	s_nop 0
	global_load_lds_dwordx4 v134, s[100:101]
	s_mov_b32 m0, s39
	s_nop 0
	global_load_lds_dwordx4 v130, s[100:101]
	s_waitcnt vmcnt(8)
	s_waitcnt lgkmcnt(0)
	s_barrier
	s_setprio 1
	s_waitcnt lgkmcnt(0)
	v_mfma_f32_16x16x32_bf16 v[60:63], v[148:151], v[180:183], v[60:63]
	v_mfma_f32_16x16x32_bf16 v[56:59], v[156:159], v[180:183], v[56:59]
	v_mfma_f32_16x16x32_bf16 v[52:55], v[148:151], v[188:191], v[52:55]
	v_mfma_f32_16x16x32_bf16 v[48:51], v[156:159], v[188:191], v[48:51]
	v_mfma_f32_16x16x32_bf16 v[36:39], v[148:151], v[196:199], v[36:39]
	v_mfma_f32_16x16x32_bf16 v[32:35], v[156:159], v[196:199], v[32:35]
	v_mfma_f32_16x16x32_bf16 v[20:23], v[148:151], v[204:207], v[20:23]
	v_mfma_f32_16x16x32_bf16 v[16:19], v[156:159], v[204:207], v[16:19]
	v_mfma_f32_16x16x32_bf16 v[60:63], v[152:155], v[184:187], v[60:63]
	v_mfma_f32_16x16x32_bf16 v[56:59], v[160:163], v[184:187], v[56:59]
	v_mfma_f32_16x16x32_bf16 v[52:55], v[152:155], v[192:195], v[52:55]
	v_mfma_f32_16x16x32_bf16 v[48:51], v[160:163], v[192:195], v[48:51]
	v_mfma_f32_16x16x32_bf16 v[36:39], v[152:155], v[200:203], v[36:39]
	v_mfma_f32_16x16x32_bf16 v[32:35], v[160:163], v[200:203], v[32:35]
	v_mfma_f32_16x16x32_bf16 v[20:23], v[152:155], v[208:211], v[20:23]
	v_mfma_f32_16x16x32_bf16 v[16:19], v[160:163], v[208:211], v[16:19]
	v_mfma_f32_16x16x32_bf16 v[44:47], v[164:167], v[180:183], v[44:47]
	v_mfma_f32_16x16x32_bf16 v[40:43], v[172:175], v[180:183], v[40:43]
	v_mfma_f32_16x16x32_bf16 v[28:31], v[164:167], v[188:191], v[28:31]
	v_mfma_f32_16x16x32_bf16 v[24:27], v[172:175], v[188:191], v[24:27]
	v_mfma_f32_16x16x32_bf16 v[12:15], v[164:167], v[196:199], v[12:15]
	v_mfma_f32_16x16x32_bf16 v[8:11], v[172:175], v[196:199], v[8:11]
	v_mfma_f32_16x16x32_bf16 v[4:7], v[164:167], v[204:207], v[4:7]
	v_mfma_f32_16x16x32_bf16 v[0:3], v[172:175], v[204:207], v[0:3]
	v_mfma_f32_16x16x32_bf16 v[44:47], v[168:171], v[184:187], v[44:47]
	v_mfma_f32_16x16x32_bf16 v[40:43], v[176:179], v[184:187], v[40:43]
	v_mfma_f32_16x16x32_bf16 v[28:31], v[168:171], v[192:195], v[28:31]
	v_mfma_f32_16x16x32_bf16 v[24:27], v[176:179], v[192:195], v[24:27]
	v_mfma_f32_16x16x32_bf16 v[12:15], v[168:171], v[200:203], v[12:15]
	v_mfma_f32_16x16x32_bf16 v[8:11], v[176:179], v[200:203], v[8:11]
	v_mfma_f32_16x16x32_bf16 v[4:7], v[168:171], v[208:211], v[4:7]
	v_mfma_f32_16x16x32_bf16 v[0:3], v[176:179], v[208:211], v[0:3]
	s_setprio 0
	s_barrier
	s_add_i32 s55, s55, 2
	s_add_u32 s22, s22, 0x100
	s_addc_u32 s23, s23, 0
	s_add_u32 s51, s51, 0x100
	s_addc_u32 s54, s54, 0

; #define PG8_STAGE(bufoff, gbase, voff) do { _Pragma("unroll") for (int _i = 0; _i < 2; ++_i) \
;         __builtin_amdgcn_global_load_lds((const unsigned*)((const char*)(gbase) + (voff)[_i]), (LAS unsigned*)(lds + (bufoff) + ldsw + _i * 8192), 16, 0, 0); } while (0)
; #define PG8_LDA(dst, b, h) do { _Pragma("unroll") for (int m = 0; m < 4; ++m) _Pragma("unroll") for (int k = 0; k < 2; ++k) dst[m][k] = *(const LAS bf16x8*)(lds + PG8_SA(b, h) + aoff + m * 2048 + k * 1024); } while (0)
; #define PG8_LDB(dst, b, h) do { _Pragma("unroll") for (int n = 0; n < 2; ++n) _Pragma("unroll") for (int k = 0; k < 2; ++k) dst[n][k] = *(const LAS bf16x8*)(lds + PG8_SB(b, h) + boff + n * 2048 + k * 1024); } while (0)
; #define PG8_MMA(ai, bj, At, Bt) do { __builtin_amdgcn_s_setprio(1); _Pragma("unroll") for (int m = 0; m < 4; ++m) _Pragma("unroll") for (int n = 0; n < 2; ++n) _Pragma("unroll") for (int k = 0; k < 2; ++k) \
;         acc[ai][bj][m][n] = __builtin_amdgcn_mfma_f32_16x16x32_bf16(Bt[n][k], At[m][k], acc[ai][bj][m][n], 0, 0, 0); __builtin_amdgcn_s_setprio(0); } while (0)
; template <class Epi, bool ALIGN_EPI, int K, int LDA, int LDB>
; __device__ __forceinline__ void gemm_phase(LAS unsigned char* lds, const int wid, const Gemm g, const StaticOrder& S, const Epi& E) {
;     ...
;         const bool has_next = S.next(ui + 1, nxt);
;         const char* nA = has_next ? (const char*)g.A + (size_t)nxt.pm * tA : cA; const char* nB = has_next ? (const char*)g.Bt + (size_t)nxt.pn * tB : cB;
;         for (int t = 0; t < nt; t += 2) {
;             const bool last = (t == nt - 2);
;             const char* a1 = cA + (size_t)(t + 1) * kstep;
;             const char* a2 = last ? nA : cA + (size_t)(t + 2) * kstep; const char* b2 = last ? nB : cB + (size_t)(t + 2) * kstep;
;             const char* a3 = a2 + kstep; const char* b3 = b2 + kstep;
;             PG8_LDB(B0, 0, 0); PG8_LDB(B1, 0, 1); PG8_SCHED; PG8_LDA(At, 0, 0); PG8_STAGE(PG8_SA(1, 1), a1 + hA, voffA);
;             PG8_WAIT_V(8); PG8_WAIT_L(0); PG8_BAR; PG8_MMA(0, 0, At, B0); PG8_MMA(0, 1, At, B1); PG8_BAR; PG8_SCHED;
;             PG8_LDA(At, 0, 1); PG8_STAGE(PG8_SB(0, 0), b2, voffB); PG8_STAGE(PG8_SB(0, 1), b2 + hB, voffB); PG8_STAGE(PG8_SA(0, 0), a2, voffA);
;             PG8_WAIT_V(8); PG8_WAIT_L(0); PG8_BAR; PG8_MMA(1, 0, At, B0); PG8_MMA(1, 1, At, B1); PG8_BAR; PG8_SCHED;
.LBB0_916:
	s_ashr_i32 s27, s26, 31
	s_lshl_b64 s[28:29], s[26:27], 19
	v_readlane_b32 s25, v254, 0
	s_add_u32 s28, s25, s28
	v_readlane_b32 s25, v254, 1
	s_addc_u32 s29, s25, s29
	s_and_b64 s[30:31], s[4:5], exec
	s_cselect_b32 s27, s29, s37
	s_cselect_b32 s63, s28, s36
	s_ashr_i32 s25, s24, 31
	s_lshl_b64 s[30:31], s[24:25], 19
	s_add_u32 s30, s1, s30
	s_addc_u32 s31, s3, s31
	s_and_b64 s[40:41], s[4:5], exec
	s_cselect_b32 s25, s31, s39
	s_cselect_b32 s64, s30, s38
	s_add_u32 s36, s36, 0x40080
	s_addc_u32 s37, s37, 0
	s_add_u32 s65, s38, 0x100
	s_addc_u32 s66, s39, 0
	s_mov_b32 s67, -2
	s_waitcnt vmcnt(0)
	ds_read_b128 v[128:131], v163
	ds_read_b128 v[132:135], v163 offset:1024
	ds_read_b128 v[136:139], v163 offset:2048
	ds_read_b128 v[140:143], v163 offset:3072
	ds_read_b128 v[166:169], v164
	ds_read_b128 v[170:173], v164 offset:1024
	ds_read_b128 v[174:177], v164 offset:2048
	ds_read_b128 v[178:181], v164 offset:3072
	s_add_u32 s38, s36, 0xfffc0080
	s_addc_u32 s39, s37, -1
	s_cmp_eq_u32 s67, 12
	s_cselect_b32 s41, s27, s39
	s_cselect_b32 s40, s63, s38
	s_cselect_b32 s39, s25, s66
	s_cselect_b32 s38, s64, s65
	s_add_i32 m0, s35, 0xc000
	ds_read_b128 v[182:185], v165
	ds_read_b128 v[186:189], v165 offset:1024
	ds_read_b128 v[190:193], v165 offset:2048
	ds_read_b128 v[194:197], v165 offset:3072
	ds_read_b128 v[198:201], v165 offset:4096
	ds_read_b128 v[202:205], v165 offset:5120
	ds_read_b128 v[206:209], v165 offset:6144
	ds_read_b128 v[210:213], v165 offset:7168
	global_load_lds_dwordx4 v152, s[36:37]
	s_add_i32 m0, s35, 0xe000
	s_nop 0
	global_load_lds_dwordx4 v154, s[36:37]
	s_waitcnt vmcnt(8)
	s_waitcnt lgkmcnt(0)
	s_barrier
	s_setprio 1
	s_waitcnt lgkmcnt(0)
	v_mfma_f32_16x16x32_bf16 v[124:127], v[128:131], v[182:185], 0
	v_mfma_f32_16x16x32_bf16 v[120:123], v[136:139], v[182:185], 0
	v_mfma_f32_16x16x32_bf16 v[108:111], v[128:131], v[190:193], 0
	v_mfma_f32_16x16x32_bf16 v[104:107], v[136:139], v[190:193], 0
	v_mfma_f32_16x16x32_bf16 v[92:95], v[128:131], v[198:201], 0
	v_mfma_f32_16x16x32_bf16 v[88:91], v[136:139], v[198:201], 0
	v_mfma_f32_16x16x32_bf16 v[76:79], v[128:131], v[206:209], 0
	v_mfma_f32_16x16x32_bf16 v[72:75], v[136:139], v[206:209], 0
	v_mfma_f32_16x16x32_bf16 v[124:127], v[132:135], v[186:189], v[124:127]
	v_mfma_f32_16x16x32_bf16 v[120:123], v[140:143], v[186:189], v[120:123]
	v_mfma_f32_16x16x32_bf16 v[108:111], v[132:135], v[194:197], v[108:111]
	v_mfma_f32_16x16x32_bf16 v[104:107], v[140:143], v[194:197], v[104:107]
	v_mfma_f32_16x16x32_bf16 v[92:95], v[132:135], v[202:205], v[92:95]
	v_mfma_f32_16x16x32_bf16 v[88:91], v[140:143], v[202:205], v[88:91]
	v_mfma_f32_16x16x32_bf16 v[76:79], v[132:135], v[210:213], v[76:79]
	v_mfma_f32_16x16x32_bf16 v[72:75], v[140:143], v[210:213], v[72:75]
	v_mfma_f32_16x16x32_bf16 v[116:119], v[166:169], v[182:185], 0
	v_mfma_f32_16x16x32_bf16 v[112:115], v[174:177], v[182:185], 0
	v_mfma_f32_16x16x32_bf16 v[100:103], v[166:169], v[190:193], 0
	v_mfma_f32_16x16x32_bf16 v[96:99], v[174:177], v[190:193], 0
	v_mfma_f32_16x16x32_bf16 v[84:87], v[166:169], v[198:201], 0
	v_mfma_f32_16x16x32_bf16 v[80:83], v[174:177], v[198:201], 0
	v_mfma_f32_16x16x32_bf16 v[68:71], v[166:169], v[206:209], 0
	v_mfma_f32_16x16x32_bf16 v[64:67], v[174:177], v[206:209], 0
	v_mfma_f32_16x16x32_bf16 v[116:119], v[170:173], v[186:189], v[116:119]
	v_mfma_f32_16x16x32_bf16 v[112:115], v[178:181], v[186:189], v[112:115]
	v_mfma_f32_16x16x32_bf16 v[100:103], v[170:173], v[194:197], v[100:103]
	v_mfma_f32_16x16x32_bf16 v[96:99], v[178:181], v[194:197], v[96:99]
	v_mfma_f32_16x16x32_bf16 v[84:87], v[170:173], v[202:205], v[84:87]
	v_mfma_f32_16x16x32_bf16 v[80:83], v[178:181], v[202:205], v[80:83]
	v_mfma_f32_16x16x32_bf16 v[68:71], v[170:173], v[210:213], v[68:71]
	v_mfma_f32_16x16x32_bf16 v[64:67], v[178:181], v[210:213], v[64:67]
	s_setprio 0
	s_barrier
	s_add_u32 s98, s38, s12
	s_addc_u32 s99, s39, s13
	s_add_u32 s100, s40, s12
	s_addc_u32 s101, s41, s13
	s_add_i32 s52, s58, s33
	s_mov_b32 m0, s52
	ds_read_b128 v[182:185], v165 offset:16384
	ds_read_b128 v[186:189], v165 offset:17408
	ds_read_b128 v[190:193], v165 offset:18432
	ds_read_b128 v[194:197], v165 offset:19456
	ds_read_b128 v[198:201], v165 offset:20480
	ds_read_b128 v[202:205], v165 offset:21504
	ds_read_b128 v[206:209], v165 offset:22528
	ds_read_b128 v[210:213], v165 offset:23552
	global_load_lds_dwordx4 v146, s[38:39]
	s_add_i32 m0, s52, 0x2000
	s_add_u32 s68, s38, 0x40000
	s_addc_u32 s69, s39, 0
	s_add_i32 s52, s59, s33
	global_load_lds_dwordx4 v150, s[38:39]
	s_mov_b32 m0, s52
	s_nop 0
	global_load_lds_dwordx4 v146, s[68:69]
	s_add_i32 m0, s52, 0x2000
	s_nop 0
	global_load_lds_dwordx4 v150, s[68:69]
	s_mov_b32 m0, s35
	s_nop 0
	global_load_lds_dwordx4 v144, s[40:41]
	s_mov_b32 m0, s42
	s_nop 0
	global_load_lds_dwordx4 v148, s[40:41]
	s_waitcnt vmcnt(8)
	s_waitcnt lgkmcnt(0)
	s_barrier
; #define PG8_STAGE(bufoff, gbase, voff) do { _Pragma("unroll") for (int _i = 0; _i < 2; ++_i) \
;         __builtin_amdgcn_global_load_lds((const unsigned*)((const char*)(gbase) + (voff)[_i]), (LAS unsigned*)(lds + (bufoff) + ldsw + _i * 8192), 16, 0, 0); } while (0)
; #define PG8_LDA(dst, b, h) do { _Pragma("unroll") for (int m = 0; m < 4; ++m) _Pragma("unroll") for (int k = 0; k < 2; ++k) dst[m][k] = *(const LAS bf16x8*)(lds + PG8_SA(b, h) + aoff + m * 2048 + k * 1024); } while (0)
; #define PG8_LDB(dst, b, h) do { _Pragma("unroll") for (int n = 0; n < 2; ++n) _Pragma("unroll") for (int k = 0; k < 2; ++k) dst[n][k] = *(const LAS bf16x8*)(lds + PG8_SB(b, h) + boff + n * 2048 + k * 1024); } while (0)
; #define PG8_MMA(ai, bj, At, Bt) do { __builtin_amdgcn_s_setprio(1); _Pragma("unroll") for (int m = 0; m < 4; ++m) _Pragma("unroll") for (int n = 0; n < 2; ++n) _Pragma("unroll") for (int k = 0; k < 2; ++k) \
;         acc[ai][bj][m][n] = __builtin_amdgcn_mfma_f32_16x16x32_bf16(Bt[n][k], At[m][k], acc[ai][bj][m][n], 0, 0, 0); __builtin_amdgcn_s_setprio(0); } while (0)
; #define PG8_WAIT_V(n) asm volatile("s_waitcnt vmcnt(" #n ")" ::: "memory")
; #define PG8_WAIT_L(n) asm volatile("s_waitcnt lgkmcnt(" #n ")" ::: "memory")
; #define PG8_BAR __builtin_amdgcn_s_barrier()
; #define PG8_SCHED __builtin_amdgcn_sched_barrier(0)
; template <class Epi, bool ALIGN_EPI, int K, int LDA, int LDB>
; __device__ __forceinline__ void gemm_phase(LAS unsigned char* lds, const int wid, const Gemm g, const StaticOrder& S, const Epi& E) {
;     ...
;             PG8_WAIT_V(8); PG8_WAIT_L(0); PG8_BAR; PG8_MMA(1, 0, At, B0); PG8_MMA(1, 1, At, B1); PG8_BAR; PG8_SCHED;
;             PG8_LDB(B0, 1, 0); PG8_LDB(B1, 1, 1); PG8_SCHED; PG8_LDA(At, 1, 0); PG8_STAGE(PG8_SA(0, 1), a2 + hA, voffA);
;             PG8_WAIT_V(8); PG8_WAIT_L(0); PG8_BAR; PG8_MMA(0, 0, At, B0); PG8_MMA(0, 1, At, B1); PG8_BAR; PG8_SCHED;
;             PG8_LDA(At, 1, 1); PG8_STAGE(PG8_SB(1, 0), b3, voffB); PG8_STAGE(PG8_SB(1, 1), b3 + hB, voffB); PG8_STAGE(PG8_SA(1, 0), a3, voffA);
;             PG8_WAIT_V(8); PG8_WAIT_L(0); PG8_BAR; PG8_MMA(1, 0, At, B0); PG8_MMA(1, 1, At, B1); PG8_BAR; PG8_SCHED;
	s_setprio 1
	s_waitcnt lgkmcnt(0)
	v_mfma_f32_16x16x32_bf16 v[60:63], v[128:131], v[182:185], 0
	v_mfma_f32_16x16x32_bf16 v[56:59], v[136:139], v[182:185], 0
	v_mfma_f32_16x16x32_bf16 v[44:47], v[128:131], v[190:193], 0
	v_mfma_f32_16x16x32_bf16 v[40:43], v[136:139], v[190:193], 0
	v_mfma_f32_16x16x32_bf16 v[28:31], v[128:131], v[198:201], 0
	v_mfma_f32_16x16x32_bf16 v[24:27], v[136:139], v[198:201], 0
	v_mfma_f32_16x16x32_bf16 v[12:15], v[128:131], v[206:209], 0
	v_mfma_f32_16x16x32_bf16 v[8:11], v[136:139], v[206:209], 0
	v_mfma_f32_16x16x32_bf16 v[60:63], v[132:135], v[186:189], v[60:63]
	v_mfma_f32_16x16x32_bf16 v[56:59], v[140:143], v[186:189], v[56:59]
	v_mfma_f32_16x16x32_bf16 v[44:47], v[132:135], v[194:197], v[44:47]
	v_mfma_f32_16x16x32_bf16 v[40:43], v[140:143], v[194:197], v[40:43]
	v_mfma_f32_16x16x32_bf16 v[28:31], v[132:135], v[202:205], v[28:31]
	v_mfma_f32_16x16x32_bf16 v[24:27], v[140:143], v[202:205], v[24:27]
	v_mfma_f32_16x16x32_bf16 v[12:15], v[132:135], v[210:213], v[12:15]
	v_mfma_f32_16x16x32_bf16 v[8:11], v[140:143], v[210:213], v[8:11]
	v_mfma_f32_16x16x32_bf16 v[52:55], v[166:169], v[182:185], 0
	v_mfma_f32_16x16x32_bf16 v[48:51], v[174:177], v[182:185], 0
	v_mfma_f32_16x16x32_bf16 v[36:39], v[166:169], v[190:193], 0
	v_mfma_f32_16x16x32_bf16 v[32:35], v[174:177], v[190:193], 0
	v_mfma_f32_16x16x32_bf16 v[20:23], v[166:169], v[198:201], 0
	v_mfma_f32_16x16x32_bf16 v[16:19], v[174:177], v[198:201], 0
	v_mfma_f32_16x16x32_bf16 v[4:7], v[166:169], v[206:209], 0
	v_mfma_f32_16x16x32_bf16 v[0:3], v[174:177], v[206:209], 0
	v_mfma_f32_16x16x32_bf16 v[52:55], v[170:173], v[186:189], v[52:55]
	v_mfma_f32_16x16x32_bf16 v[48:51], v[178:181], v[186:189], v[48:51]
	v_mfma_f32_16x16x32_bf16 v[36:39], v[170:173], v[194:197], v[36:39]
	v_mfma_f32_16x16x32_bf16 v[32:35], v[178:181], v[194:197], v[32:35]
	v_mfma_f32_16x16x32_bf16 v[20:23], v[170:173], v[202:205], v[20:23]
	v_mfma_f32_16x16x32_bf16 v[16:19], v[178:181], v[202:205], v[16:19]
	v_mfma_f32_16x16x32_bf16 v[4:7], v[170:173], v[210:213], v[4:7]
	v_mfma_f32_16x16x32_bf16 v[0:3], v[178:181], v[210:213], v[0:3]
	s_setprio 0
	s_barrier
	s_add_i32 s52, 0, 0x18000
	s_add_i32 s53, 0, 0x1c000
	v_add_u32_e32 v140, s52, v162
	v_add_u32_e32 v178, s53, v162
	ds_read_b128 v[128:131], v140
	ds_read_b128 v[132:135], v140 offset:1024
	ds_read_b128 v[136:139], v140 offset:2048
	ds_read_b128 v[140:143], v140 offset:3072
	ds_read_b128 v[166:169], v178
	ds_read_b128 v[170:173], v178 offset:1024
	ds_read_b128 v[174:177], v178 offset:2048
	ds_read_b128 v[178:181], v178 offset:3072
	s_add_u32 s40, s40, 0x40000
	s_addc_u32 s41, s41, 0
	s_mov_b32 m0, s43
	ds_read_b128 v[182:185], v165 offset:32768
	ds_read_b128 v[186:189], v165 offset:33792
	ds_read_b128 v[190:193], v165 offset:34816
	ds_read_b128 v[194:197], v165 offset:35840
	ds_read_b128 v[198:201], v165 offset:36864
	ds_read_b128 v[202:205], v165 offset:37888
	ds_read_b128 v[206:209], v165 offset:38912
	ds_read_b128 v[210:213], v165 offset:39936
	global_load_lds_dwordx4 v144, s[40:41]
	s_mov_b32 m0, s48
	s_nop 0
	global_load_lds_dwordx4 v148, s[40:41]
	s_waitcnt vmcnt(8)
	s_waitcnt lgkmcnt(0)
	s_barrier
	s_setprio 1
	s_waitcnt lgkmcnt(0)
	v_mfma_f32_16x16x32_bf16 v[124:127], v[128:131], v[182:185], v[124:127]
	v_mfma_f32_16x16x32_bf16 v[120:123], v[136:139], v[182:185], v[120:123]
	v_mfma_f32_16x16x32_bf16 v[108:111], v[128:131], v[190:193], v[108:111]
	v_mfma_f32_16x16x32_bf16 v[104:107], v[136:139], v[190:193], v[104:107]
	v_mfma_f32_16x16x32_bf16 v[92:95], v[128:131], v[198:201], v[92:95]
	v_mfma_f32_16x16x32_bf16 v[88:91], v[136:139], v[198:201], v[88:91]
	v_mfma_f32_16x16x32_bf16 v[76:79], v[128:131], v[206:209], v[76:79]
	v_mfma_f32_16x16x32_bf16 v[72:75], v[136:139], v[206:209], v[72:75]
	v_mfma_f32_16x16x32_bf16 v[124:127], v[132:135], v[186:189], v[124:127]
	v_mfma_f32_16x16x32_bf16 v[120:123], v[140:143], v[186:189], v[120:123]
	v_mfma_f32_16x16x32_bf16 v[108:111], v[132:135], v[194:197], v[108:111]
	v_mfma_f32_16x16x32_bf16 v[104:107], v[140:143], v[194:197], v[104:107]
	v_mfma_f32_16x16x32_bf16 v[92:95], v[132:135], v[202:205], v[92:95]
	v_mfma_f32_16x16x32_bf16 v[88:91], v[140:143], v[202:205], v[88:91]
	v_mfma_f32_16x16x32_bf16 v[76:79], v[132:135], v[210:213], v[76:79]
	v_mfma_f32_16x16x32_bf16 v[72:75], v[140:143], v[210:213], v[72:75]
	v_mfma_f32_16x16x32_bf16 v[116:119], v[166:169], v[182:185], v[116:119]
	v_mfma_f32_16x16x32_bf16 v[112:115], v[174:177], v[182:185], v[112:115]
	v_mfma_f32_16x16x32_bf16 v[100:103], v[166:169], v[190:193], v[100:103]
	v_mfma_f32_16x16x32_bf16 v[96:99], v[174:177], v[190:193], v[96:99]
	v_mfma_f32_16x16x32_bf16 v[84:87], v[166:169], v[198:201], v[84:87]
	v_mfma_f32_16x16x32_bf16 v[80:83], v[174:177], v[198:201], v[80:83]
	v_mfma_f32_16x16x32_bf16 v[68:71], v[166:169], v[206:209], v[68:71]
	v_mfma_f32_16x16x32_bf16 v[64:67], v[174:177], v[206:209], v[64:67]
	v_mfma_f32_16x16x32_bf16 v[116:119], v[170:173], v[186:189], v[116:119]
	v_mfma_f32_16x16x32_bf16 v[112:115], v[178:181], v[186:189], v[112:115]
	v_mfma_f32_16x16x32_bf16 v[100:103], v[170:173], v[194:197], v[100:103]
	v_mfma_f32_16x16x32_bf16 v[96:99], v[178:181], v[194:197], v[96:99]
	v_mfma_f32_16x16x32_bf16 v[84:87], v[170:173], v[202:205], v[84:87]
	v_mfma_f32_16x16x32_bf16 v[80:83], v[178:181], v[202:205], v[80:83]
	v_mfma_f32_16x16x32_bf16 v[68:71], v[170:173], v[210:213], v[68:71]
	v_mfma_f32_16x16x32_bf16 v[64:67], v[178:181], v[210:213], v[64:67]
	s_setprio 0
	s_barrier
; #define PG8_STAGE(bufoff, gbase, voff) do { _Pragma("unroll") for (int _i = 0; _i < 2; ++_i) \
;         __builtin_amdgcn_global_load_lds((const unsigned*)((const char*)(gbase) + (voff)[_i]), (LAS unsigned*)(lds + (bufoff) + ldsw + _i * 8192), 16, 0, 0); } while (0)
; #define PG8_LDA(dst, b, h) do { _Pragma("unroll") for (int m = 0; m < 4; ++m) _Pragma("unroll") for (int k = 0; k < 2; ++k) dst[m][k] = *(const LAS bf16x8*)(lds + PG8_SA(b, h) + aoff + m * 2048 + k * 1024); } while (0)
; #define PG8_MMA(ai, bj, At, Bt) do { __builtin_amdgcn_s_setprio(1); _Pragma("unroll") for (int m = 0; m < 4; ++m) _Pragma("unroll") for (int n = 0; n < 2; ++n) _Pragma("unroll") for (int k = 0; k < 2; ++k) \
;         acc[ai][bj][m][n] = __builtin_amdgcn_mfma_f32_16x16x32_bf16(Bt[n][k], At[m][k], acc[ai][bj][m][n], 0, 0, 0); __builtin_amdgcn_s_setprio(0); } while (0)
; #define PG8_WAIT_V(n) asm volatile("s_waitcnt vmcnt(" #n ")" ::: "memory")
; #define PG8_WAIT_L(n) asm volatile("s_waitcnt lgkmcnt(" #n ")" ::: "memory")
; #define PG8_BAR __builtin_amdgcn_s_barrier()
; #define PG8_SCHED __builtin_amdgcn_sched_barrier(0)
; template <class Epi, bool ALIGN_EPI, int K, int LDA, int LDB>
; __device__ __forceinline__ void gemm_phase(LAS unsigned char* lds, const int wid, const Gemm g, const StaticOrder& S, const Epi& E) {
;     ...
;             PG8_LDA(At, 1, 1); PG8_STAGE(PG8_SB(1, 0), b3, voffB); PG8_STAGE(PG8_SB(1, 1), b3 + hB, voffB); PG8_STAGE(PG8_SA(1, 0), a3, voffA);
;             PG8_WAIT_V(8); PG8_WAIT_L(0); PG8_BAR; PG8_MMA(1, 0, At, B0); PG8_MMA(1, 1, At, B1); PG8_BAR; PG8_SCHED;
;         }
	s_add_i32 s40, s52, s33
	s_mov_b32 m0, s40
	ds_read_b128 v[182:185], v165 offset:49152
	ds_read_b128 v[186:189], v165 offset:50176
	ds_read_b128 v[190:193], v165 offset:51200
	ds_read_b128 v[194:197], v165 offset:52224
	ds_read_b128 v[198:201], v165 offset:53248
	ds_read_b128 v[202:205], v165 offset:54272
	ds_read_b128 v[206:209], v165 offset:55296
	ds_read_b128 v[210:213], v165 offset:56320
	global_load_lds_dwordx4 v146, s[98:99]
	s_add_i32 m0, s40, 0x2000
	s_add_u32 s38, s38, 0x40080
	s_addc_u32 s39, s39, 0
	s_add_i32 s40, s53, s33
	global_load_lds_dwordx4 v150, s[98:99]
	s_mov_b32 m0, s40
	s_nop 0
	global_load_lds_dwordx4 v146, s[38:39]
	s_add_i32 m0, s40, 0x2000
	s_nop 0
	global_load_lds_dwordx4 v150, s[38:39]
	s_mov_b32 m0, s55
	s_nop 0
	global_load_lds_dwordx4 v144, s[100:101]
	s_mov_b32 m0, s56
	s_nop 0
	global_load_lds_dwordx4 v148, s[100:101]
	s_waitcnt vmcnt(8)
	s_waitcnt lgkmcnt(0)
	s_barrier
	s_setprio 1
	s_waitcnt lgkmcnt(0)
	v_mfma_f32_16x16x32_bf16 v[60:63], v[128:131], v[182:185], v[60:63]
	v_mfma_f32_16x16x32_bf16 v[56:59], v[136:139], v[182:185], v[56:59]
	v_mfma_f32_16x16x32_bf16 v[44:47], v[128:131], v[190:193], v[44:47]
	v_mfma_f32_16x16x32_bf16 v[40:43], v[136:139], v[190:193], v[40:43]
	v_mfma_f32_16x16x32_bf16 v[28:31], v[128:131], v[198:201], v[28:31]
	v_mfma_f32_16x16x32_bf16 v[24:27], v[136:139], v[198:201], v[24:27]
	v_mfma_f32_16x16x32_bf16 v[12:15], v[128:131], v[206:209], v[12:15]
	v_mfma_f32_16x16x32_bf16 v[8:11], v[136:139], v[206:209], v[8:11]
	v_mfma_f32_16x16x32_bf16 v[60:63], v[132:135], v[186:189], v[60:63]
	v_mfma_f32_16x16x32_bf16 v[56:59], v[140:143], v[186:189], v[56:59]
	v_mfma_f32_16x16x32_bf16 v[44:47], v[132:135], v[194:197], v[44:47]
	v_mfma_f32_16x16x32_bf16 v[40:43], v[140:143], v[194:197], v[40:43]
	v_mfma_f32_16x16x32_bf16 v[28:31], v[132:135], v[202:205], v[28:31]
	v_mfma_f32_16x16x32_bf16 v[24:27], v[140:143], v[202:205], v[24:27]
	v_mfma_f32_16x16x32_bf16 v[12:15], v[132:135], v[210:213], v[12:15]
	v_mfma_f32_16x16x32_bf16 v[8:11], v[140:143], v[210:213], v[8:11]
	v_mfma_f32_16x16x32_bf16 v[52:55], v[166:169], v[182:185], v[52:55]
	v_mfma_f32_16x16x32_bf16 v[48:51], v[174:177], v[182:185], v[48:51]
	v_mfma_f32_16x16x32_bf16 v[36:39], v[166:169], v[190:193], v[36:39]
	v_mfma_f32_16x16x32_bf16 v[32:35], v[174:177], v[190:193], v[32:35]
	v_mfma_f32_16x16x32_bf16 v[20:23], v[166:169], v[198:201], v[20:23]
	v_mfma_f32_16x16x32_bf16 v[16:19], v[174:177], v[198:201], v[16:19]
	v_mfma_f32_16x16x32_bf16 v[4:7], v[166:169], v[206:209], v[4:7]
	v_mfma_f32_16x16x32_bf16 v[0:3], v[174:177], v[206:209], v[0:3]
	v_mfma_f32_16x16x32_bf16 v[52:55], v[170:173], v[186:189], v[52:55]
	v_mfma_f32_16x16x32_bf16 v[48:51], v[178:181], v[186:189], v[48:51]
	v_mfma_f32_16x16x32_bf16 v[36:39], v[170:173], v[194:197], v[36:39]
	v_mfma_f32_16x16x32_bf16 v[32:35], v[178:181], v[194:197], v[32:35]
	v_mfma_f32_16x16x32_bf16 v[20:23], v[170:173], v[202:205], v[20:23]
	v_mfma_f32_16x16x32_bf16 v[16:19], v[178:181], v[202:205], v[16:19]
	v_mfma_f32_16x16x32_bf16 v[4:7], v[170:173], v[210:213], v[4:7]
	v_mfma_f32_16x16x32_bf16 v[0:3], v[178:181], v[210:213], v[0:3]
	s_setprio 0
	s_barrier
	s_add_i32 s67, s67, 2
	s_add_u32 s36, s36, 0x100
	s_addc_u32 s37, s37, 0
	s_add_u32 s65, s65, 0x100
	s_addc_u32 s66, s66, 0

; #define PG8_STAGE(bufoff, gbase, voff) do { _Pragma("unroll") for (int _i = 0; _i < 2; ++_i) \
;         __builtin_amdgcn_global_load_lds((const unsigned*)((const char*)(gbase) + (voff)[_i]), (LAS unsigned*)(lds + (bufoff) + ldsw + _i * 8192), 16, 0, 0); } while (0)
; #define PG8_LDA(dst, b, h) do { _Pragma("unroll") for (int m = 0; m < 4; ++m) _Pragma("unroll") for (int k = 0; k < 2; ++k) dst[m][k] = *(const LAS bf16x8*)(lds + PG8_SA(b, h) + aoff + m * 2048 + k * 1024); } while (0)
; #define PG8_LDB(dst, b, h) do { _Pragma("unroll") for (int n = 0; n < 2; ++n) _Pragma("unroll") for (int k = 0; k < 2; ++k) dst[n][k] = *(const LAS bf16x8*)(lds + PG8_SB(b, h) + boff + n * 2048 + k * 1024); } while (0)
; #define PG8_MMA(ai, bj, At, Bt) do { __builtin_amdgcn_s_setprio(1); _Pragma("unroll") for (int m = 0; m < 4; ++m) _Pragma("unroll") for (int n = 0; n < 2; ++n) _Pragma("unroll") for (int k = 0; k < 2; ++k) \
;         acc[ai][bj][m][n] = __builtin_amdgcn_mfma_f32_16x16x32_bf16(Bt[n][k], At[m][k], acc[ai][bj][m][n], 0, 0, 0); __builtin_amdgcn_s_setprio(0); } while (0)
; template <class Epi, bool ALIGN_EPI, int K, int LDA, int LDB>
; __device__ __forceinline__ void gemm_phase(LAS unsigned char* lds, const int wid, const Gemm g, const StaticOrder& S, const Epi& E) {
;     ...
;         const bool has_next = S.next(ui + 1, nxt);
;         const char* nA = has_next ? (const char*)g.A + (size_t)nxt.pm * tA : cA; const char* nB = has_next ? (const char*)g.Bt + (size_t)nxt.pn * tB : cB;
;         for (int t = 0; t < nt; t += 2) {
;             const bool last = (t == nt - 2);
;             const char* a1 = cA + (size_t)(t + 1) * kstep;
;             const char* a2 = last ? nA : cA + (size_t)(t + 2) * kstep; const char* b2 = last ? nB : cB + (size_t)(t + 2) * kstep;
;             const char* a3 = a2 + kstep; const char* b3 = b2 + kstep;
;             PG8_LDB(B0, 0, 0); PG8_LDB(B1, 0, 1); PG8_SCHED; PG8_LDA(At, 0, 0); PG8_STAGE(PG8_SA(1, 1), a1 + hA, voffA);
;             PG8_WAIT_V(8); PG8_WAIT_L(0); PG8_BAR; PG8_MMA(0, 0, At, B0); PG8_MMA(0, 1, At, B1); PG8_BAR; PG8_SCHED;
;             PG8_LDA(At, 0, 1); PG8_STAGE(PG8_SB(0, 0), b2, voffB); PG8_STAGE(PG8_SB(0, 1), b2 + hB, voffB); PG8_STAGE(PG8_SA(0, 0), a2, voffA);
;             PG8_WAIT_V(8); PG8_WAIT_L(0); PG8_BAR; PG8_MMA(1, 0, At, B0); PG8_MMA(1, 1, At, B1); PG8_BAR; PG8_SCHED;
.LBB0_1051:
	s_ashr_i32 s15, s14, 31
	s_lshl_b64 s[16:17], s[14:15], 19
	v_readlane_b32 s13, v254, 0
	s_add_u32 s16, s13, s16
	v_readlane_b32 s13, v254, 1
	s_addc_u32 s17, s13, s17
	s_and_b64 s[18:19], s[4:5], exec
	s_cselect_b32 s15, s17, s23
	s_cselect_b32 s48, s16, s22
	s_ashr_i32 s13, s12, 31
	s_lshl_b64 s[18:19], s[12:13], 19
	s_add_u32 s18, s0, s18
	s_addc_u32 s19, s1, s19
	s_and_b64 s[26:27], s[4:5], exec
	s_cselect_b32 s13, s19, s25
	s_cselect_b32 s49, s18, s24
	s_add_u32 s22, s22, 0x40080
	s_addc_u32 s23, s23, 0
	s_add_u32 s51, s24, 0x100
	s_addc_u32 s54, s25, 0
	s_mov_b32 s55, -2
	ds_read_b128 v[148:151], v145
	ds_read_b128 v[152:155], v145 offset:1024
	ds_read_b128 v[156:159], v145 offset:2048
	ds_read_b128 v[160:163], v145 offset:3072
	ds_read_b128 v[164:167], v146
	ds_read_b128 v[168:171], v146 offset:1024
	ds_read_b128 v[172:175], v146 offset:2048
	ds_read_b128 v[176:179], v146 offset:3072
	s_add_u32 s24, s22, 0xfffc0080
	s_addc_u32 s25, s23, -1
	s_cmp_eq_u32 s55, 12
	s_cselect_b32 s27, s15, s25
	s_cselect_b32 s26, s48, s24
	s_cselect_b32 s25, s13, s54
	s_cselect_b32 s24, s49, s51
	s_add_i32 m0, s21, 0xc000
	ds_read_b128 v[180:183], v147
	ds_read_b128 v[184:187], v147 offset:1024
	ds_read_b128 v[188:191], v147 offset:2048
	ds_read_b128 v[192:195], v147 offset:3072
	ds_read_b128 v[196:199], v147 offset:4096
	ds_read_b128 v[200:203], v147 offset:5120
	ds_read_b128 v[204:207], v147 offset:6144
	ds_read_b128 v[208:211], v147 offset:7168
	global_load_lds_dwordx4 v136, s[22:23]
	s_add_i32 m0, s21, 0xe000
	s_nop 0
	global_load_lds_dwordx4 v138, s[22:23]
	s_waitcnt vmcnt(8)
	s_waitcnt lgkmcnt(0)
	s_barrier
	s_setprio 1
	s_waitcnt lgkmcnt(0)
	v_mfma_f32_16x16x32_bf16 v[124:127], v[148:151], v[180:183], 0
	v_mfma_f32_16x16x32_bf16 v[120:123], v[156:159], v[180:183], 0
	v_mfma_f32_16x16x32_bf16 v[108:111], v[148:151], v[188:191], 0
	v_mfma_f32_16x16x32_bf16 v[104:107], v[156:159], v[188:191], 0
	v_mfma_f32_16x16x32_bf16 v[92:95], v[148:151], v[196:199], 0
	v_mfma_f32_16x16x32_bf16 v[88:91], v[156:159], v[196:199], 0
	v_mfma_f32_16x16x32_bf16 v[76:79], v[148:151], v[204:207], 0
	v_mfma_f32_16x16x32_bf16 v[72:75], v[156:159], v[204:207], 0
	v_mfma_f32_16x16x32_bf16 v[124:127], v[152:155], v[184:187], v[124:127]
	v_mfma_f32_16x16x32_bf16 v[120:123], v[160:163], v[184:187], v[120:123]
	v_mfma_f32_16x16x32_bf16 v[108:111], v[152:155], v[192:195], v[108:111]
	v_mfma_f32_16x16x32_bf16 v[104:107], v[160:163], v[192:195], v[104:107]
	v_mfma_f32_16x16x32_bf16 v[92:95], v[152:155], v[200:203], v[92:95]
	v_mfma_f32_16x16x32_bf16 v[88:91], v[160:163], v[200:203], v[88:91]
	v_mfma_f32_16x16x32_bf16 v[76:79], v[152:155], v[208:211], v[76:79]
	v_mfma_f32_16x16x32_bf16 v[72:75], v[160:163], v[208:211], v[72:75]
	v_mfma_f32_16x16x32_bf16 v[116:119], v[164:167], v[180:183], 0
	v_mfma_f32_16x16x32_bf16 v[112:115], v[172:175], v[180:183], 0
	v_mfma_f32_16x16x32_bf16 v[100:103], v[164:167], v[188:191], 0
	v_mfma_f32_16x16x32_bf16 v[96:99], v[172:175], v[188:191], 0
	v_mfma_f32_16x16x32_bf16 v[84:87], v[164:167], v[196:199], 0
	v_mfma_f32_16x16x32_bf16 v[80:83], v[172:175], v[196:199], 0
	v_mfma_f32_16x16x32_bf16 v[68:71], v[164:167], v[204:207], 0
	v_mfma_f32_16x16x32_bf16 v[64:67], v[172:175], v[204:207], 0
	v_mfma_f32_16x16x32_bf16 v[116:119], v[168:171], v[184:187], v[116:119]
	v_mfma_f32_16x16x32_bf16 v[112:115], v[176:179], v[184:187], v[112:115]
	v_mfma_f32_16x16x32_bf16 v[100:103], v[168:171], v[192:195], v[100:103]
	v_mfma_f32_16x16x32_bf16 v[96:99], v[176:179], v[192:195], v[96:99]
	v_mfma_f32_16x16x32_bf16 v[84:87], v[168:171], v[200:203], v[84:87]
	v_mfma_f32_16x16x32_bf16 v[80:83], v[176:179], v[200:203], v[80:83]
	v_mfma_f32_16x16x32_bf16 v[68:71], v[168:171], v[208:211], v[68:71]
	v_mfma_f32_16x16x32_bf16 v[64:67], v[176:179], v[208:211], v[64:67]
	s_setprio 0
	s_barrier
	s_add_u32 s98, s24, s10
	s_addc_u32 s99, s25, s11
	s_add_u32 s100, s26, s10
	s_addc_u32 s101, s27, s11
	s_add_i32 s52, s40, s3
	s_mov_b32 m0, s52
	ds_read_b128 v[180:183], v147 offset:16384
	ds_read_b128 v[184:187], v147 offset:17408
	ds_read_b128 v[188:191], v147 offset:18432
	ds_read_b128 v[192:195], v147 offset:19456
	ds_read_b128 v[196:199], v147 offset:20480
	ds_read_b128 v[200:203], v147 offset:21504
	ds_read_b128 v[204:207], v147 offset:22528
	ds_read_b128 v[208:211], v147 offset:23552
	global_load_lds_dwordx4 v132, s[24:25]
	s_add_i32 m0, s52, 0x2000
	s_add_u32 s56, s24, 0x40000
	s_addc_u32 s57, s25, 0
	s_add_i32 s52, s41, s3
	global_load_lds_dwordx4 v128, s[24:25]
	s_mov_b32 m0, s52
	s_nop 0
	global_load_lds_dwordx4 v132, s[56:57]
	s_add_i32 m0, s52, 0x2000
	s_nop 0
	global_load_lds_dwordx4 v128, s[56:57]
	s_mov_b32 m0, s21
	s_nop 0
	global_load_lds_dwordx4 v134, s[26:27]
	s_mov_b32 m0, s30
	s_nop 0
	global_load_lds_dwordx4 v130, s[26:27]
	s_waitcnt vmcnt(8)
	s_waitcnt lgkmcnt(0)
	s_barrier
; #define PG8_STAGE(bufoff, gbase, voff) do { _Pragma("unroll") for (int _i = 0; _i < 2; ++_i) \
;         __builtin_amdgcn_global_load_lds((const unsigned*)((const char*)(gbase) + (voff)[_i]), (LAS unsigned*)(lds + (bufoff) + ldsw + _i * 8192), 16, 0, 0); } while (0)
; #define PG8_LDA(dst, b, h) do { _Pragma("unroll") for (int m = 0; m < 4; ++m) _Pragma("unroll") for (int k = 0; k < 2; ++k) dst[m][k] = *(const LAS bf16x8*)(lds + PG8_SA(b, h) + aoff + m * 2048 + k * 1024); } while (0)
; #define PG8_LDB(dst, b, h) do { _Pragma("unroll") for (int n = 0; n < 2; ++n) _Pragma("unroll") for (int k = 0; k < 2; ++k) dst[n][k] = *(const LAS bf16x8*)(lds + PG8_SB(b, h) + boff + n * 2048 + k * 1024); } while (0)
; #define PG8_MMA(ai, bj, At, Bt) do { __builtin_amdgcn_s_setprio(1); _Pragma("unroll") for (int m = 0; m < 4; ++m) _Pragma("unroll") for (int n = 0; n < 2; ++n) _Pragma("unroll") for (int k = 0; k < 2; ++k) \
;         acc[ai][bj][m][n] = __builtin_amdgcn_mfma_f32_16x16x32_bf16(Bt[n][k], At[m][k], acc[ai][bj][m][n], 0, 0, 0); __builtin_amdgcn_s_setprio(0); } while (0)
; #define PG8_WAIT_V(n) asm volatile("s_waitcnt vmcnt(" #n ")" ::: "memory")
; #define PG8_WAIT_L(n) asm volatile("s_waitcnt lgkmcnt(" #n ")" ::: "memory")
; #define PG8_BAR __builtin_amdgcn_s_barrier()
; #define PG8_SCHED __builtin_amdgcn_sched_barrier(0)
; template <class Epi, bool ALIGN_EPI, int K, int LDA, int LDB>
; __device__ __forceinline__ void gemm_phase(LAS unsigned char* lds, const int wid, const Gemm g, const StaticOrder& S, const Epi& E) {
;     ...
;             PG8_WAIT_V(8); PG8_WAIT_L(0); PG8_BAR; PG8_MMA(0, 0, At, B0); PG8_MMA(0, 1, At, B1); PG8_BAR; PG8_SCHED;
;             PG8_LDA(At, 0, 1); PG8_STAGE(PG8_SB(0, 0), b2, voffB); PG8_STAGE(PG8_SB(0, 1), b2 + hB, voffB); PG8_STAGE(PG8_SA(0, 0), a2, voffA);
;             PG8_WAIT_V(8); PG8_WAIT_L(0); PG8_BAR; PG8_MMA(1, 0, At, B0); PG8_MMA(1, 1, At, B1); PG8_BAR; PG8_SCHED;
;             PG8_LDB(B0, 1, 0); PG8_LDB(B1, 1, 1); PG8_SCHED; PG8_LDA(At, 1, 0); PG8_STAGE(PG8_SA(0, 1), a2 + hA, voffA);
;             PG8_WAIT_V(8); PG8_WAIT_L(0); PG8_BAR; PG8_MMA(0, 0, At, B0); PG8_MMA(0, 1, At, B1); PG8_BAR; PG8_SCHED;
;             PG8_LDA(At, 1, 1); PG8_STAGE(PG8_SB(1, 0), b3, voffB); PG8_STAGE(PG8_SB(1, 1), b3 + hB, voffB); PG8_STAGE(PG8_SA(1, 0), a3, voffA);
	s_setprio 1
	s_waitcnt lgkmcnt(0)
	v_mfma_f32_16x16x32_bf16 v[60:63], v[148:151], v[180:183], 0
	v_mfma_f32_16x16x32_bf16 v[56:59], v[156:159], v[180:183], 0
	v_mfma_f32_16x16x32_bf16 v[44:47], v[148:151], v[188:191], 0
	v_mfma_f32_16x16x32_bf16 v[40:43], v[156:159], v[188:191], 0
	v_mfma_f32_16x16x32_bf16 v[28:31], v[148:151], v[196:199], 0
	v_mfma_f32_16x16x32_bf16 v[24:27], v[156:159], v[196:199], 0
	v_mfma_f32_16x16x32_bf16 v[12:15], v[148:151], v[204:207], 0
	v_mfma_f32_16x16x32_bf16 v[8:11], v[156:159], v[204:207], 0
	v_mfma_f32_16x16x32_bf16 v[60:63], v[152:155], v[184:187], v[60:63]
	v_mfma_f32_16x16x32_bf16 v[56:59], v[160:163], v[184:187], v[56:59]
	v_mfma_f32_16x16x32_bf16 v[44:47], v[152:155], v[192:195], v[44:47]
	v_mfma_f32_16x16x32_bf16 v[40:43], v[160:163], v[192:195], v[40:43]
	v_mfma_f32_16x16x32_bf16 v[28:31], v[152:155], v[200:203], v[28:31]
	v_mfma_f32_16x16x32_bf16 v[24:27], v[160:163], v[200:203], v[24:27]
	v_mfma_f32_16x16x32_bf16 v[12:15], v[152:155], v[208:211], v[12:15]
	v_mfma_f32_16x16x32_bf16 v[8:11], v[160:163], v[208:211], v[8:11]
	v_mfma_f32_16x16x32_bf16 v[52:55], v[164:167], v[180:183], 0
	v_mfma_f32_16x16x32_bf16 v[48:51], v[172:175], v[180:183], 0
	v_mfma_f32_16x16x32_bf16 v[36:39], v[164:167], v[188:191], 0
	v_mfma_f32_16x16x32_bf16 v[32:35], v[172:175], v[188:191], 0
	v_mfma_f32_16x16x32_bf16 v[20:23], v[164:167], v[196:199], 0
	v_mfma_f32_16x16x32_bf16 v[16:19], v[172:175], v[196:199], 0
	v_mfma_f32_16x16x32_bf16 v[4:7], v[164:167], v[204:207], 0
	v_mfma_f32_16x16x32_bf16 v[0:3], v[172:175], v[204:207], 0
	v_mfma_f32_16x16x32_bf16 v[52:55], v[168:171], v[184:187], v[52:55]
	v_mfma_f32_16x16x32_bf16 v[48:51], v[176:179], v[184:187], v[48:51]
	v_mfma_f32_16x16x32_bf16 v[36:39], v[168:171], v[192:195], v[36:39]
	v_mfma_f32_16x16x32_bf16 v[32:35], v[176:179], v[192:195], v[32:35]
	v_mfma_f32_16x16x32_bf16 v[20:23], v[168:171], v[200:203], v[20:23]
	v_mfma_f32_16x16x32_bf16 v[16:19], v[176:179], v[200:203], v[16:19]
	v_mfma_f32_16x16x32_bf16 v[4:7], v[168:171], v[208:211], v[4:7]
	v_mfma_f32_16x16x32_bf16 v[0:3], v[176:179], v[208:211], v[0:3]
	s_setprio 0
	s_barrier
	s_add_i32 s52, 0, 0x18000
	s_add_i32 s53, 0, 0x1c000
	v_add_u32_e32 v160, s52, v144
	v_add_u32_e32 v176, s53, v144
	ds_read_b128 v[148:151], v160
	ds_read_b128 v[152:155], v160 offset:1024
	ds_read_b128 v[156:159], v160 offset:2048
	ds_read_b128 v[160:163], v160 offset:3072
	ds_read_b128 v[164:167], v176
	ds_read_b128 v[168:171], v176 offset:1024
	ds_read_b128 v[172:175], v176 offset:2048
	ds_read_b128 v[176:179], v176 offset:3072
	s_add_u32 s26, s26, 0x40000
	s_addc_u32 s27, s27, 0
	s_mov_b32 m0, s31
	ds_read_b128 v[180:183], v147 offset:32768
	ds_read_b128 v[184:187], v147 offset:33792
	ds_read_b128 v[188:191], v147 offset:34816
	ds_read_b128 v[192:195], v147 offset:35840
	ds_read_b128 v[196:199], v147 offset:36864
	ds_read_b128 v[200:203], v147 offset:37888
	ds_read_b128 v[204:207], v147 offset:38912
	ds_read_b128 v[208:211], v147 offset:39936
	global_load_lds_dwordx4 v134, s[26:27]
	s_mov_b32 m0, s33
	s_nop 0
	global_load_lds_dwordx4 v130, s[26:27]
	s_waitcnt vmcnt(8)
	s_waitcnt lgkmcnt(0)
	s_barrier
	s_setprio 1
	s_waitcnt lgkmcnt(0)
	v_mfma_f32_16x16x32_bf16 v[124:127], v[148:151], v[180:183], v[124:127]
	v_mfma_f32_16x16x32_bf16 v[120:123], v[156:159], v[180:183], v[120:123]
	v_mfma_f32_16x16x32_bf16 v[108:111], v[148:151], v[188:191], v[108:111]
	v_mfma_f32_16x16x32_bf16 v[104:107], v[156:159], v[188:191], v[104:107]
	v_mfma_f32_16x16x32_bf16 v[92:95], v[148:151], v[196:199], v[92:95]
	v_mfma_f32_16x16x32_bf16 v[88:91], v[156:159], v[196:199], v[88:91]
	v_mfma_f32_16x16x32_bf16 v[76:79], v[148:151], v[204:207], v[76:79]
	v_mfma_f32_16x16x32_bf16 v[72:75], v[156:159], v[204:207], v[72:75]
	v_mfma_f32_16x16x32_bf16 v[124:127], v[152:155], v[184:187], v[124:127]
	v_mfma_f32_16x16x32_bf16 v[120:123], v[160:163], v[184:187], v[120:123]
	v_mfma_f32_16x16x32_bf16 v[108:111], v[152:155], v[192:195], v[108:111]
	v_mfma_f32_16x16x32_bf16 v[104:107], v[160:163], v[192:195], v[104:107]
	v_mfma_f32_16x16x32_bf16 v[92:95], v[152:155], v[200:203], v[92:95]
	v_mfma_f32_16x16x32_bf16 v[88:91], v[160:163], v[200:203], v[88:91]
	v_mfma_f32_16x16x32_bf16 v[76:79], v[152:155], v[208:211], v[76:79]
	v_mfma_f32_16x16x32_bf16 v[72:75], v[160:163], v[208:211], v[72:75]
	v_mfma_f32_16x16x32_bf16 v[116:119], v[164:167], v[180:183], v[116:119]
	v_mfma_f32_16x16x32_bf16 v[112:115], v[172:175], v[180:183], v[112:115]
	v_mfma_f32_16x16x32_bf16 v[100:103], v[164:167], v[188:191], v[100:103]
	v_mfma_f32_16x16x32_bf16 v[96:99], v[172:175], v[188:191], v[96:99]
	v_mfma_f32_16x16x32_bf16 v[84:87], v[164:167], v[196:199], v[84:87]
	v_mfma_f32_16x16x32_bf16 v[80:83], v[172:175], v[196:199], v[80:83]
	v_mfma_f32_16x16x32_bf16 v[68:71], v[164:167], v[204:207], v[68:71]
	v_mfma_f32_16x16x32_bf16 v[64:67], v[172:175], v[204:207], v[64:67]
	v_mfma_f32_16x16x32_bf16 v[116:119], v[168:171], v[184:187], v[116:119]
	v_mfma_f32_16x16x32_bf16 v[112:115], v[176:179], v[184:187], v[112:115]
	v_mfma_f32_16x16x32_bf16 v[100:103], v[168:171], v[192:195], v[100:103]
	v_mfma_f32_16x16x32_bf16 v[96:99], v[176:179], v[192:195], v[96:99]
	v_mfma_f32_16x16x32_bf16 v[84:87], v[168:171], v[200:203], v[84:87]
	v_mfma_f32_16x16x32_bf16 v[80:83], v[176:179], v[200:203], v[80:83]
	v_mfma_f32_16x16x32_bf16 v[68:71], v[168:171], v[208:211], v[68:71]
	v_mfma_f32_16x16x32_bf16 v[64:67], v[176:179], v[208:211], v[64:67]
	s_setprio 0
	s_barrier
; #define PG8_STAGE(bufoff, gbase, voff) do { _Pragma("unroll") for (int _i = 0; _i < 2; ++_i) \
;         __builtin_amdgcn_global_load_lds((const unsigned*)((const char*)(gbase) + (voff)[_i]), (LAS unsigned*)(lds + (bufoff) + ldsw + _i * 8192), 16, 0, 0); } while (0)
; #define PG8_LDA(dst, b, h) do { _Pragma("unroll") for (int m = 0; m < 4; ++m) _Pragma("unroll") for (int k = 0; k < 2; ++k) dst[m][k] = *(const LAS bf16x8*)(lds + PG8_SA(b, h) + aoff + m * 2048 + k * 1024); } while (0)
; #define PG8_LDB(dst, b, h) do { _Pragma("unroll") for (int n = 0; n < 2; ++n) _Pragma("unroll") for (int k = 0; k < 2; ++k) dst[n][k] = *(const LAS bf16x8*)(lds + PG8_SB(b, h) + boff + n * 2048 + k * 1024); } while (0)
; #define PG8_WAIT_V(n) asm volatile("s_waitcnt vmcnt(" #n ")" ::: "memory")
; template <class Epi, bool ALIGN_EPI, int K, int LDA, int LDB>
; __device__ __forceinline__ void gemm_phase(LAS unsigned char* lds, const int wid, const Gemm g, const StaticOrder& S, const Epi& E) {
;     ...
;         for (int t = 0; t < nt; t += 2) {
;             const bool last = (t == nt - 2);
;             const char* a1 = cA + (size_t)(t + 1) * kstep;
;             const char* a2 = last ? nA : cA + (size_t)(t + 2) * kstep; const char* b2 = last ? nB : cB + (size_t)(t + 2) * kstep;
;             const char* a3 = a2 + kstep; const char* b3 = b2 + kstep;
;             PG8_LDB(B0, 0, 0); PG8_LDB(B1, 0, 1); PG8_SCHED; PG8_LDA(At, 0, 0); PG8_STAGE(PG8_SA(1, 1), a1 + hA, voffA);
;             PG8_WAIT_V(8); PG8_WAIT_L(0); PG8_BAR; PG8_MMA(0, 0, At, B0); PG8_MMA(0, 1, At, B1); PG8_BAR; PG8_SCHED;
;             PG8_LDA(At, 0, 1); PG8_STAGE(PG8_SB(0, 0), b2, voffB); PG8_STAGE(PG8_SB(0, 1), b2 + hB, voffB); PG8_STAGE(PG8_SA(0, 0), a2, voffA);
;             PG8_WAIT_V(8); PG8_WAIT_L(0); PG8_BAR; PG8_MMA(1, 0, At, B0); PG8_MMA(1, 1, At, B1); PG8_BAR; PG8_SCHED;
;             PG8_LDB(B0, 1, 0); PG8_LDB(B1, 1, 1); PG8_SCHED; PG8_LDA(At, 1, 0); PG8_STAGE(PG8_SA(0, 1), a2 + hA, voffA);
;             PG8_WAIT_V(8); PG8_WAIT_L(0); PG8_BAR; PG8_MMA(0, 0, At, B0); PG8_MMA(0, 1, At, B1); PG8_BAR; PG8_SCHED;
;             PG8_LDA(At, 1, 1); PG8_STAGE(PG8_SB(1, 0), b3, voffB); PG8_STAGE(PG8_SB(1, 1), b3 + hB, voffB); PG8_STAGE(PG8_SA(1, 0), a3, voffA);
;             PG8_WAIT_V(8); PG8_WAIT_L(0); PG8_BAR; PG8_MMA(1, 0, At, B0); PG8_MMA(1, 1, At, B1); PG8_BAR; PG8_SCHED;
;         }
	s_add_i32 s26, s52, s3
	s_mov_b32 m0, s26
	ds_read_b128 v[180:183], v147 offset:49152
	ds_read_b128 v[184:187], v147 offset:50176
	ds_read_b128 v[188:191], v147 offset:51200
	ds_read_b128 v[192:195], v147 offset:52224
	ds_read_b128 v[196:199], v147 offset:53248
	ds_read_b128 v[200:203], v147 offset:54272
	ds_read_b128 v[204:207], v147 offset:55296
	ds_read_b128 v[208:211], v147 offset:56320
	global_load_lds_dwordx4 v132, s[98:99]
	s_add_i32 m0, s26, 0x2000
	s_add_u32 s24, s24, 0x40080
	s_addc_u32 s25, s25, 0
	s_add_i32 s26, s53, s3
	global_load_lds_dwordx4 v128, s[98:99]
	s_mov_b32 m0, s26
	s_nop 0
	global_load_lds_dwordx4 v132, s[24:25]
	s_add_i32 m0, s26, 0x2000
	s_nop 0
	global_load_lds_dwordx4 v128, s[24:25]
	s_mov_b32 m0, s38
	s_nop 0
	global_load_lds_dwordx4 v134, s[100:101]
	s_mov_b32 m0, s39
	s_nop 0
	global_load_lds_dwordx4 v130, s[100:101]
	s_waitcnt vmcnt(8)
	s_waitcnt lgkmcnt(0)
	s_barrier
	s_setprio 1
	s_waitcnt lgkmcnt(0)
	v_mfma_f32_16x16x32_bf16 v[60:63], v[148:151], v[180:183], v[60:63]
	v_mfma_f32_16x16x32_bf16 v[56:59], v[156:159], v[180:183], v[56:59]
	v_mfma_f32_16x16x32_bf16 v[44:47], v[148:151], v[188:191], v[44:47]
	v_mfma_f32_16x16x32_bf16 v[40:43], v[156:159], v[188:191], v[40:43]
	v_mfma_f32_16x16x32_bf16 v[28:31], v[148:151], v[196:199], v[28:31]
	v_mfma_f32_16x16x32_bf16 v[24:27], v[156:159], v[196:199], v[24:27]
	v_mfma_f32_16x16x32_bf16 v[12:15], v[148:151], v[204:207], v[12:15]
	v_mfma_f32_16x16x32_bf16 v[8:11], v[156:159], v[204:207], v[8:11]
	v_mfma_f32_16x16x32_bf16 v[60:63], v[152:155], v[184:187], v[60:63]
	v_mfma_f32_16x16x32_bf16 v[56:59], v[160:163], v[184:187], v[56:59]
	v_mfma_f32_16x16x32_bf16 v[44:47], v[152:155], v[192:195], v[44:47]
	v_mfma_f32_16x16x32_bf16 v[40:43], v[160:163], v[192:195], v[40:43]
	v_mfma_f32_16x16x32_bf16 v[28:31], v[152:155], v[200:203], v[28:31]
	v_mfma_f32_16x16x32_bf16 v[24:27], v[160:163], v[200:203], v[24:27]
	v_mfma_f32_16x16x32_bf16 v[12:15], v[152:155], v[208:211], v[12:15]
	v_mfma_f32_16x16x32_bf16 v[8:11], v[160:163], v[208:211], v[8:11]
	v_mfma_f32_16x16x32_bf16 v[52:55], v[164:167], v[180:183], v[52:55]
	v_mfma_f32_16x16x32_bf16 v[48:51], v[172:175], v[180:183], v[48:51]
	v_mfma_f32_16x16x32_bf16 v[36:39], v[164:167], v[188:191], v[36:39]
	v_mfma_f32_16x16x32_bf16 v[32:35], v[172:175], v[188:191], v[32:35]
	v_mfma_f32_16x16x32_bf16 v[20:23], v[164:167], v[196:199], v[20:23]
	v_mfma_f32_16x16x32_bf16 v[16:19], v[172:175], v[196:199], v[16:19]
	v_mfma_f32_16x16x32_bf16 v[4:7], v[164:167], v[204:207], v[4:7]
	v_mfma_f32_16x16x32_bf16 v[0:3], v[172:175], v[204:207], v[0:3]
	v_mfma_f32_16x16x32_bf16 v[52:55], v[168:171], v[184:187], v[52:55]
	v_mfma_f32_16x16x32_bf16 v[48:51], v[176:179], v[184:187], v[48:51]
	v_mfma_f32_16x16x32_bf16 v[36:39], v[168:171], v[192:195], v[36:39]
	v_mfma_f32_16x16x32_bf16 v[32:35], v[176:179], v[192:195], v[32:35]
	v_mfma_f32_16x16x32_bf16 v[20:23], v[168:171], v[200:203], v[20:23]
	v_mfma_f32_16x16x32_bf16 v[16:19], v[176:179], v[200:203], v[16:19]
	v_mfma_f32_16x16x32_bf16 v[4:7], v[168:171], v[208:211], v[4:7]
	v_mfma_f32_16x16x32_bf16 v[0:3], v[176:179], v[208:211], v[0:3]
	s_setprio 0
	s_barrier
	s_add_i32 s55, s55, 2
	s_add_u32 s22, s22, 0x100
	s_addc_u32 s23, s23, 0
	s_add_u32 s51, s51, 0x100
	s_addc_u32 s54, s54, 0

; #define PG8_STAGE(bufoff, gbase, voff) do { _Pragma("unroll") for (int _i = 0; _i < 2; ++_i) \
;         __builtin_amdgcn_global_load_lds((const unsigned*)((const char*)(gbase) + (voff)[_i]), (LAS unsigned*)(lds + (bufoff) + ldsw + _i * 8192), 16, 0, 0); } while (0)
; #define PG8_LDA(dst, b, h) do { _Pragma("unroll") for (int m = 0; m < 4; ++m) _Pragma("unroll") for (int k = 0; k < 2; ++k) dst[m][k] = *(const LAS bf16x8*)(lds + PG8_SA(b, h) + aoff + m * 2048 + k * 1024); } while (0)
; #define PG8_LDB(dst, b, h) do { _Pragma("unroll") for (int n = 0; n < 2; ++n) _Pragma("unroll") for (int k = 0; k < 2; ++k) dst[n][k] = *(const LAS bf16x8*)(lds + PG8_SB(b, h) + boff + n * 2048 + k * 1024); } while (0)
; #define PG8_WAIT_V(n) asm volatile("s_waitcnt vmcnt(" #n ")" ::: "memory")
; #define PG8_BAR __builtin_amdgcn_s_barrier()
; template <class Epi, bool ALIGN_EPI, int K, int LDA, int LDB>
; __device__ __forceinline__ void gemm_phase(LAS unsigned char* lds, const int wid, const Gemm g, const StaticOrder& S, const Epi& E) {
;     ...
;         const bool has_next = S.next(ui + 1, nxt);
;         const char* nA = has_next ? (const char*)g.A + (size_t)nxt.pm * tA : cA; const char* nB = has_next ? (const char*)g.Bt + (size_t)nxt.pn * tB : cB;
;         for (int t = 0; t < nt; t += 2) {
;             const bool last = (t == nt - 2);
;             const char* a1 = cA + (size_t)(t + 1) * kstep;
;             const char* a2 = last ? nA : cA + (size_t)(t + 2) * kstep; const char* b2 = last ? nB : cB + (size_t)(t + 2) * kstep;
;             const char* a3 = a2 + kstep; const char* b3 = b2 + kstep;
;             PG8_LDB(B0, 0, 0); PG8_LDB(B1, 0, 1); PG8_SCHED; PG8_LDA(At, 0, 0); PG8_STAGE(PG8_SA(1, 1), a1 + hA, voffA);
;             PG8_WAIT_V(8); PG8_WAIT_L(0); PG8_BAR; PG8_MMA(0, 0, At, B0); PG8_MMA(0, 1, At, B1); PG8_BAR; PG8_SCHED;
;             PG8_LDA(At, 0, 1); PG8_STAGE(PG8_SB(0, 0), b2, voffB); PG8_STAGE(PG8_SB(0, 1), b2 + hB, voffB); PG8_STAGE(PG8_SA(0, 0), a2, voffA);
;             PG8_WAIT_V(8); PG8_WAIT_L(0); PG8_BAR; PG8_MMA(1, 0, At, B0); PG8_MMA(1, 1, At, B1); PG8_BAR; PG8_SCHED;
;     ...
; #pragma unroll
;         for (int a = 0; a < 2; ++a)
; #pragma unroll
;             for (int b = 0; b < 2; ++b)
; #pragma unroll
;                 for (int m = 0; m < 4; ++m)
; #pragma unroll
;                     for (int n = 0; n < 2; ++n) acc[a][b][m][n] = (f32x4){0.f, 0.f, 0.f, 0.f};
.LBB0_1136:
	s_add_u32 s65, s28, 0x100
	s_addc_u32 s66, s29, 0
	s_mov_b32 s67, -2
	s_waitcnt vmcnt(0)
	ds_read_b128 v[128:131], v175
	ds_read_b128 v[132:135], v175 offset:1024
	ds_read_b128 v[136:139], v175 offset:2048
	ds_read_b128 v[140:143], v175 offset:3072
	ds_read_b128 v[144:147], v176
	ds_read_b128 v[164:167], v176 offset:1024
	ds_read_b128 v[168:171], v176 offset:2048
	ds_read_b128 v[178:181], v176 offset:3072
	s_add_u32 s28, s26, 0x100
	s_addc_u32 s29, s27, 0
	s_cmp_eq_u32 s67, 40
	s_cselect_b32 s35, s7, s29
	s_cselect_b32 s34, s6, s28
	s_cselect_b32 s31, s25, s66
	s_cselect_b32 s30, s24, s65
	s_add_i32 m0, s36, 0xc000
	ds_read_b128 v[182:185], v177
	ds_read_b128 v[186:189], v177 offset:1024
	ds_read_b128 v[190:193], v177 offset:2048
	ds_read_b128 v[194:197], v177 offset:3072
	ds_read_b128 v[198:201], v177 offset:4096
	ds_read_b128 v[202:205], v177 offset:5120
	ds_read_b128 v[206:209], v177 offset:6144
	ds_read_b128 v[210:213], v177 offset:7168
	global_load_lds_dwordx4 v156, s[26:27]
	s_add_i32 m0, s36, 0xe000
	s_nop 0
	global_load_lds_dwordx4 v158, s[26:27]
	s_waitcnt vmcnt(8)
	s_waitcnt lgkmcnt(0)
	s_barrier
	s_setprio 1
	s_waitcnt lgkmcnt(0)
	v_mfma_f32_16x16x32_bf16 v[124:127], v[128:131], v[182:185], 0
	v_mfma_f32_16x16x32_bf16 v[116:119], v[136:139], v[182:185], 0
	v_mfma_f32_16x16x32_bf16 v[120:123], v[128:131], v[190:193], 0
	v_mfma_f32_16x16x32_bf16 v[112:115], v[136:139], v[190:193], 0
	v_mfma_f32_16x16x32_bf16 v[92:95], v[128:131], v[198:201], 0
	v_mfma_f32_16x16x32_bf16 v[88:91], v[136:139], v[198:201], 0
	v_mfma_f32_16x16x32_bf16 v[76:79], v[128:131], v[206:209], 0
	v_mfma_f32_16x16x32_bf16 v[72:75], v[136:139], v[206:209], 0
	v_mfma_f32_16x16x32_bf16 v[124:127], v[132:135], v[186:189], v[124:127]
	v_mfma_f32_16x16x32_bf16 v[116:119], v[140:143], v[186:189], v[116:119]
	v_mfma_f32_16x16x32_bf16 v[120:123], v[132:135], v[194:197], v[120:123]
	v_mfma_f32_16x16x32_bf16 v[112:115], v[140:143], v[194:197], v[112:115]
	v_mfma_f32_16x16x32_bf16 v[92:95], v[132:135], v[202:205], v[92:95]
	v_mfma_f32_16x16x32_bf16 v[88:91], v[140:143], v[202:205], v[88:91]
	v_mfma_f32_16x16x32_bf16 v[76:79], v[132:135], v[210:213], v[76:79]
	v_mfma_f32_16x16x32_bf16 v[72:75], v[140:143], v[210:213], v[72:75]
	v_mfma_f32_16x16x32_bf16 v[108:111], v[144:147], v[182:185], 0
	v_mfma_f32_16x16x32_bf16 v[104:107], v[168:171], v[182:185], 0
	v_mfma_f32_16x16x32_bf16 v[100:103], v[144:147], v[190:193], 0
	v_mfma_f32_16x16x32_bf16 v[96:99], v[168:171], v[190:193], 0
	v_mfma_f32_16x16x32_bf16 v[84:87], v[144:147], v[198:201], 0
	v_mfma_f32_16x16x32_bf16 v[80:83], v[168:171], v[198:201], 0
	v_mfma_f32_16x16x32_bf16 v[68:71], v[144:147], v[206:209], 0
	v_mfma_f32_16x16x32_bf16 v[64:67], v[168:171], v[206:209], 0
	v_mfma_f32_16x16x32_bf16 v[108:111], v[164:167], v[186:189], v[108:111]
	v_mfma_f32_16x16x32_bf16 v[104:107], v[178:181], v[186:189], v[104:107]
	v_mfma_f32_16x16x32_bf16 v[100:103], v[164:167], v[194:197], v[100:103]
	v_mfma_f32_16x16x32_bf16 v[96:99], v[178:181], v[194:197], v[96:99]
	v_mfma_f32_16x16x32_bf16 v[84:87], v[164:167], v[202:205], v[84:87]
	v_mfma_f32_16x16x32_bf16 v[80:83], v[178:181], v[202:205], v[80:83]
	v_mfma_f32_16x16x32_bf16 v[68:71], v[164:167], v[210:213], v[68:71]
	v_mfma_f32_16x16x32_bf16 v[64:67], v[178:181], v[210:213], v[64:67]
	s_setprio 0
	s_barrier
	s_add_u32 s98, s30, s12
	s_addc_u32 s99, s31, s13
	s_add_u32 s100, s34, s12
	s_addc_u32 s101, s35, s13
	s_add_i32 s26, s54, s33
	s_mov_b32 m0, s26
	ds_read_b128 v[182:185], v177 offset:16384
	ds_read_b128 v[186:189], v177 offset:17408
	ds_read_b128 v[190:193], v177 offset:18432
	ds_read_b128 v[194:197], v177 offset:19456
	ds_read_b128 v[198:201], v177 offset:20480
	ds_read_b128 v[202:205], v177 offset:21504
	ds_read_b128 v[206:209], v177 offset:22528
	ds_read_b128 v[210:213], v177 offset:23552
	global_load_lds_dwordx4 v150, s[30:31]
	s_add_i32 m0, s26, 0x2000
	s_add_u32 s26, s30, 0xb0000
	s_addc_u32 s27, s31, 0
	s_add_i32 s52, s55, s33
	global_load_lds_dwordx4 v154, s[30:31]
	s_mov_b32 m0, s52
	s_nop 0
	global_load_lds_dwordx4 v150, s[26:27]
	s_add_i32 m0, s52, 0x2000
	s_nop 0
	global_load_lds_dwordx4 v154, s[26:27]
	s_mov_b32 m0, s36
	s_nop 0
	global_load_lds_dwordx4 v148, s[34:35]
	s_mov_b32 m0, s37
	s_nop 0
	global_load_lds_dwordx4 v152, s[34:35]
	s_waitcnt vmcnt(8)
	s_waitcnt lgkmcnt(0)
	s_barrier
	s_setprio 1
	s_waitcnt lgkmcnt(0)
	v_mfma_f32_16x16x32_bf16 v[60:63], v[128:131], v[182:185], 0
	v_mfma_f32_16x16x32_bf16 v[56:59], v[136:139], v[182:185], 0
	v_mfma_f32_16x16x32_bf16 v[44:47], v[128:131], v[190:193], 0
	v_mfma_f32_16x16x32_bf16 v[40:43], v[136:139], v[190:193], 0
	v_mfma_f32_16x16x32_bf16 v[36:39], v[128:131], v[198:201], 0
	v_mfma_f32_16x16x32_bf16 v[32:35], v[136:139], v[198:201], 0
	v_mfma_f32_16x16x32_bf16 v[20:23], v[128:131], v[206:209], 0
	v_mfma_f32_16x16x32_bf16 v[16:19], v[136:139], v[206:209], 0
	v_mfma_f32_16x16x32_bf16 v[60:63], v[132:135], v[186:189], v[60:63]
	v_mfma_f32_16x16x32_bf16 v[56:59], v[140:143], v[186:189], v[56:59]
	v_mfma_f32_16x16x32_bf16 v[44:47], v[132:135], v[194:197], v[44:47]
	v_mfma_f32_16x16x32_bf16 v[40:43], v[140:143], v[194:197], v[40:43]
	v_mfma_f32_16x16x32_bf16 v[36:39], v[132:135], v[202:205], v[36:39]
	v_mfma_f32_16x16x32_bf16 v[32:35], v[140:143], v[202:205], v[32:35]
	v_mfma_f32_16x16x32_bf16 v[20:23], v[132:135], v[210:213], v[20:23]
	v_mfma_f32_16x16x32_bf16 v[16:19], v[140:143], v[210:213], v[16:19]
	v_mfma_f32_16x16x32_bf16 v[52:55], v[144:147], v[182:185], 0
	v_mfma_f32_16x16x32_bf16 v[48:51], v[168:171], v[182:185], 0
	v_mfma_f32_16x16x32_bf16 v[28:31], v[144:147], v[190:193], 0
	v_mfma_f32_16x16x32_bf16 v[24:27], v[168:171], v[190:193], 0
	v_mfma_f32_16x16x32_bf16 v[12:15], v[144:147], v[198:201], 0
	v_mfma_f32_16x16x32_bf16 v[8:11], v[168:171], v[198:201], 0
	v_mfma_f32_16x16x32_bf16 v[4:7], v[144:147], v[206:209], 0
	v_mfma_f32_16x16x32_bf16 v[0:3], v[168:171], v[206:209], 0
	v_mfma_f32_16x16x32_bf16 v[52:55], v[164:167], v[186:189], v[52:55]
	v_mfma_f32_16x16x32_bf16 v[48:51], v[178:181], v[186:189], v[48:51]
	v_mfma_f32_16x16x32_bf16 v[28:31], v[164:167], v[194:197], v[28:31]
	v_mfma_f32_16x16x32_bf16 v[24:27], v[178:181], v[194:197], v[24:27]
	v_mfma_f32_16x16x32_bf16 v[12:15], v[164:167], v[202:205], v[12:15]
	v_mfma_f32_16x16x32_bf16 v[8:11], v[178:181], v[202:205], v[8:11]
	v_mfma_f32_16x16x32_bf16 v[4:7], v[164:167], v[210:213], v[4:7]
	v_mfma_f32_16x16x32_bf16 v[0:3], v[178:181], v[210:213], v[0:3]
	s_setprio 0
	s_barrier
; #define PG8_STAGE(bufoff, gbase, voff) do { _Pragma("unroll") for (int _i = 0; _i < 2; ++_i) \
;         __builtin_amdgcn_global_load_lds((const unsigned*)((const char*)(gbase) + (voff)[_i]), (LAS unsigned*)(lds + (bufoff) + ldsw + _i * 8192), 16, 0, 0); } while (0)
; #define PG8_LDA(dst, b, h) do { _Pragma("unroll") for (int m = 0; m < 4; ++m) _Pragma("unroll") for (int k = 0; k < 2; ++k) dst[m][k] = *(const LAS bf16x8*)(lds + PG8_SA(b, h) + aoff + m * 2048 + k * 1024); } while (0)
; #define PG8_LDB(dst, b, h) do { _Pragma("unroll") for (int n = 0; n < 2; ++n) _Pragma("unroll") for (int k = 0; k < 2; ++k) dst[n][k] = *(const LAS bf16x8*)(lds + PG8_SB(b, h) + boff + n * 2048 + k * 1024); } while (0)
; #define PG8_MMA(ai, bj, At, Bt) do { __builtin_amdgcn_s_setprio(1); _Pragma("unroll") for (int m = 0; m < 4; ++m) _Pragma("unroll") for (int n = 0; n < 2; ++n) _Pragma("unroll") for (int k = 0; k < 2; ++k) \
;         acc[ai][bj][m][n] = __builtin_amdgcn_mfma_f32_16x16x32_bf16(Bt[n][k], At[m][k], acc[ai][bj][m][n], 0, 0, 0); __builtin_amdgcn_s_setprio(0); } while (0)
; #define PG8_WAIT_V(n) asm volatile("s_waitcnt vmcnt(" #n ")" ::: "memory")
; #define PG8_WAIT_L(n) asm volatile("s_waitcnt lgkmcnt(" #n ")" ::: "memory")
; #define PG8_BAR __builtin_amdgcn_s_barrier()
; #define PG8_SCHED __builtin_amdgcn_sched_barrier(0)
; template <class Epi, bool ALIGN_EPI, int K, int LDA, int LDB>
; __device__ __forceinline__ void gemm_phase(LAS unsigned char* lds, const int wid, const Gemm g, const StaticOrder& S, const Epi& E) {
;     ...
;             PG8_LDB(B0, 1, 0); PG8_LDB(B1, 1, 1); PG8_SCHED; PG8_LDA(At, 1, 0); PG8_STAGE(PG8_SA(0, 1), a2 + hA, voffA);
;             PG8_WAIT_V(8); PG8_WAIT_L(0); PG8_BAR; PG8_MMA(0, 0, At, B0); PG8_MMA(0, 1, At, B1); PG8_BAR; PG8_SCHED;
;             PG8_LDA(At, 1, 1); PG8_STAGE(PG8_SB(1, 0), b3, voffB); PG8_STAGE(PG8_SB(1, 1), b3 + hB, voffB); PG8_STAGE(PG8_SA(1, 0), a3, voffA);
;             PG8_WAIT_V(8); PG8_WAIT_L(0); PG8_BAR; PG8_MMA(1, 0, At, B0); PG8_MMA(1, 1, At, B1); PG8_BAR; PG8_SCHED;
;         }
	s_add_i32 s52, 0, 0x18000
	s_add_i32 s53, 0, 0x1c000
	v_add_u32_e32 v140, s52, v174
	v_add_u32_e32 v178, s53, v174
	ds_read_b128 v[128:131], v140
	ds_read_b128 v[132:135], v140 offset:1024
	ds_read_b128 v[136:139], v140 offset:2048
	ds_read_b128 v[140:143], v140 offset:3072
	ds_read_b128 v[144:147], v178
	ds_read_b128 v[164:167], v178 offset:1024
	ds_read_b128 v[168:171], v178 offset:2048
	ds_read_b128 v[178:181], v178 offset:3072
	s_add_u32 s26, s34, 0xb0000
	s_addc_u32 s27, s35, 0
	s_mov_b32 m0, s38
	ds_read_b128 v[182:185], v177 offset:32768
	ds_read_b128 v[186:189], v177 offset:33792
	ds_read_b128 v[190:193], v177 offset:34816
	ds_read_b128 v[194:197], v177 offset:35840
	ds_read_b128 v[198:201], v177 offset:36864
	ds_read_b128 v[202:205], v177 offset:37888
	ds_read_b128 v[206:209], v177 offset:38912
	ds_read_b128 v[210:213], v177 offset:39936
	global_load_lds_dwordx4 v148, s[26:27]
	s_mov_b32 m0, s39
	s_nop 0
	global_load_lds_dwordx4 v152, s[26:27]
	s_waitcnt vmcnt(8)
	s_waitcnt lgkmcnt(0)
	s_barrier
	s_setprio 1
	s_waitcnt lgkmcnt(0)
	v_mfma_f32_16x16x32_bf16 v[124:127], v[128:131], v[182:185], v[124:127]
	v_mfma_f32_16x16x32_bf16 v[116:119], v[136:139], v[182:185], v[116:119]
	v_mfma_f32_16x16x32_bf16 v[120:123], v[128:131], v[190:193], v[120:123]
	v_mfma_f32_16x16x32_bf16 v[112:115], v[136:139], v[190:193], v[112:115]
	v_mfma_f32_16x16x32_bf16 v[92:95], v[128:131], v[198:201], v[92:95]
	v_mfma_f32_16x16x32_bf16 v[88:91], v[136:139], v[198:201], v[88:91]
	v_mfma_f32_16x16x32_bf16 v[76:79], v[128:131], v[206:209], v[76:79]
	v_mfma_f32_16x16x32_bf16 v[72:75], v[136:139], v[206:209], v[72:75]
	v_mfma_f32_16x16x32_bf16 v[124:127], v[132:135], v[186:189], v[124:127]
	v_mfma_f32_16x16x32_bf16 v[116:119], v[140:143], v[186:189], v[116:119]
	v_mfma_f32_16x16x32_bf16 v[120:123], v[132:135], v[194:197], v[120:123]
	v_mfma_f32_16x16x32_bf16 v[112:115], v[140:143], v[194:197], v[112:115]
	v_mfma_f32_16x16x32_bf16 v[92:95], v[132:135], v[202:205], v[92:95]
	v_mfma_f32_16x16x32_bf16 v[88:91], v[140:143], v[202:205], v[88:91]
	v_mfma_f32_16x16x32_bf16 v[76:79], v[132:135], v[210:213], v[76:79]
	v_mfma_f32_16x16x32_bf16 v[72:75], v[140:143], v[210:213], v[72:75]
	v_mfma_f32_16x16x32_bf16 v[108:111], v[144:147], v[182:185], v[108:111]
	v_mfma_f32_16x16x32_bf16 v[104:107], v[168:171], v[182:185], v[104:107]
	v_mfma_f32_16x16x32_bf16 v[100:103], v[144:147], v[190:193], v[100:103]
	v_mfma_f32_16x16x32_bf16 v[96:99], v[168:171], v[190:193], v[96:99]
	v_mfma_f32_16x16x32_bf16 v[84:87], v[144:147], v[198:201], v[84:87]
	v_mfma_f32_16x16x32_bf16 v[80:83], v[168:171], v[198:201], v[80:83]
	v_mfma_f32_16x16x32_bf16 v[68:71], v[144:147], v[206:209], v[68:71]
	v_mfma_f32_16x16x32_bf16 v[64:67], v[168:171], v[206:209], v[64:67]
	v_mfma_f32_16x16x32_bf16 v[108:111], v[164:167], v[186:189], v[108:111]
	v_mfma_f32_16x16x32_bf16 v[104:107], v[178:181], v[186:189], v[104:107]
	v_mfma_f32_16x16x32_bf16 v[100:103], v[164:167], v[194:197], v[100:103]
	v_mfma_f32_16x16x32_bf16 v[96:99], v[178:181], v[194:197], v[96:99]
	v_mfma_f32_16x16x32_bf16 v[84:87], v[164:167], v[202:205], v[84:87]
	v_mfma_f32_16x16x32_bf16 v[80:83], v[178:181], v[202:205], v[80:83]
	v_mfma_f32_16x16x32_bf16 v[68:71], v[164:167], v[210:213], v[68:71]
	v_mfma_f32_16x16x32_bf16 v[64:67], v[178:181], v[210:213], v[64:67]
	s_setprio 0
	s_barrier
	s_add_i32 s26, s52, s33
	s_mov_b32 m0, s26
	ds_read_b128 v[182:185], v177 offset:49152
	ds_read_b128 v[186:189], v177 offset:50176
	ds_read_b128 v[190:193], v177 offset:51200
	ds_read_b128 v[194:197], v177 offset:52224
	ds_read_b128 v[198:201], v177 offset:53248
	ds_read_b128 v[202:205], v177 offset:54272
	ds_read_b128 v[206:209], v177 offset:55296
	ds_read_b128 v[210:213], v177 offset:56320
	global_load_lds_dwordx4 v150, s[98:99]
	s_add_i32 m0, s26, 0x2000
	s_add_u32 s26, s30, 0xb0080
	s_addc_u32 s27, s31, 0
	s_add_i32 s30, s53, s33
	global_load_lds_dwordx4 v154, s[98:99]
	s_mov_b32 m0, s30
	s_nop 0
	global_load_lds_dwordx4 v150, s[26:27]
	s_add_i32 m0, s30, 0x2000
	s_nop 0
	global_load_lds_dwordx4 v154, s[26:27]
	s_mov_b32 m0, s48
	s_nop 0
	global_load_lds_dwordx4 v148, s[100:101]
	s_mov_b32 m0, s49
	s_nop 0
	global_load_lds_dwordx4 v152, s[100:101]
	s_waitcnt vmcnt(8)
	s_waitcnt lgkmcnt(0)
	s_barrier
	s_setprio 1
	s_waitcnt lgkmcnt(0)
	v_mfma_f32_16x16x32_bf16 v[60:63], v[128:131], v[182:185], v[60:63]
	v_mfma_f32_16x16x32_bf16 v[56:59], v[136:139], v[182:185], v[56:59]
	v_mfma_f32_16x16x32_bf16 v[44:47], v[128:131], v[190:193], v[44:47]
	v_mfma_f32_16x16x32_bf16 v[40:43], v[136:139], v[190:193], v[40:43]
	v_mfma_f32_16x16x32_bf16 v[36:39], v[128:131], v[198:201], v[36:39]
	v_mfma_f32_16x16x32_bf16 v[32:35], v[136:139], v[198:201], v[32:35]
	v_mfma_f32_16x16x32_bf16 v[20:23], v[128:131], v[206:209], v[20:23]
	v_mfma_f32_16x16x32_bf16 v[16:19], v[136:139], v[206:209], v[16:19]
	v_mfma_f32_16x16x32_bf16 v[60:63], v[132:135], v[186:189], v[60:63]
	v_mfma_f32_16x16x32_bf16 v[56:59], v[140:143], v[186:189], v[56:59]
	v_mfma_f32_16x16x32_bf16 v[44:47], v[132:135], v[194:197], v[44:47]
	v_mfma_f32_16x16x32_bf16 v[40:43], v[140:143], v[194:197], v[40:43]
	v_mfma_f32_16x16x32_bf16 v[36:39], v[132:135], v[202:205], v[36:39]
	v_mfma_f32_16x16x32_bf16 v[32:35], v[140:143], v[202:205], v[32:35]
	v_mfma_f32_16x16x32_bf16 v[20:23], v[132:135], v[210:213], v[20:23]
	v_mfma_f32_16x16x32_bf16 v[16:19], v[140:143], v[210:213], v[16:19]
	v_mfma_f32_16x16x32_bf16 v[52:55], v[144:147], v[182:185], v[52:55]
	v_mfma_f32_16x16x32_bf16 v[48:51], v[168:171], v[182:185], v[48:51]
	v_mfma_f32_16x16x32_bf16 v[28:31], v[144:147], v[190:193], v[28:31]
	v_mfma_f32_16x16x32_bf16 v[24:27], v[168:171], v[190:193], v[24:27]
	v_mfma_f32_16x16x32_bf16 v[12:15], v[144:147], v[198:201], v[12:15]
	v_mfma_f32_16x16x32_bf16 v[8:11], v[168:171], v[198:201], v[8:11]
	v_mfma_f32_16x16x32_bf16 v[4:7], v[144:147], v[206:209], v[4:7]
	v_mfma_f32_16x16x32_bf16 v[0:3], v[168:171], v[206:209], v[0:3]
	v_mfma_f32_16x16x32_bf16 v[52:55], v[164:167], v[186:189], v[52:55]
	v_mfma_f32_16x16x32_bf16 v[48:51], v[178:181], v[186:189], v[48:51]
	v_mfma_f32_16x16x32_bf16 v[28:31], v[164:167], v[194:197], v[28:31]
	v_mfma_f32_16x16x32_bf16 v[24:27], v[178:181], v[194:197], v[24:27]
	v_mfma_f32_16x16x32_bf16 v[12:15], v[164:167], v[202:205], v[12:15]
	v_mfma_f32_16x16x32_bf16 v[8:11], v[178:181], v[202:205], v[8:11]
	v_mfma_f32_16x16x32_bf16 v[4:7], v[164:167], v[210:213], v[4:7]
	v_mfma_f32_16x16x32_bf16 v[0:3], v[178:181], v[210:213], v[0:3]
	s_setprio 0
	s_barrier
	s_add_i32 s67, s67, 2
	s_add_u32 s65, s65, 0x100
	s_addc_u32 s66, s66, 0
	s_mov_b64 s[26:27], s[28:29]

; #define PG8_STAGE(bufoff, gbase, voff) do { _Pragma("unroll") for (int _i = 0; _i < 2; ++_i) \
;         __builtin_amdgcn_global_load_lds((const unsigned*)((const char*)(gbase) + (voff)[_i]), (LAS unsigned*)(lds + (bufoff) + ldsw + _i * 8192), 16, 0, 0); } while (0)
; #define PG8_LDA(dst, b, h) do { _Pragma("unroll") for (int m = 0; m < 4; ++m) _Pragma("unroll") for (int k = 0; k < 2; ++k) dst[m][k] = *(const LAS bf16x8*)(lds + PG8_SA(b, h) + aoff + m * 2048 + k * 1024); } while (0)
; #define PG8_LDB(dst, b, h) do { _Pragma("unroll") for (int n = 0; n < 2; ++n) _Pragma("unroll") for (int k = 0; k < 2; ++k) dst[n][k] = *(const LAS bf16x8*)(lds + PG8_SB(b, h) + boff + n * 2048 + k * 1024); } while (0)
; #define PG8_MMA(ai, bj, At, Bt) do { __builtin_amdgcn_s_setprio(1); _Pragma("unroll") for (int m = 0; m < 4; ++m) _Pragma("unroll") for (int n = 0; n < 2; ++n) _Pragma("unroll") for (int k = 0; k < 2; ++k) \
;         acc[ai][bj][m][n] = __builtin_amdgcn_mfma_f32_16x16x32_bf16(Bt[n][k], At[m][k], acc[ai][bj][m][n], 0, 0, 0); __builtin_amdgcn_s_setprio(0); } while (0)
; template <class Epi, bool ALIGN_EPI, int K, int LDA, int LDB>
; __device__ __forceinline__ void gemm_phase(LAS unsigned char* lds, const int wid, const Gemm g, const StaticOrder& S, const Epi& E) {
;     ...
;         const bool has_next = S.next(ui + 1, nxt);
;         const char* nA = has_next ? (const char*)g.A + (size_t)nxt.pm * tA : cA; const char* nB = has_next ? (const char*)g.Bt + (size_t)nxt.pn * tB : cB;
;         for (int t = 0; t < nt; t += 2) {
;             const bool last = (t == nt - 2);
;             const char* a1 = cA + (size_t)(t + 1) * kstep;
;             const char* a2 = last ? nA : cA + (size_t)(t + 2) * kstep; const char* b2 = last ? nB : cB + (size_t)(t + 2) * kstep;
;             const char* a3 = a2 + kstep; const char* b3 = b2 + kstep;
;             PG8_LDB(B0, 0, 0); PG8_LDB(B1, 0, 1); PG8_SCHED; PG8_LDA(At, 0, 0); PG8_STAGE(PG8_SA(1, 1), a1 + hA, voffA);
;             PG8_WAIT_V(8); PG8_WAIT_L(0); PG8_BAR; PG8_MMA(0, 0, At, B0); PG8_MMA(0, 1, At, B1); PG8_BAR; PG8_SCHED;
;     ...
; #pragma unroll
;         for (int a = 0; a < 2; ++a)
; #pragma unroll
;             for (int b = 0; b < 2; ++b)
; #pragma unroll
;                 for (int m = 0; m < 4; ++m)
; #pragma unroll
;                     for (int n = 0; n < 2; ++n) acc[a][b][m][n] = (f32x4){0.f, 0.f, 0.f, 0.f};
.LBB0_1278:
	s_ashr_i32 s25, s24, 31
	s_lshl_b64 s[26:27], s[24:25], 19
	v_readlane_b32 s7, v254, 0
	s_add_u32 s26, s7, s26
	v_readlane_b32 s7, v254, 1
	s_addc_u32 s27, s7, s27
	s_and_b64 s[28:29], s[4:5], exec
	s_cselect_b32 s7, s27, s35
	s_cselect_b32 s25, s26, s34
	s_ashr_i32 s23, s22, 31
	s_lshl_b64 s[28:29], s[22:23], 19
	s_add_u32 s28, s0, s28
	s_addc_u32 s29, s1, s29
	s_and_b64 s[38:39], s[4:5], exec
	s_cselect_b32 s23, s29, s37
	s_cselect_b32 s42, s28, s36
	s_add_u32 s34, s34, 0x40080
	s_addc_u32 s35, s35, 0
	s_add_u32 s59, s36, 0x100
	s_addc_u32 s60, s37, 0
	s_mov_b32 s61, -2
	ds_read_b128 v[144:147], v151
	ds_read_b128 v[154:157], v151 offset:1024
	ds_read_b128 v[158:161], v151 offset:2048
	ds_read_b128 v[162:165], v151 offset:3072
	ds_read_b128 v[166:169], v152
	ds_read_b128 v[170:173], v152 offset:1024
	ds_read_b128 v[174:177], v152 offset:2048
	ds_read_b128 v[178:181], v152 offset:3072
	s_add_u32 s36, s34, 0xfffc0080
	s_addc_u32 s37, s35, -1
	s_cmp_eq_u32 s61, 12
	s_cselect_b32 s39, s7, s37
	s_cselect_b32 s38, s25, s36
	s_cselect_b32 s37, s23, s60
	s_cselect_b32 s36, s42, s59
	s_add_i32 m0, s31, 0xc000
	ds_read_b128 v[182:185], v153
	ds_read_b128 v[186:189], v153 offset:1024
	ds_read_b128 v[190:193], v153 offset:2048
	ds_read_b128 v[194:197], v153 offset:3072
	ds_read_b128 v[198:201], v153 offset:4096
	ds_read_b128 v[202:205], v153 offset:5120
	ds_read_b128 v[206:209], v153 offset:6144
	ds_read_b128 v[210:213], v153 offset:7168
	global_load_lds_dwordx4 v136, s[34:35]
	s_add_i32 m0, s31, 0xe000
	s_nop 0
	global_load_lds_dwordx4 v138, s[34:35]
	s_waitcnt vmcnt(8)
	s_waitcnt lgkmcnt(0)
	s_barrier
	s_setprio 1
	s_waitcnt lgkmcnt(0)
	v_mfma_f32_16x16x32_bf16 v[124:127], v[144:147], v[182:185], 0
	v_mfma_f32_16x16x32_bf16 v[120:123], v[158:161], v[182:185], 0
	v_mfma_f32_16x16x32_bf16 v[108:111], v[144:147], v[190:193], 0
	v_mfma_f32_16x16x32_bf16 v[104:107], v[158:161], v[190:193], 0
	v_mfma_f32_16x16x32_bf16 v[92:95], v[144:147], v[198:201], 0
	v_mfma_f32_16x16x32_bf16 v[88:91], v[158:161], v[198:201], 0
	v_mfma_f32_16x16x32_bf16 v[76:79], v[144:147], v[206:209], 0
	v_mfma_f32_16x16x32_bf16 v[72:75], v[158:161], v[206:209], 0
	v_mfma_f32_16x16x32_bf16 v[124:127], v[154:157], v[186:189], v[124:127]
	v_mfma_f32_16x16x32_bf16 v[120:123], v[162:165], v[186:189], v[120:123]
	v_mfma_f32_16x16x32_bf16 v[108:111], v[154:157], v[194:197], v[108:111]
	v_mfma_f32_16x16x32_bf16 v[104:107], v[162:165], v[194:197], v[104:107]
	v_mfma_f32_16x16x32_bf16 v[92:95], v[154:157], v[202:205], v[92:95]
	v_mfma_f32_16x16x32_bf16 v[88:91], v[162:165], v[202:205], v[88:91]
	v_mfma_f32_16x16x32_bf16 v[76:79], v[154:157], v[210:213], v[76:79]
	v_mfma_f32_16x16x32_bf16 v[72:75], v[162:165], v[210:213], v[72:75]
	v_mfma_f32_16x16x32_bf16 v[116:119], v[166:169], v[182:185], 0
	v_mfma_f32_16x16x32_bf16 v[112:115], v[174:177], v[182:185], 0
	v_mfma_f32_16x16x32_bf16 v[100:103], v[166:169], v[190:193], 0
	v_mfma_f32_16x16x32_bf16 v[96:99], v[174:177], v[190:193], 0
	v_mfma_f32_16x16x32_bf16 v[84:87], v[166:169], v[198:201], 0
	v_mfma_f32_16x16x32_bf16 v[80:83], v[174:177], v[198:201], 0
	v_mfma_f32_16x16x32_bf16 v[68:71], v[166:169], v[206:209], 0
	v_mfma_f32_16x16x32_bf16 v[64:67], v[174:177], v[206:209], 0
	v_mfma_f32_16x16x32_bf16 v[116:119], v[170:173], v[186:189], v[116:119]
	v_mfma_f32_16x16x32_bf16 v[112:115], v[178:181], v[186:189], v[112:115]
	v_mfma_f32_16x16x32_bf16 v[100:103], v[170:173], v[194:197], v[100:103]
	v_mfma_f32_16x16x32_bf16 v[96:99], v[178:181], v[194:197], v[96:99]
	v_mfma_f32_16x16x32_bf16 v[84:87], v[170:173], v[202:205], v[84:87]
	v_mfma_f32_16x16x32_bf16 v[80:83], v[178:181], v[202:205], v[80:83]
	v_mfma_f32_16x16x32_bf16 v[68:71], v[170:173], v[210:213], v[68:71]
	v_mfma_f32_16x16x32_bf16 v[64:67], v[178:181], v[210:213], v[64:67]
	s_setprio 0
	s_barrier
	s_add_u32 s98, s36, s12
	s_addc_u32 s99, s37, s13
	s_add_u32 s100, s38, s12
	s_addc_u32 s101, s39, s13
	s_add_i32 s52, s57, s3
	s_mov_b32 m0, s52
	ds_read_b128 v[182:185], v153 offset:16384
	ds_read_b128 v[186:189], v153 offset:17408
	ds_read_b128 v[190:193], v153 offset:18432
	ds_read_b128 v[194:197], v153 offset:19456
	ds_read_b128 v[198:201], v153 offset:20480
	ds_read_b128 v[202:205], v153 offset:21504
	ds_read_b128 v[206:209], v153 offset:22528
	ds_read_b128 v[210:213], v153 offset:23552
	global_load_lds_dwordx4 v130, s[36:37]
	s_add_i32 m0, s52, 0x2000
	s_add_u32 s62, s36, 0x40000
	s_addc_u32 s63, s37, 0
	s_add_i32 s52, s58, s3
	global_load_lds_dwordx4 v134, s[36:37]
	s_mov_b32 m0, s52
	s_nop 0
	global_load_lds_dwordx4 v130, s[62:63]
	s_add_i32 m0, s52, 0x2000
	s_nop 0
	global_load_lds_dwordx4 v134, s[62:63]
	s_mov_b32 m0, s31
	s_nop 0
	global_load_lds_dwordx4 v128, s[38:39]
	s_mov_b32 m0, s33
	s_nop 0
	global_load_lds_dwordx4 v132, s[38:39]
	s_waitcnt vmcnt(8)
	s_waitcnt lgkmcnt(0)
	s_barrier
; #define PG8_STAGE(bufoff, gbase, voff) do { _Pragma("unroll") for (int _i = 0; _i < 2; ++_i) \
;         __builtin_amdgcn_global_load_lds((const unsigned*)((const char*)(gbase) + (voff)[_i]), (LAS unsigned*)(lds + (bufoff) + ldsw + _i * 8192), 16, 0, 0); } while (0)
; #define PG8_LDA(dst, b, h) do { _Pragma("unroll") for (int m = 0; m < 4; ++m) _Pragma("unroll") for (int k = 0; k < 2; ++k) dst[m][k] = *(const LAS bf16x8*)(lds + PG8_SA(b, h) + aoff + m * 2048 + k * 1024); } while (0)
; #define PG8_LDB(dst, b, h) do { _Pragma("unroll") for (int n = 0; n < 2; ++n) _Pragma("unroll") for (int k = 0; k < 2; ++k) dst[n][k] = *(const LAS bf16x8*)(lds + PG8_SB(b, h) + boff + n * 2048 + k * 1024); } while (0)
; #define PG8_MMA(ai, bj, At, Bt) do { __builtin_amdgcn_s_setprio(1); _Pragma("unroll") for (int m = 0; m < 4; ++m) _Pragma("unroll") for (int n = 0; n < 2; ++n) _Pragma("unroll") for (int k = 0; k < 2; ++k) \
;         acc[ai][bj][m][n] = __builtin_amdgcn_mfma_f32_16x16x32_bf16(Bt[n][k], At[m][k], acc[ai][bj][m][n], 0, 0, 0); __builtin_amdgcn_s_setprio(0); } while (0)
; #define PG8_WAIT_V(n) asm volatile("s_waitcnt vmcnt(" #n ")" ::: "memory")
; #define PG8_WAIT_L(n) asm volatile("s_waitcnt lgkmcnt(" #n ")" ::: "memory")
; #define PG8_BAR __builtin_amdgcn_s_barrier()
; #define PG8_SCHED __builtin_amdgcn_sched_barrier(0)
; template <class Epi, bool ALIGN_EPI, int K, int LDA, int LDB>
; __device__ __forceinline__ void gemm_phase(LAS unsigned char* lds, const int wid, const Gemm g, const StaticOrder& S, const Epi& E) {
;     ...
;             PG8_WAIT_V(8); PG8_WAIT_L(0); PG8_BAR; PG8_MMA(1, 0, At, B0); PG8_MMA(1, 1, At, B1); PG8_BAR; PG8_SCHED;
;             PG8_LDB(B0, 1, 0); PG8_LDB(B1, 1, 1); PG8_SCHED; PG8_LDA(At, 1, 0); PG8_STAGE(PG8_SA(0, 1), a2 + hA, voffA);
;             PG8_WAIT_V(8); PG8_WAIT_L(0); PG8_BAR; PG8_MMA(0, 0, At, B0); PG8_MMA(0, 1, At, B1); PG8_BAR; PG8_SCHED;
	s_setprio 1
	s_waitcnt lgkmcnt(0)
	v_mfma_f32_16x16x32_bf16 v[60:63], v[144:147], v[182:185], 0
	v_mfma_f32_16x16x32_bf16 v[56:59], v[158:161], v[182:185], 0
	v_mfma_f32_16x16x32_bf16 v[44:47], v[144:147], v[190:193], 0
	v_mfma_f32_16x16x32_bf16 v[40:43], v[158:161], v[190:193], 0
	v_mfma_f32_16x16x32_bf16 v[28:31], v[144:147], v[198:201], 0
	v_mfma_f32_16x16x32_bf16 v[24:27], v[158:161], v[198:201], 0
	v_mfma_f32_16x16x32_bf16 v[12:15], v[144:147], v[206:209], 0
	v_mfma_f32_16x16x32_bf16 v[8:11], v[158:161], v[206:209], 0
	v_mfma_f32_16x16x32_bf16 v[60:63], v[154:157], v[186:189], v[60:63]
	v_mfma_f32_16x16x32_bf16 v[56:59], v[162:165], v[186:189], v[56:59]
	v_mfma_f32_16x16x32_bf16 v[44:47], v[154:157], v[194:197], v[44:47]
	v_mfma_f32_16x16x32_bf16 v[40:43], v[162:165], v[194:197], v[40:43]
	v_mfma_f32_16x16x32_bf16 v[28:31], v[154:157], v[202:205], v[28:31]
	v_mfma_f32_16x16x32_bf16 v[24:27], v[162:165], v[202:205], v[24:27]
	v_mfma_f32_16x16x32_bf16 v[12:15], v[154:157], v[210:213], v[12:15]
	v_mfma_f32_16x16x32_bf16 v[8:11], v[162:165], v[210:213], v[8:11]
	v_mfma_f32_16x16x32_bf16 v[52:55], v[166:169], v[182:185], 0
	v_mfma_f32_16x16x32_bf16 v[48:51], v[174:177], v[182:185], 0
	v_mfma_f32_16x16x32_bf16 v[36:39], v[166:169], v[190:193], 0
	v_mfma_f32_16x16x32_bf16 v[32:35], v[174:177], v[190:193], 0
	v_mfma_f32_16x16x32_bf16 v[20:23], v[166:169], v[198:201], 0
	v_mfma_f32_16x16x32_bf16 v[16:19], v[174:177], v[198:201], 0
	v_mfma_f32_16x16x32_bf16 v[4:7], v[166:169], v[206:209], 0
	v_mfma_f32_16x16x32_bf16 v[0:3], v[174:177], v[206:209], 0
	v_mfma_f32_16x16x32_bf16 v[52:55], v[170:173], v[186:189], v[52:55]
	v_mfma_f32_16x16x32_bf16 v[48:51], v[178:181], v[186:189], v[48:51]
	v_mfma_f32_16x16x32_bf16 v[36:39], v[170:173], v[194:197], v[36:39]
	v_mfma_f32_16x16x32_bf16 v[32:35], v[178:181], v[194:197], v[32:35]
	v_mfma_f32_16x16x32_bf16 v[20:23], v[170:173], v[202:205], v[20:23]
	v_mfma_f32_16x16x32_bf16 v[16:19], v[178:181], v[202:205], v[16:19]
	v_mfma_f32_16x16x32_bf16 v[4:7], v[170:173], v[210:213], v[4:7]
	v_mfma_f32_16x16x32_bf16 v[0:3], v[178:181], v[210:213], v[0:3]
	s_setprio 0
	s_barrier
	s_add_i32 s52, 0, 0x18000
	s_add_i32 s53, 0, 0x1c000
	v_add_u32_e32 v162, s52, v150
	v_add_u32_e32 v178, s53, v150
	ds_read_b128 v[144:147], v162
	ds_read_b128 v[154:157], v162 offset:1024
	ds_read_b128 v[158:161], v162 offset:2048
	ds_read_b128 v[162:165], v162 offset:3072
	ds_read_b128 v[166:169], v178
	ds_read_b128 v[170:173], v178 offset:1024
	ds_read_b128 v[174:177], v178 offset:2048
	ds_read_b128 v[178:181], v178 offset:3072
	s_add_u32 s38, s38, 0x40000
	s_addc_u32 s39, s39, 0
	s_mov_b32 m0, s40
	ds_read_b128 v[182:185], v153 offset:32768
	ds_read_b128 v[186:189], v153 offset:33792
	ds_read_b128 v[190:193], v153 offset:34816
	ds_read_b128 v[194:197], v153 offset:35840
	ds_read_b128 v[198:201], v153 offset:36864
	ds_read_b128 v[202:205], v153 offset:37888
	ds_read_b128 v[206:209], v153 offset:38912
	ds_read_b128 v[210:213], v153 offset:39936
	global_load_lds_dwordx4 v128, s[38:39]
	s_mov_b32 m0, s41
	s_nop 0
	global_load_lds_dwordx4 v132, s[38:39]
	s_waitcnt vmcnt(8)
	s_waitcnt lgkmcnt(0)
	s_barrier
	s_setprio 1
	s_waitcnt lgkmcnt(0)
	v_mfma_f32_16x16x32_bf16 v[124:127], v[144:147], v[182:185], v[124:127]
	v_mfma_f32_16x16x32_bf16 v[120:123], v[158:161], v[182:185], v[120:123]
	v_mfma_f32_16x16x32_bf16 v[108:111], v[144:147], v[190:193], v[108:111]
	v_mfma_f32_16x16x32_bf16 v[104:107], v[158:161], v[190:193], v[104:107]
	v_mfma_f32_16x16x32_bf16 v[92:95], v[144:147], v[198:201], v[92:95]
	v_mfma_f32_16x16x32_bf16 v[88:91], v[158:161], v[198:201], v[88:91]
	v_mfma_f32_16x16x32_bf16 v[76:79], v[144:147], v[206:209], v[76:79]
	v_mfma_f32_16x16x32_bf16 v[72:75], v[158:161], v[206:209], v[72:75]
	v_mfma_f32_16x16x32_bf16 v[124:127], v[154:157], v[186:189], v[124:127]
	v_mfma_f32_16x16x32_bf16 v[120:123], v[162:165], v[186:189], v[120:123]
	v_mfma_f32_16x16x32_bf16 v[108:111], v[154:157], v[194:197], v[108:111]
	v_mfma_f32_16x16x32_bf16 v[104:107], v[162:165], v[194:197], v[104:107]
	v_mfma_f32_16x16x32_bf16 v[92:95], v[154:157], v[202:205], v[92:95]
	v_mfma_f32_16x16x32_bf16 v[88:91], v[162:165], v[202:205], v[88:91]
	v_mfma_f32_16x16x32_bf16 v[76:79], v[154:157], v[210:213], v[76:79]
	v_mfma_f32_16x16x32_bf16 v[72:75], v[162:165], v[210:213], v[72:75]
	v_mfma_f32_16x16x32_bf16 v[116:119], v[166:169], v[182:185], v[116:119]
	v_mfma_f32_16x16x32_bf16 v[112:115], v[174:177], v[182:185], v[112:115]
	v_mfma_f32_16x16x32_bf16 v[100:103], v[166:169], v[190:193], v[100:103]
	v_mfma_f32_16x16x32_bf16 v[96:99], v[174:177], v[190:193], v[96:99]
	v_mfma_f32_16x16x32_bf16 v[84:87], v[166:169], v[198:201], v[84:87]
	v_mfma_f32_16x16x32_bf16 v[80:83], v[174:177], v[198:201], v[80:83]
	v_mfma_f32_16x16x32_bf16 v[68:71], v[166:169], v[206:209], v[68:71]
	v_mfma_f32_16x16x32_bf16 v[64:67], v[174:177], v[206:209], v[64:67]
	v_mfma_f32_16x16x32_bf16 v[116:119], v[170:173], v[186:189], v[116:119]
	v_mfma_f32_16x16x32_bf16 v[112:115], v[178:181], v[186:189], v[112:115]
	v_mfma_f32_16x16x32_bf16 v[100:103], v[170:173], v[194:197], v[100:103]
	v_mfma_f32_16x16x32_bf16 v[96:99], v[178:181], v[194:197], v[96:99]
	v_mfma_f32_16x16x32_bf16 v[84:87], v[170:173], v[202:205], v[84:87]
	v_mfma_f32_16x16x32_bf16 v[80:83], v[178:181], v[202:205], v[80:83]
	v_mfma_f32_16x16x32_bf16 v[68:71], v[170:173], v[210:213], v[68:71]
	v_mfma_f32_16x16x32_bf16 v[64:67], v[178:181], v[210:213], v[64:67]
	s_setprio 0
	s_barrier
; #define PG8_STAGE(bufoff, gbase, voff) do { _Pragma("unroll") for (int _i = 0; _i < 2; ++_i) \
;         __builtin_amdgcn_global_load_lds((const unsigned*)((const char*)(gbase) + (voff)[_i]), (LAS unsigned*)(lds + (bufoff) + ldsw + _i * 8192), 16, 0, 0); } while (0)
; #define PG8_LDA(dst, b, h) do { _Pragma("unroll") for (int m = 0; m < 4; ++m) _Pragma("unroll") for (int k = 0; k < 2; ++k) dst[m][k] = *(const LAS bf16x8*)(lds + PG8_SA(b, h) + aoff + m * 2048 + k * 1024); } while (0)
; #define PG8_MMA(ai, bj, At, Bt) do { __builtin_amdgcn_s_setprio(1); _Pragma("unroll") for (int m = 0; m < 4; ++m) _Pragma("unroll") for (int n = 0; n < 2; ++n) _Pragma("unroll") for (int k = 0; k < 2; ++k) \
;         acc[ai][bj][m][n] = __builtin_amdgcn_mfma_f32_16x16x32_bf16(Bt[n][k], At[m][k], acc[ai][bj][m][n], 0, 0, 0); __builtin_amdgcn_s_setprio(0); } while (0)
; #define PG8_WAIT_V(n) asm volatile("s_waitcnt vmcnt(" #n ")" ::: "memory")
; #define PG8_WAIT_L(n) asm volatile("s_waitcnt lgkmcnt(" #n ")" ::: "memory")
; #define PG8_BAR __builtin_amdgcn_s_barrier()
; #define PG8_SCHED __builtin_amdgcn_sched_barrier(0)
; template <class Epi, bool ALIGN_EPI, int K, int LDA, int LDB>
; __device__ __forceinline__ void gemm_phase(LAS unsigned char* lds, const int wid, const Gemm g, const StaticOrder& S, const Epi& E) {
;     ...
;             PG8_LDA(At, 1, 1); PG8_STAGE(PG8_SB(1, 0), b3, voffB); PG8_STAGE(PG8_SB(1, 1), b3 + hB, voffB); PG8_STAGE(PG8_SA(1, 0), a3, voffA);
;             PG8_WAIT_V(8); PG8_WAIT_L(0); PG8_BAR; PG8_MMA(1, 0, At, B0); PG8_MMA(1, 1, At, B1); PG8_BAR; PG8_SCHED;
;         }
	s_add_i32 s38, s52, s3
	s_mov_b32 m0, s38
	ds_read_b128 v[182:185], v153 offset:49152
	ds_read_b128 v[186:189], v153 offset:50176
	ds_read_b128 v[190:193], v153 offset:51200
	ds_read_b128 v[194:197], v153 offset:52224
	ds_read_b128 v[198:201], v153 offset:53248
	ds_read_b128 v[202:205], v153 offset:54272
	ds_read_b128 v[206:209], v153 offset:55296
	ds_read_b128 v[210:213], v153 offset:56320
	global_load_lds_dwordx4 v130, s[98:99]
	s_add_i32 m0, s38, 0x2000
	s_add_u32 s36, s36, 0x40080
	s_addc_u32 s37, s37, 0
	s_add_i32 s38, s53, s3
	global_load_lds_dwordx4 v134, s[98:99]
	s_mov_b32 m0, s38
	s_nop 0
	global_load_lds_dwordx4 v130, s[36:37]
	s_add_i32 m0, s38, 0x2000
	s_nop 0
	global_load_lds_dwordx4 v134, s[36:37]
	s_mov_b32 m0, s55
	s_nop 0
	global_load_lds_dwordx4 v128, s[100:101]
	s_mov_b32 m0, s56
	s_nop 0
	global_load_lds_dwordx4 v132, s[100:101]
	s_waitcnt vmcnt(8)
	s_waitcnt lgkmcnt(0)
	s_barrier
	s_setprio 1
	s_waitcnt lgkmcnt(0)
	v_mfma_f32_16x16x32_bf16 v[60:63], v[144:147], v[182:185], v[60:63]
	v_mfma_f32_16x16x32_bf16 v[56:59], v[158:161], v[182:185], v[56:59]
	v_mfma_f32_16x16x32_bf16 v[44:47], v[144:147], v[190:193], v[44:47]
	v_mfma_f32_16x16x32_bf16 v[40:43], v[158:161], v[190:193], v[40:43]
	v_mfma_f32_16x16x32_bf16 v[28:31], v[144:147], v[198:201], v[28:31]
	v_mfma_f32_16x16x32_bf16 v[24:27], v[158:161], v[198:201], v[24:27]
	v_mfma_f32_16x16x32_bf16 v[12:15], v[144:147], v[206:209], v[12:15]
	v_mfma_f32_16x16x32_bf16 v[8:11], v[158:161], v[206:209], v[8:11]
	v_mfma_f32_16x16x32_bf16 v[60:63], v[154:157], v[186:189], v[60:63]
	v_mfma_f32_16x16x32_bf16 v[56:59], v[162:165], v[186:189], v[56:59]
	v_mfma_f32_16x16x32_bf16 v[44:47], v[154:157], v[194:197], v[44:47]
	v_mfma_f32_16x16x32_bf16 v[40:43], v[162:165], v[194:197], v[40:43]
	v_mfma_f32_16x16x32_bf16 v[28:31], v[154:157], v[202:205], v[28:31]
	v_mfma_f32_16x16x32_bf16 v[24:27], v[162:165], v[202:205], v[24:27]
	v_mfma_f32_16x16x32_bf16 v[12:15], v[154:157], v[210:213], v[12:15]
	v_mfma_f32_16x16x32_bf16 v[8:11], v[162:165], v[210:213], v[8:11]
	v_mfma_f32_16x16x32_bf16 v[52:55], v[166:169], v[182:185], v[52:55]
	v_mfma_f32_16x16x32_bf16 v[48:51], v[174:177], v[182:185], v[48:51]
	v_mfma_f32_16x16x32_bf16 v[36:39], v[166:169], v[190:193], v[36:39]
	v_mfma_f32_16x16x32_bf16 v[32:35], v[174:177], v[190:193], v[32:35]
	v_mfma_f32_16x16x32_bf16 v[20:23], v[166:169], v[198:201], v[20:23]
	v_mfma_f32_16x16x32_bf16 v[16:19], v[174:177], v[198:201], v[16:19]
	v_mfma_f32_16x16x32_bf16 v[4:7], v[166:169], v[206:209], v[4:7]
	v_mfma_f32_16x16x32_bf16 v[0:3], v[174:177], v[206:209], v[0:3]
	v_mfma_f32_16x16x32_bf16 v[52:55], v[170:173], v[186:189], v[52:55]
	v_mfma_f32_16x16x32_bf16 v[48:51], v[178:181], v[186:189], v[48:51]
	v_mfma_f32_16x16x32_bf16 v[36:39], v[170:173], v[194:197], v[36:39]
	v_mfma_f32_16x16x32_bf16 v[32:35], v[178:181], v[194:197], v[32:35]
	v_mfma_f32_16x16x32_bf16 v[20:23], v[170:173], v[202:205], v[20:23]
	v_mfma_f32_16x16x32_bf16 v[16:19], v[178:181], v[202:205], v[16:19]
	v_mfma_f32_16x16x32_bf16 v[4:7], v[170:173], v[210:213], v[4:7]
	v_mfma_f32_16x16x32_bf16 v[0:3], v[178:181], v[210:213], v[0:3]
	s_setprio 0
	s_barrier
	s_add_i32 s61, s61, 2
	s_add_u32 s34, s34, 0x100
	s_addc_u32 s35, s35, 0
	s_add_u32 s59, s59, 0x100
	s_addc_u32 s60, s60, 0

; #define PG8_STAGE(bufoff, gbase, voff) do { _Pragma("unroll") for (int _i = 0; _i < 2; ++_i) \
;         __builtin_amdgcn_global_load_lds((const unsigned*)((const char*)(gbase) + (voff)[_i]), (LAS unsigned*)(lds + (bufoff) + ldsw + _i * 8192), 16, 0, 0); } while (0)
; #define PG8_LDA(dst, b, h) do { _Pragma("unroll") for (int m = 0; m < 4; ++m) _Pragma("unroll") for (int k = 0; k < 2; ++k) dst[m][k] = *(const LAS bf16x8*)(lds + PG8_SA(b, h) + aoff + m * 2048 + k * 1024); } while (0)
; #define PG8_LDB(dst, b, h) do { _Pragma("unroll") for (int n = 0; n < 2; ++n) _Pragma("unroll") for (int k = 0; k < 2; ++k) dst[n][k] = *(const LAS bf16x8*)(lds + PG8_SB(b, h) + boff + n * 2048 + k * 1024); } while (0)
; #define PG8_MMA(ai, bj, At, Bt) do { __builtin_amdgcn_s_setprio(1); _Pragma("unroll") for (int m = 0; m < 4; ++m) _Pragma("unroll") for (int n = 0; n < 2; ++n) _Pragma("unroll") for (int k = 0; k < 2; ++k) \
;         acc[ai][bj][m][n] = __builtin_amdgcn_mfma_f32_16x16x32_bf16(Bt[n][k], At[m][k], acc[ai][bj][m][n], 0, 0, 0); __builtin_amdgcn_s_setprio(0); } while (0)
; template <class Epi, bool ALIGN_EPI, int K, int LDA, int LDB>
; __device__ __forceinline__ void gemm_phase(LAS unsigned char* lds, const int wid, const Gemm g, const StaticOrder& S, const Epi& E) {
;     ...
;         const bool has_next = S.next(ui + 1, nxt);
;         const char* nA = has_next ? (const char*)g.A + (size_t)nxt.pm * tA : cA; const char* nB = has_next ? (const char*)g.Bt + (size_t)nxt.pn * tB : cB;
;         for (int t = 0; t < nt; t += 2) {
;             const bool last = (t == nt - 2);
;             const char* a1 = cA + (size_t)(t + 1) * kstep;
;             const char* a2 = last ? nA : cA + (size_t)(t + 2) * kstep; const char* b2 = last ? nB : cB + (size_t)(t + 2) * kstep;
;             const char* a3 = a2 + kstep; const char* b3 = b2 + kstep;
;             PG8_LDB(B0, 0, 0); PG8_LDB(B1, 0, 1); PG8_SCHED; PG8_LDA(At, 0, 0); PG8_STAGE(PG8_SA(1, 1), a1 + hA, voffA);
;             PG8_WAIT_V(8); PG8_WAIT_L(0); PG8_BAR; PG8_MMA(0, 0, At, B0); PG8_MMA(0, 1, At, B1); PG8_BAR; PG8_SCHED;
;     ...
; #pragma unroll
;         for (int a = 0; a < 2; ++a)
; #pragma unroll
;             for (int b = 0; b < 2; ++b)
; #pragma unroll
;                 for (int m = 0; m < 4; ++m)
; #pragma unroll
;                     for (int n = 0; n < 2; ++n) acc[a][b][m][n] = (f32x4){0.f, 0.f, 0.f, 0.f};
.LBB0_1476:
	s_ashr_i32 s25, s24, 31
	s_lshl_b64 s[26:27], s[24:25], 19
	v_readlane_b32 s23, v254, 0
	s_add_u32 s26, s23, s26
	v_readlane_b32 s23, v254, 1
	s_addc_u32 s27, s23, s27
	s_and_b64 s[28:29], s[4:5], exec
	s_cselect_b32 s25, s27, s35
	s_cselect_b32 s42, s26, s34
	s_ashr_i32 s23, s22, 31
	s_lshl_b64 s[28:29], s[22:23], 19
	s_add_u32 s28, s1, s28
	s_addc_u32 s29, s3, s29
	s_and_b64 s[38:39], s[4:5], exec
	s_cselect_b32 s23, s29, s37
	s_cselect_b32 s66, s28, s36
	s_add_u32 s34, s34, 0x40080
	s_addc_u32 s35, s35, 0
	s_add_u32 s67, s36, 0x100
	s_addc_u32 s68, s37, 0
	s_mov_b32 s69, -2
	s_waitcnt vmcnt(0)
	ds_read_b128 v[128:131], v175
	ds_read_b128 v[132:135], v175 offset:1024
	ds_read_b128 v[136:139], v175 offset:2048
	ds_read_b128 v[140:143], v175 offset:3072
	ds_read_b128 v[144:147], v176
	ds_read_b128 v[164:167], v176 offset:1024
	ds_read_b128 v[168:171], v176 offset:2048
	ds_read_b128 v[178:181], v176 offset:3072
	s_add_u32 s36, s34, 0xfffc0080
	s_addc_u32 s37, s35, -1
	s_cmp_eq_u32 s69, 12
	s_cselect_b32 s39, s25, s37
	s_cselect_b32 s38, s42, s36
	s_cselect_b32 s37, s23, s68
	s_cselect_b32 s36, s66, s67
	s_add_i32 m0, s40, 0xc000
	ds_read_b128 v[182:185], v177
	ds_read_b128 v[186:189], v177 offset:1024
	ds_read_b128 v[190:193], v177 offset:2048
	ds_read_b128 v[194:197], v177 offset:3072
	ds_read_b128 v[198:201], v177 offset:4096
	ds_read_b128 v[202:205], v177 offset:5120
	ds_read_b128 v[206:209], v177 offset:6144
	ds_read_b128 v[210:213], v177 offset:7168
	global_load_lds_dwordx4 v156, s[34:35]
	s_add_i32 m0, s40, 0xe000
	s_nop 0
	global_load_lds_dwordx4 v158, s[34:35]
	s_waitcnt vmcnt(8)
	s_waitcnt lgkmcnt(0)
	s_barrier
	s_setprio 1
	s_waitcnt lgkmcnt(0)
	v_mfma_f32_16x16x32_bf16 v[124:127], v[128:131], v[182:185], 0
	v_mfma_f32_16x16x32_bf16 v[116:119], v[136:139], v[182:185], 0
	v_mfma_f32_16x16x32_bf16 v[120:123], v[128:131], v[190:193], 0
	v_mfma_f32_16x16x32_bf16 v[112:115], v[136:139], v[190:193], 0
	v_mfma_f32_16x16x32_bf16 v[92:95], v[128:131], v[198:201], 0
	v_mfma_f32_16x16x32_bf16 v[88:91], v[136:139], v[198:201], 0
	v_mfma_f32_16x16x32_bf16 v[76:79], v[128:131], v[206:209], 0
	v_mfma_f32_16x16x32_bf16 v[72:75], v[136:139], v[206:209], 0
	v_mfma_f32_16x16x32_bf16 v[124:127], v[132:135], v[186:189], v[124:127]
	v_mfma_f32_16x16x32_bf16 v[116:119], v[140:143], v[186:189], v[116:119]
	v_mfma_f32_16x16x32_bf16 v[120:123], v[132:135], v[194:197], v[120:123]
	v_mfma_f32_16x16x32_bf16 v[112:115], v[140:143], v[194:197], v[112:115]
	v_mfma_f32_16x16x32_bf16 v[92:95], v[132:135], v[202:205], v[92:95]
	v_mfma_f32_16x16x32_bf16 v[88:91], v[140:143], v[202:205], v[88:91]
	v_mfma_f32_16x16x32_bf16 v[76:79], v[132:135], v[210:213], v[76:79]
	v_mfma_f32_16x16x32_bf16 v[72:75], v[140:143], v[210:213], v[72:75]
	v_mfma_f32_16x16x32_bf16 v[108:111], v[144:147], v[182:185], 0
	v_mfma_f32_16x16x32_bf16 v[104:107], v[168:171], v[182:185], 0
	v_mfma_f32_16x16x32_bf16 v[100:103], v[144:147], v[190:193], 0
	v_mfma_f32_16x16x32_bf16 v[96:99], v[168:171], v[190:193], 0
	v_mfma_f32_16x16x32_bf16 v[84:87], v[144:147], v[198:201], 0
	v_mfma_f32_16x16x32_bf16 v[80:83], v[168:171], v[198:201], 0
	v_mfma_f32_16x16x32_bf16 v[68:71], v[144:147], v[206:209], 0
	v_mfma_f32_16x16x32_bf16 v[64:67], v[168:171], v[206:209], 0
	v_mfma_f32_16x16x32_bf16 v[108:111], v[164:167], v[186:189], v[108:111]
	v_mfma_f32_16x16x32_bf16 v[104:107], v[178:181], v[186:189], v[104:107]
	v_mfma_f32_16x16x32_bf16 v[100:103], v[164:167], v[194:197], v[100:103]
	v_mfma_f32_16x16x32_bf16 v[96:99], v[178:181], v[194:197], v[96:99]
	v_mfma_f32_16x16x32_bf16 v[84:87], v[164:167], v[202:205], v[84:87]
	v_mfma_f32_16x16x32_bf16 v[80:83], v[178:181], v[202:205], v[80:83]
	v_mfma_f32_16x16x32_bf16 v[68:71], v[164:167], v[210:213], v[68:71]
	v_mfma_f32_16x16x32_bf16 v[64:67], v[178:181], v[210:213], v[64:67]
	s_setprio 0
	s_barrier
	s_add_u32 s98, s36, s12
	s_addc_u32 s99, s37, s13
	s_add_u32 s100, s38, s12
	s_addc_u32 s101, s39, s13
	s_add_i32 s52, s58, s33
	s_mov_b32 m0, s52
	ds_read_b128 v[182:185], v177 offset:16384
	ds_read_b128 v[186:189], v177 offset:17408
	ds_read_b128 v[190:193], v177 offset:18432
	ds_read_b128 v[194:197], v177 offset:19456
	ds_read_b128 v[198:201], v177 offset:20480
	ds_read_b128 v[202:205], v177 offset:21504
	ds_read_b128 v[206:209], v177 offset:22528
	ds_read_b128 v[210:213], v177 offset:23552
	global_load_lds_dwordx4 v150, s[36:37]
	s_add_i32 m0, s52, 0x2000
	s_add_u32 s70, s36, 0x40000
	s_addc_u32 s71, s37, 0
	s_add_i32 s52, s59, s33
	global_load_lds_dwordx4 v154, s[36:37]
	s_mov_b32 m0, s52
	s_nop 0
	global_load_lds_dwordx4 v150, s[70:71]
	s_add_i32 m0, s52, 0x2000
	s_nop 0
	global_load_lds_dwordx4 v154, s[70:71]
	s_mov_b32 m0, s40
	s_nop 0
	global_load_lds_dwordx4 v148, s[38:39]
	s_mov_b32 m0, s41
	s_nop 0
	global_load_lds_dwordx4 v152, s[38:39]
	s_waitcnt vmcnt(8)
	s_waitcnt lgkmcnt(0)
	s_barrier
; #define PG8_STAGE(bufoff, gbase, voff) do { _Pragma("unroll") for (int _i = 0; _i < 2; ++_i) \
;         __builtin_amdgcn_global_load_lds((const unsigned*)((const char*)(gbase) + (voff)[_i]), (LAS unsigned*)(lds + (bufoff) + ldsw + _i * 8192), 16, 0, 0); } while (0)
; #define PG8_LDA(dst, b, h) do { _Pragma("unroll") for (int m = 0; m < 4; ++m) _Pragma("unroll") for (int k = 0; k < 2; ++k) dst[m][k] = *(const LAS bf16x8*)(lds + PG8_SA(b, h) + aoff + m * 2048 + k * 1024); } while (0)
; #define PG8_LDB(dst, b, h) do { _Pragma("unroll") for (int n = 0; n < 2; ++n) _Pragma("unroll") for (int k = 0; k < 2; ++k) dst[n][k] = *(const LAS bf16x8*)(lds + PG8_SB(b, h) + boff + n * 2048 + k * 1024); } while (0)
; #define PG8_MMA(ai, bj, At, Bt) do { __builtin_amdgcn_s_setprio(1); _Pragma("unroll") for (int m = 0; m < 4; ++m) _Pragma("unroll") for (int n = 0; n < 2; ++n) _Pragma("unroll") for (int k = 0; k < 2; ++k) \
;         acc[ai][bj][m][n] = __builtin_amdgcn_mfma_f32_16x16x32_bf16(Bt[n][k], At[m][k], acc[ai][bj][m][n], 0, 0, 0); __builtin_amdgcn_s_setprio(0); } while (0)
; #define PG8_WAIT_V(n) asm volatile("s_waitcnt vmcnt(" #n ")" ::: "memory")
; #define PG8_WAIT_L(n) asm volatile("s_waitcnt lgkmcnt(" #n ")" ::: "memory")
; #define PG8_BAR __builtin_amdgcn_s_barrier()
; #define PG8_SCHED __builtin_amdgcn_sched_barrier(0)
; template <class Epi, bool ALIGN_EPI, int K, int LDA, int LDB>
; __device__ __forceinline__ void gemm_phase(LAS unsigned char* lds, const int wid, const Gemm g, const StaticOrder& S, const Epi& E) {
;     ...
;             PG8_WAIT_V(8); PG8_WAIT_L(0); PG8_BAR; PG8_MMA(1, 0, At, B0); PG8_MMA(1, 1, At, B1); PG8_BAR; PG8_SCHED;
;             PG8_LDB(B0, 1, 0); PG8_LDB(B1, 1, 1); PG8_SCHED; PG8_LDA(At, 1, 0); PG8_STAGE(PG8_SA(0, 1), a2 + hA, voffA);
;             PG8_WAIT_V(8); PG8_WAIT_L(0); PG8_BAR; PG8_MMA(0, 0, At, B0); PG8_MMA(0, 1, At, B1); PG8_BAR; PG8_SCHED;
	s_setprio 1
	s_waitcnt lgkmcnt(0)
	v_mfma_f32_16x16x32_bf16 v[60:63], v[128:131], v[182:185], 0
	v_mfma_f32_16x16x32_bf16 v[56:59], v[136:139], v[182:185], 0
	v_mfma_f32_16x16x32_bf16 v[44:47], v[128:131], v[190:193], 0
	v_mfma_f32_16x16x32_bf16 v[40:43], v[136:139], v[190:193], 0
	v_mfma_f32_16x16x32_bf16 v[36:39], v[128:131], v[198:201], 0
	v_mfma_f32_16x16x32_bf16 v[32:35], v[136:139], v[198:201], 0
	v_mfma_f32_16x16x32_bf16 v[20:23], v[128:131], v[206:209], 0
	v_mfma_f32_16x16x32_bf16 v[16:19], v[136:139], v[206:209], 0
	v_mfma_f32_16x16x32_bf16 v[60:63], v[132:135], v[186:189], v[60:63]
	v_mfma_f32_16x16x32_bf16 v[56:59], v[140:143], v[186:189], v[56:59]
	v_mfma_f32_16x16x32_bf16 v[44:47], v[132:135], v[194:197], v[44:47]
	v_mfma_f32_16x16x32_bf16 v[40:43], v[140:143], v[194:197], v[40:43]
	v_mfma_f32_16x16x32_bf16 v[36:39], v[132:135], v[202:205], v[36:39]
	v_mfma_f32_16x16x32_bf16 v[32:35], v[140:143], v[202:205], v[32:35]
	v_mfma_f32_16x16x32_bf16 v[20:23], v[132:135], v[210:213], v[20:23]
	v_mfma_f32_16x16x32_bf16 v[16:19], v[140:143], v[210:213], v[16:19]
	v_mfma_f32_16x16x32_bf16 v[52:55], v[144:147], v[182:185], 0
	v_mfma_f32_16x16x32_bf16 v[48:51], v[168:171], v[182:185], 0
	v_mfma_f32_16x16x32_bf16 v[28:31], v[144:147], v[190:193], 0
	v_mfma_f32_16x16x32_bf16 v[24:27], v[168:171], v[190:193], 0
	v_mfma_f32_16x16x32_bf16 v[12:15], v[144:147], v[198:201], 0
	v_mfma_f32_16x16x32_bf16 v[8:11], v[168:171], v[198:201], 0
	v_mfma_f32_16x16x32_bf16 v[4:7], v[144:147], v[206:209], 0
	v_mfma_f32_16x16x32_bf16 v[0:3], v[168:171], v[206:209], 0
	v_mfma_f32_16x16x32_bf16 v[52:55], v[164:167], v[186:189], v[52:55]
	v_mfma_f32_16x16x32_bf16 v[48:51], v[178:181], v[186:189], v[48:51]
	v_mfma_f32_16x16x32_bf16 v[28:31], v[164:167], v[194:197], v[28:31]
	v_mfma_f32_16x16x32_bf16 v[24:27], v[178:181], v[194:197], v[24:27]
	v_mfma_f32_16x16x32_bf16 v[12:15], v[164:167], v[202:205], v[12:15]
	v_mfma_f32_16x16x32_bf16 v[8:11], v[178:181], v[202:205], v[8:11]
	v_mfma_f32_16x16x32_bf16 v[4:7], v[164:167], v[210:213], v[4:7]
	v_mfma_f32_16x16x32_bf16 v[0:3], v[178:181], v[210:213], v[0:3]
	s_setprio 0
	s_barrier
	s_add_i32 s52, 0, 0x18000
	s_add_i32 s53, 0, 0x1c000
	v_add_u32_e32 v140, s52, v174
	v_add_u32_e32 v178, s53, v174
	ds_read_b128 v[128:131], v140
	ds_read_b128 v[132:135], v140 offset:1024
	ds_read_b128 v[136:139], v140 offset:2048
	ds_read_b128 v[140:143], v140 offset:3072
	ds_read_b128 v[144:147], v178
	ds_read_b128 v[164:167], v178 offset:1024
	ds_read_b128 v[168:171], v178 offset:2048
	ds_read_b128 v[178:181], v178 offset:3072
	s_add_u32 s38, s38, 0x40000
	s_addc_u32 s39, s39, 0
	s_mov_b32 m0, s43
	ds_read_b128 v[182:185], v177 offset:32768
	ds_read_b128 v[186:189], v177 offset:33792
	ds_read_b128 v[190:193], v177 offset:34816
	ds_read_b128 v[194:197], v177 offset:35840
	ds_read_b128 v[198:201], v177 offset:36864
	ds_read_b128 v[202:205], v177 offset:37888
	ds_read_b128 v[206:209], v177 offset:38912
	ds_read_b128 v[210:213], v177 offset:39936
	global_load_lds_dwordx4 v148, s[38:39]
	s_mov_b32 m0, s48
	s_nop 0
	global_load_lds_dwordx4 v152, s[38:39]
	s_waitcnt vmcnt(8)
	s_waitcnt lgkmcnt(0)
	s_barrier
	s_setprio 1
	s_waitcnt lgkmcnt(0)
	v_mfma_f32_16x16x32_bf16 v[124:127], v[128:131], v[182:185], v[124:127]
	v_mfma_f32_16x16x32_bf16 v[116:119], v[136:139], v[182:185], v[116:119]
	v_mfma_f32_16x16x32_bf16 v[120:123], v[128:131], v[190:193], v[120:123]
	v_mfma_f32_16x16x32_bf16 v[112:115], v[136:139], v[190:193], v[112:115]
	v_mfma_f32_16x16x32_bf16 v[92:95], v[128:131], v[198:201], v[92:95]
	v_mfma_f32_16x16x32_bf16 v[88:91], v[136:139], v[198:201], v[88:91]
	v_mfma_f32_16x16x32_bf16 v[76:79], v[128:131], v[206:209], v[76:79]
	v_mfma_f32_16x16x32_bf16 v[72:75], v[136:139], v[206:209], v[72:75]
	v_mfma_f32_16x16x32_bf16 v[124:127], v[132:135], v[186:189], v[124:127]
	v_mfma_f32_16x16x32_bf16 v[116:119], v[140:143], v[186:189], v[116:119]
	v_mfma_f32_16x16x32_bf16 v[120:123], v[132:135], v[194:197], v[120:123]
	v_mfma_f32_16x16x32_bf16 v[112:115], v[140:143], v[194:197], v[112:115]
	v_mfma_f32_16x16x32_bf16 v[92:95], v[132:135], v[202:205], v[92:95]
	v_mfma_f32_16x16x32_bf16 v[88:91], v[140:143], v[202:205], v[88:91]
	v_mfma_f32_16x16x32_bf16 v[76:79], v[132:135], v[210:213], v[76:79]
	v_mfma_f32_16x16x32_bf16 v[72:75], v[140:143], v[210:213], v[72:75]
	v_mfma_f32_16x16x32_bf16 v[108:111], v[144:147], v[182:185], v[108:111]
	v_mfma_f32_16x16x32_bf16 v[104:107], v[168:171], v[182:185], v[104:107]
	v_mfma_f32_16x16x32_bf16 v[100:103], v[144:147], v[190:193], v[100:103]
	v_mfma_f32_16x16x32_bf16 v[96:99], v[168:171], v[190:193], v[96:99]
	v_mfma_f32_16x16x32_bf16 v[84:87], v[144:147], v[198:201], v[84:87]
	v_mfma_f32_16x16x32_bf16 v[80:83], v[168:171], v[198:201], v[80:83]
	v_mfma_f32_16x16x32_bf16 v[68:71], v[144:147], v[206:209], v[68:71]
	v_mfma_f32_16x16x32_bf16 v[64:67], v[168:171], v[206:209], v[64:67]
	v_mfma_f32_16x16x32_bf16 v[108:111], v[164:167], v[186:189], v[108:111]
	v_mfma_f32_16x16x32_bf16 v[104:107], v[178:181], v[186:189], v[104:107]
	v_mfma_f32_16x16x32_bf16 v[100:103], v[164:167], v[194:197], v[100:103]
	v_mfma_f32_16x16x32_bf16 v[96:99], v[178:181], v[194:197], v[96:99]
	v_mfma_f32_16x16x32_bf16 v[84:87], v[164:167], v[202:205], v[84:87]
	v_mfma_f32_16x16x32_bf16 v[80:83], v[178:181], v[202:205], v[80:83]
	v_mfma_f32_16x16x32_bf16 v[68:71], v[164:167], v[210:213], v[68:71]
	v_mfma_f32_16x16x32_bf16 v[64:67], v[178:181], v[210:213], v[64:67]
	s_setprio 0
	s_barrier
; #define PG8_STAGE(bufoff, gbase, voff) do { _Pragma("unroll") for (int _i = 0; _i < 2; ++_i) \
;         __builtin_amdgcn_global_load_lds((const unsigned*)((const char*)(gbase) + (voff)[_i]), (LAS unsigned*)(lds + (bufoff) + ldsw + _i * 8192), 16, 0, 0); } while (0)
; #define PG8_LDA(dst, b, h) do { _Pragma("unroll") for (int m = 0; m < 4; ++m) _Pragma("unroll") for (int k = 0; k < 2; ++k) dst[m][k] = *(const LAS bf16x8*)(lds + PG8_SA(b, h) + aoff + m * 2048 + k * 1024); } while (0)
; #define PG8_MMA(ai, bj, At, Bt) do { __builtin_amdgcn_s_setprio(1); _Pragma("unroll") for (int m = 0; m < 4; ++m) _Pragma("unroll") for (int n = 0; n < 2; ++n) _Pragma("unroll") for (int k = 0; k < 2; ++k) \
;         acc[ai][bj][m][n] = __builtin_amdgcn_mfma_f32_16x16x32_bf16(Bt[n][k], At[m][k], acc[ai][bj][m][n], 0, 0, 0); __builtin_amdgcn_s_setprio(0); } while (0)
; #define PG8_WAIT_V(n) asm volatile("s_waitcnt vmcnt(" #n ")" ::: "memory")
; #define PG8_WAIT_L(n) asm volatile("s_waitcnt lgkmcnt(" #n ")" ::: "memory")
; #define PG8_BAR __builtin_amdgcn_s_barrier()
; #define PG8_SCHED __builtin_amdgcn_sched_barrier(0)
; template <class Epi, bool ALIGN_EPI, int K, int LDA, int LDB>
; __device__ __forceinline__ void gemm_phase(LAS unsigned char* lds, const int wid, const Gemm g, const StaticOrder& S, const Epi& E) {
;     ...
;             PG8_LDA(At, 1, 1); PG8_STAGE(PG8_SB(1, 0), b3, voffB); PG8_STAGE(PG8_SB(1, 1), b3 + hB, voffB); PG8_STAGE(PG8_SA(1, 0), a3, voffA);
;             PG8_WAIT_V(8); PG8_WAIT_L(0); PG8_BAR; PG8_MMA(1, 0, At, B0); PG8_MMA(1, 1, At, B1); PG8_BAR; PG8_SCHED;
;         }
	s_add_i32 s38, s52, s33
	s_mov_b32 m0, s38
	ds_read_b128 v[182:185], v177 offset:49152
	ds_read_b128 v[186:189], v177 offset:50176
	ds_read_b128 v[190:193], v177 offset:51200
	ds_read_b128 v[194:197], v177 offset:52224
	ds_read_b128 v[198:201], v177 offset:53248
	ds_read_b128 v[202:205], v177 offset:54272
	ds_read_b128 v[206:209], v177 offset:55296
	ds_read_b128 v[210:213], v177 offset:56320
	global_load_lds_dwordx4 v150, s[98:99]
	s_add_i32 m0, s38, 0x2000
	s_add_u32 s36, s36, 0x40080
	s_addc_u32 s37, s37, 0
	s_add_i32 s38, s53, s33
	global_load_lds_dwordx4 v154, s[98:99]
	s_mov_b32 m0, s38
	s_nop 0
	global_load_lds_dwordx4 v150, s[36:37]
	s_add_i32 m0, s38, 0x2000
	s_nop 0
	global_load_lds_dwordx4 v154, s[36:37]
	s_mov_b32 m0, s55
	s_nop 0
	global_load_lds_dwordx4 v148, s[100:101]
	s_mov_b32 m0, s56
	s_nop 0
	global_load_lds_dwordx4 v152, s[100:101]
	s_waitcnt vmcnt(8)
	s_waitcnt lgkmcnt(0)
	s_barrier
	s_setprio 1
	s_waitcnt lgkmcnt(0)
	v_mfma_f32_16x16x32_bf16 v[60:63], v[128:131], v[182:185], v[60:63]
	v_mfma_f32_16x16x32_bf16 v[56:59], v[136:139], v[182:185], v[56:59]
	v_mfma_f32_16x16x32_bf16 v[44:47], v[128:131], v[190:193], v[44:47]
	v_mfma_f32_16x16x32_bf16 v[40:43], v[136:139], v[190:193], v[40:43]
	v_mfma_f32_16x16x32_bf16 v[36:39], v[128:131], v[198:201], v[36:39]
	v_mfma_f32_16x16x32_bf16 v[32:35], v[136:139], v[198:201], v[32:35]
	v_mfma_f32_16x16x32_bf16 v[20:23], v[128:131], v[206:209], v[20:23]
	v_mfma_f32_16x16x32_bf16 v[16:19], v[136:139], v[206:209], v[16:19]
	v_mfma_f32_16x16x32_bf16 v[60:63], v[132:135], v[186:189], v[60:63]
	v_mfma_f32_16x16x32_bf16 v[56:59], v[140:143], v[186:189], v[56:59]
	v_mfma_f32_16x16x32_bf16 v[44:47], v[132:135], v[194:197], v[44:47]
	v_mfma_f32_16x16x32_bf16 v[40:43], v[140:143], v[194:197], v[40:43]
	v_mfma_f32_16x16x32_bf16 v[36:39], v[132:135], v[202:205], v[36:39]
	v_mfma_f32_16x16x32_bf16 v[32:35], v[140:143], v[202:205], v[32:35]
	v_mfma_f32_16x16x32_bf16 v[20:23], v[132:135], v[210:213], v[20:23]
	v_mfma_f32_16x16x32_bf16 v[16:19], v[140:143], v[210:213], v[16:19]
	v_mfma_f32_16x16x32_bf16 v[52:55], v[144:147], v[182:185], v[52:55]
	v_mfma_f32_16x16x32_bf16 v[48:51], v[168:171], v[182:185], v[48:51]
	v_mfma_f32_16x16x32_bf16 v[28:31], v[144:147], v[190:193], v[28:31]
	v_mfma_f32_16x16x32_bf16 v[24:27], v[168:171], v[190:193], v[24:27]
	v_mfma_f32_16x16x32_bf16 v[12:15], v[144:147], v[198:201], v[12:15]
	v_mfma_f32_16x16x32_bf16 v[8:11], v[168:171], v[198:201], v[8:11]
	v_mfma_f32_16x16x32_bf16 v[4:7], v[144:147], v[206:209], v[4:7]
	v_mfma_f32_16x16x32_bf16 v[0:3], v[168:171], v[206:209], v[0:3]
	v_mfma_f32_16x16x32_bf16 v[52:55], v[164:167], v[186:189], v[52:55]
	v_mfma_f32_16x16x32_bf16 v[48:51], v[178:181], v[186:189], v[48:51]
	v_mfma_f32_16x16x32_bf16 v[28:31], v[164:167], v[194:197], v[28:31]
	v_mfma_f32_16x16x32_bf16 v[24:27], v[178:181], v[194:197], v[24:27]
	v_mfma_f32_16x16x32_bf16 v[12:15], v[164:167], v[202:205], v[12:15]
	v_mfma_f32_16x16x32_bf16 v[8:11], v[178:181], v[202:205], v[8:11]
	v_mfma_f32_16x16x32_bf16 v[4:7], v[164:167], v[210:213], v[4:7]
	v_mfma_f32_16x16x32_bf16 v[0:3], v[178:181], v[210:213], v[0:3]
	s_setprio 0
	s_barrier
	s_add_i32 s69, s69, 2
	s_add_u32 s34, s34, 0x100
	s_addc_u32 s35, s35, 0
	s_add_u32 s67, s67, 0x100
	s_addc_u32 s68, s68, 0

; #define PG8_STAGE(bufoff, gbase, voff) do { _Pragma("unroll") for (int _i = 0; _i < 2; ++_i) \
;         __builtin_amdgcn_global_load_lds((const unsigned*)((const char*)(gbase) + (voff)[_i]), (LAS unsigned*)(lds + (bufoff) + ldsw + _i * 8192), 16, 0, 0); } while (0)
; #define PG8_LDA(dst, b, h) do { _Pragma("unroll") for (int m = 0; m < 4; ++m) _Pragma("unroll") for (int k = 0; k < 2; ++k) dst[m][k] = *(const LAS bf16x8*)(lds + PG8_SA(b, h) + aoff + m * 2048 + k * 1024); } while (0)
; #define PG8_LDB(dst, b, h) do { _Pragma("unroll") for (int n = 0; n < 2; ++n) _Pragma("unroll") for (int k = 0; k < 2; ++k) dst[n][k] = *(const LAS bf16x8*)(lds + PG8_SB(b, h) + boff + n * 2048 + k * 1024); } while (0)
; #define PG8_WAIT_V(n) asm volatile("s_waitcnt vmcnt(" #n ")" ::: "memory")
; #define PG8_BAR __builtin_amdgcn_s_barrier()
; template <class Epi, bool ALIGN_EPI, int K, int LDA, int LDB>
; __device__ __forceinline__ void gemm_phase(LAS unsigned char* lds, const int wid, const Gemm g, const StaticOrder& S, const Epi& E) {
;     ...
;         const bool has_next = S.next(ui + 1, nxt);
;         const char* nA = has_next ? (const char*)g.A + (size_t)nxt.pm * tA : cA; const char* nB = has_next ? (const char*)g.Bt + (size_t)nxt.pn * tB : cB;
;         for (int t = 0; t < nt; t += 2) {
;             const bool last = (t == nt - 2);
;             const char* a1 = cA + (size_t)(t + 1) * kstep;
;             const char* a2 = last ? nA : cA + (size_t)(t + 2) * kstep; const char* b2 = last ? nB : cB + (size_t)(t + 2) * kstep;
;             const char* a3 = a2 + kstep; const char* b3 = b2 + kstep;
;             PG8_LDB(B0, 0, 0); PG8_LDB(B1, 0, 1); PG8_SCHED; PG8_LDA(At, 0, 0); PG8_STAGE(PG8_SA(1, 1), a1 + hA, voffA);
;             PG8_WAIT_V(8); PG8_WAIT_L(0); PG8_BAR; PG8_MMA(0, 0, At, B0); PG8_MMA(0, 1, At, B1); PG8_BAR; PG8_SCHED;
;             PG8_LDA(At, 0, 1); PG8_STAGE(PG8_SB(0, 0), b2, voffB); PG8_STAGE(PG8_SB(0, 1), b2 + hB, voffB); PG8_STAGE(PG8_SA(0, 0), a2, voffA);
;             PG8_WAIT_V(8); PG8_WAIT_L(0); PG8_BAR; PG8_MMA(1, 0, At, B0); PG8_MMA(1, 1, At, B1); PG8_BAR; PG8_SCHED;
;     ...
; #pragma unroll
;         for (int a = 0; a < 2; ++a)
; #pragma unroll
;             for (int b = 0; b < 2; ++b)
; #pragma unroll
;                 for (int m = 0; m < 4; ++m)
; #pragma unroll
;                     for (int n = 0; n < 2; ++n) acc[a][b][m][n] = (f32x4){0.f, 0.f, 0.f, 0.f};
.LBB0_1696:
	s_add_u32 s61, s28, 0x100
	s_addc_u32 s62, s29, 0
	s_mov_b32 s63, -2
	s_waitcnt vmcnt(0)
	ds_read_b128 v[120:123], v167
	ds_read_b128 v[124:127], v167 offset:1024
	ds_read_b128 v[128:131], v167 offset:2048
	ds_read_b128 v[132:135], v167 offset:3072
	ds_read_b128 v[160:163], v168
	ds_read_b128 v[170:173], v168 offset:1024
	ds_read_b128 v[174:177], v168 offset:2048
	ds_read_b128 v[178:181], v168 offset:3072
	s_add_u32 s28, s26, 0x100
	s_addc_u32 s29, s27, 0
	s_cmp_eq_u32 s63, 40
	s_cselect_b32 s35, s7, s29
	s_cselect_b32 s34, s6, s28
	s_cselect_b32 s31, s25, s62
	s_cselect_b32 s30, s24, s61
	s_add_i32 m0, s36, 0xc000
	ds_read_b128 v[182:185], v169
	ds_read_b128 v[186:189], v169 offset:1024
	ds_read_b128 v[190:193], v169 offset:2048
	ds_read_b128 v[194:197], v169 offset:3072
	ds_read_b128 v[198:201], v169 offset:4096
	ds_read_b128 v[202:205], v169 offset:5120
	ds_read_b128 v[206:209], v169 offset:6144
	ds_read_b128 v[210:213], v169 offset:7168
	global_load_lds_dwordx4 v152, s[26:27]
	s_add_i32 m0, s36, 0xe000
	s_nop 0
	global_load_lds_dwordx4 v154, s[26:27]
	s_waitcnt vmcnt(8)
	s_waitcnt lgkmcnt(0)
	s_barrier
	s_setprio 1
	s_waitcnt lgkmcnt(0)
	v_mfma_f32_16x16x32_bf16 v[140:143], v[120:123], v[182:185], 0
	v_mfma_f32_16x16x32_bf16 v[136:139], v[128:131], v[182:185], 0
	v_mfma_f32_16x16x32_bf16 v[108:111], v[120:123], v[190:193], 0
	v_mfma_f32_16x16x32_bf16 v[104:107], v[128:131], v[190:193], 0
	v_mfma_f32_16x16x32_bf16 v[92:95], v[120:123], v[198:201], 0
	v_mfma_f32_16x16x32_bf16 v[88:91], v[128:131], v[198:201], 0
	v_mfma_f32_16x16x32_bf16 v[76:79], v[120:123], v[206:209], 0
	v_mfma_f32_16x16x32_bf16 v[72:75], v[128:131], v[206:209], 0
	v_mfma_f32_16x16x32_bf16 v[140:143], v[124:127], v[186:189], v[140:143]
	v_mfma_f32_16x16x32_bf16 v[136:139], v[132:135], v[186:189], v[136:139]
	v_mfma_f32_16x16x32_bf16 v[108:111], v[124:127], v[194:197], v[108:111]
	v_mfma_f32_16x16x32_bf16 v[104:107], v[132:135], v[194:197], v[104:107]
	v_mfma_f32_16x16x32_bf16 v[92:95], v[124:127], v[202:205], v[92:95]
	v_mfma_f32_16x16x32_bf16 v[88:91], v[132:135], v[202:205], v[88:91]
	v_mfma_f32_16x16x32_bf16 v[76:79], v[124:127], v[210:213], v[76:79]
	v_mfma_f32_16x16x32_bf16 v[72:75], v[132:135], v[210:213], v[72:75]
	v_mfma_f32_16x16x32_bf16 v[116:119], v[160:163], v[182:185], 0
	v_mfma_f32_16x16x32_bf16 v[112:115], v[174:177], v[182:185], 0
	v_mfma_f32_16x16x32_bf16 v[100:103], v[160:163], v[190:193], 0
	v_mfma_f32_16x16x32_bf16 v[96:99], v[174:177], v[190:193], 0
	v_mfma_f32_16x16x32_bf16 v[84:87], v[160:163], v[198:201], 0
	v_mfma_f32_16x16x32_bf16 v[80:83], v[174:177], v[198:201], 0
	v_mfma_f32_16x16x32_bf16 v[68:71], v[160:163], v[206:209], 0
	v_mfma_f32_16x16x32_bf16 v[64:67], v[174:177], v[206:209], 0
	v_mfma_f32_16x16x32_bf16 v[116:119], v[170:173], v[186:189], v[116:119]
	v_mfma_f32_16x16x32_bf16 v[112:115], v[178:181], v[186:189], v[112:115]
	v_mfma_f32_16x16x32_bf16 v[100:103], v[170:173], v[194:197], v[100:103]
	v_mfma_f32_16x16x32_bf16 v[96:99], v[178:181], v[194:197], v[96:99]
	v_mfma_f32_16x16x32_bf16 v[84:87], v[170:173], v[202:205], v[84:87]
	v_mfma_f32_16x16x32_bf16 v[80:83], v[178:181], v[202:205], v[80:83]
	v_mfma_f32_16x16x32_bf16 v[68:71], v[170:173], v[210:213], v[68:71]
	v_mfma_f32_16x16x32_bf16 v[64:67], v[178:181], v[210:213], v[64:67]
	s_setprio 0
	s_barrier
	s_add_u32 s98, s30, s12
	s_addc_u32 s99, s31, s13
	s_add_u32 s100, s34, s12
	s_addc_u32 s101, s35, s13
	s_add_i32 s26, s54, s33
	s_mov_b32 m0, s26
	ds_read_b128 v[182:185], v169 offset:16384
	ds_read_b128 v[186:189], v169 offset:17408
	ds_read_b128 v[190:193], v169 offset:18432
	ds_read_b128 v[194:197], v169 offset:19456
	ds_read_b128 v[198:201], v169 offset:20480
	ds_read_b128 v[202:205], v169 offset:21504
	ds_read_b128 v[206:209], v169 offset:22528
	ds_read_b128 v[210:213], v169 offset:23552
	global_load_lds_dwordx4 v146, s[30:31]
	s_add_i32 m0, s26, 0x2000
	s_add_u32 s26, s30, 0xb0000
	s_addc_u32 s27, s31, 0
	s_add_i32 s52, s55, s33
	global_load_lds_dwordx4 v150, s[30:31]
	s_mov_b32 m0, s52
	s_nop 0
	global_load_lds_dwordx4 v146, s[26:27]
	s_add_i32 m0, s52, 0x2000
	s_nop 0
	global_load_lds_dwordx4 v150, s[26:27]
	s_mov_b32 m0, s36
	s_nop 0
	global_load_lds_dwordx4 v144, s[34:35]
	s_mov_b32 m0, s37
	s_nop 0
	global_load_lds_dwordx4 v148, s[34:35]
	s_waitcnt vmcnt(8)
	s_waitcnt lgkmcnt(0)
	s_barrier
	s_setprio 1
	s_waitcnt lgkmcnt(0)
	v_mfma_f32_16x16x32_bf16 v[60:63], v[120:123], v[182:185], 0
	v_mfma_f32_16x16x32_bf16 v[56:59], v[128:131], v[182:185], 0
	v_mfma_f32_16x16x32_bf16 v[44:47], v[120:123], v[190:193], 0
	v_mfma_f32_16x16x32_bf16 v[40:43], v[128:131], v[190:193], 0
	v_mfma_f32_16x16x32_bf16 v[28:31], v[120:123], v[198:201], 0
	v_mfma_f32_16x16x32_bf16 v[24:27], v[128:131], v[198:201], 0
	v_mfma_f32_16x16x32_bf16 v[12:15], v[120:123], v[206:209], 0
	v_mfma_f32_16x16x32_bf16 v[8:11], v[128:131], v[206:209], 0
	v_mfma_f32_16x16x32_bf16 v[60:63], v[124:127], v[186:189], v[60:63]
	v_mfma_f32_16x16x32_bf16 v[56:59], v[132:135], v[186:189], v[56:59]
	v_mfma_f32_16x16x32_bf16 v[44:47], v[124:127], v[194:197], v[44:47]
	v_mfma_f32_16x16x32_bf16 v[40:43], v[132:135], v[194:197], v[40:43]
	v_mfma_f32_16x16x32_bf16 v[28:31], v[124:127], v[202:205], v[28:31]
	v_mfma_f32_16x16x32_bf16 v[24:27], v[132:135], v[202:205], v[24:27]
	v_mfma_f32_16x16x32_bf16 v[12:15], v[124:127], v[210:213], v[12:15]
	v_mfma_f32_16x16x32_bf16 v[8:11], v[132:135], v[210:213], v[8:11]
	v_mfma_f32_16x16x32_bf16 v[52:55], v[160:163], v[182:185], 0
	v_mfma_f32_16x16x32_bf16 v[48:51], v[174:177], v[182:185], 0
	v_mfma_f32_16x16x32_bf16 v[36:39], v[160:163], v[190:193], 0
	v_mfma_f32_16x16x32_bf16 v[32:35], v[174:177], v[190:193], 0
	v_mfma_f32_16x16x32_bf16 v[20:23], v[160:163], v[198:201], 0
	v_mfma_f32_16x16x32_bf16 v[16:19], v[174:177], v[198:201], 0
	v_mfma_f32_16x16x32_bf16 v[4:7], v[160:163], v[206:209], 0
	v_mfma_f32_16x16x32_bf16 v[0:3], v[174:177], v[206:209], 0
	v_mfma_f32_16x16x32_bf16 v[52:55], v[170:173], v[186:189], v[52:55]
	v_mfma_f32_16x16x32_bf16 v[48:51], v[178:181], v[186:189], v[48:51]
	v_mfma_f32_16x16x32_bf16 v[36:39], v[170:173], v[194:197], v[36:39]
	v_mfma_f32_16x16x32_bf16 v[32:35], v[178:181], v[194:197], v[32:35]
	v_mfma_f32_16x16x32_bf16 v[20:23], v[170:173], v[202:205], v[20:23]
	v_mfma_f32_16x16x32_bf16 v[16:19], v[178:181], v[202:205], v[16:19]
	v_mfma_f32_16x16x32_bf16 v[4:7], v[170:173], v[210:213], v[4:7]
	v_mfma_f32_16x16x32_bf16 v[0:3], v[178:181], v[210:213], v[0:3]
	s_setprio 0
	s_barrier
; #define PG8_STAGE(bufoff, gbase, voff) do { _Pragma("unroll") for (int _i = 0; _i < 2; ++_i) \
;         __builtin_amdgcn_global_load_lds((const unsigned*)((const char*)(gbase) + (voff)[_i]), (LAS unsigned*)(lds + (bufoff) + ldsw + _i * 8192), 16, 0, 0); } while (0)
; #define PG8_LDA(dst, b, h) do { _Pragma("unroll") for (int m = 0; m < 4; ++m) _Pragma("unroll") for (int k = 0; k < 2; ++k) dst[m][k] = *(const LAS bf16x8*)(lds + PG8_SA(b, h) + aoff + m * 2048 + k * 1024); } while (0)
; #define PG8_LDB(dst, b, h) do { _Pragma("unroll") for (int n = 0; n < 2; ++n) _Pragma("unroll") for (int k = 0; k < 2; ++k) dst[n][k] = *(const LAS bf16x8*)(lds + PG8_SB(b, h) + boff + n * 2048 + k * 1024); } while (0)
; #define PG8_MMA(ai, bj, At, Bt) do { __builtin_amdgcn_s_setprio(1); _Pragma("unroll") for (int m = 0; m < 4; ++m) _Pragma("unroll") for (int n = 0; n < 2; ++n) _Pragma("unroll") for (int k = 0; k < 2; ++k) \
;         acc[ai][bj][m][n] = __builtin_amdgcn_mfma_f32_16x16x32_bf16(Bt[n][k], At[m][k], acc[ai][bj][m][n], 0, 0, 0); __builtin_amdgcn_s_setprio(0); } while (0)
; #define PG8_WAIT_V(n) asm volatile("s_waitcnt vmcnt(" #n ")" ::: "memory")
; #define PG8_WAIT_L(n) asm volatile("s_waitcnt lgkmcnt(" #n ")" ::: "memory")
; #define PG8_BAR __builtin_amdgcn_s_barrier()
; #define PG8_SCHED __builtin_amdgcn_sched_barrier(0)
; template <class Epi, bool ALIGN_EPI, int K, int LDA, int LDB>
; __device__ __forceinline__ void gemm_phase(LAS unsigned char* lds, const int wid, const Gemm g, const StaticOrder& S, const Epi& E) {
;     ...
;             PG8_LDB(B0, 1, 0); PG8_LDB(B1, 1, 1); PG8_SCHED; PG8_LDA(At, 1, 0); PG8_STAGE(PG8_SA(0, 1), a2 + hA, voffA);
;             PG8_WAIT_V(8); PG8_WAIT_L(0); PG8_BAR; PG8_MMA(0, 0, At, B0); PG8_MMA(0, 1, At, B1); PG8_BAR; PG8_SCHED;
;             PG8_LDA(At, 1, 1); PG8_STAGE(PG8_SB(1, 0), b3, voffB); PG8_STAGE(PG8_SB(1, 1), b3 + hB, voffB); PG8_STAGE(PG8_SA(1, 0), a3, voffA);
;             PG8_WAIT_V(8); PG8_WAIT_L(0); PG8_BAR; PG8_MMA(1, 0, At, B0); PG8_MMA(1, 1, At, B1); PG8_BAR; PG8_SCHED;
;         }
	s_add_i32 s52, 0, 0x18000
	s_add_i32 s53, 0, 0x1c000
	v_add_u32_e32 v132, s52, v166
	v_add_u32_e32 v178, s53, v166
	ds_read_b128 v[120:123], v132
	ds_read_b128 v[124:127], v132 offset:1024
	ds_read_b128 v[128:131], v132 offset:2048
	ds_read_b128 v[132:135], v132 offset:3072
	ds_read_b128 v[160:163], v178
	ds_read_b128 v[170:173], v178 offset:1024
	ds_read_b128 v[174:177], v178 offset:2048
	ds_read_b128 v[178:181], v178 offset:3072
	s_add_u32 s26, s34, 0xb0000
	s_addc_u32 s27, s35, 0
	s_mov_b32 m0, s38
	ds_read_b128 v[182:185], v169 offset:32768
	ds_read_b128 v[186:189], v169 offset:33792
	ds_read_b128 v[190:193], v169 offset:34816
	ds_read_b128 v[194:197], v169 offset:35840
	ds_read_b128 v[198:201], v169 offset:36864
	ds_read_b128 v[202:205], v169 offset:37888
	ds_read_b128 v[206:209], v169 offset:38912
	ds_read_b128 v[210:213], v169 offset:39936
	global_load_lds_dwordx4 v144, s[26:27]
	s_mov_b32 m0, s39
	s_nop 0
	global_load_lds_dwordx4 v148, s[26:27]
	s_waitcnt vmcnt(8)
	s_waitcnt lgkmcnt(0)
	s_barrier
	s_setprio 1
	s_waitcnt lgkmcnt(0)
	v_mfma_f32_16x16x32_bf16 v[140:143], v[120:123], v[182:185], v[140:143]
	v_mfma_f32_16x16x32_bf16 v[136:139], v[128:131], v[182:185], v[136:139]
	v_mfma_f32_16x16x32_bf16 v[108:111], v[120:123], v[190:193], v[108:111]
	v_mfma_f32_16x16x32_bf16 v[104:107], v[128:131], v[190:193], v[104:107]
	v_mfma_f32_16x16x32_bf16 v[92:95], v[120:123], v[198:201], v[92:95]
	v_mfma_f32_16x16x32_bf16 v[88:91], v[128:131], v[198:201], v[88:91]
	v_mfma_f32_16x16x32_bf16 v[76:79], v[120:123], v[206:209], v[76:79]
	v_mfma_f32_16x16x32_bf16 v[72:75], v[128:131], v[206:209], v[72:75]
	v_mfma_f32_16x16x32_bf16 v[140:143], v[124:127], v[186:189], v[140:143]
	v_mfma_f32_16x16x32_bf16 v[136:139], v[132:135], v[186:189], v[136:139]
	v_mfma_f32_16x16x32_bf16 v[108:111], v[124:127], v[194:197], v[108:111]
	v_mfma_f32_16x16x32_bf16 v[104:107], v[132:135], v[194:197], v[104:107]
	v_mfma_f32_16x16x32_bf16 v[92:95], v[124:127], v[202:205], v[92:95]
	v_mfma_f32_16x16x32_bf16 v[88:91], v[132:135], v[202:205], v[88:91]
	v_mfma_f32_16x16x32_bf16 v[76:79], v[124:127], v[210:213], v[76:79]
	v_mfma_f32_16x16x32_bf16 v[72:75], v[132:135], v[210:213], v[72:75]
	v_mfma_f32_16x16x32_bf16 v[116:119], v[160:163], v[182:185], v[116:119]
	v_mfma_f32_16x16x32_bf16 v[112:115], v[174:177], v[182:185], v[112:115]
	v_mfma_f32_16x16x32_bf16 v[100:103], v[160:163], v[190:193], v[100:103]
	v_mfma_f32_16x16x32_bf16 v[96:99], v[174:177], v[190:193], v[96:99]
	v_mfma_f32_16x16x32_bf16 v[84:87], v[160:163], v[198:201], v[84:87]
	v_mfma_f32_16x16x32_bf16 v[80:83], v[174:177], v[198:201], v[80:83]
	v_mfma_f32_16x16x32_bf16 v[68:71], v[160:163], v[206:209], v[68:71]
	v_mfma_f32_16x16x32_bf16 v[64:67], v[174:177], v[206:209], v[64:67]
	v_mfma_f32_16x16x32_bf16 v[116:119], v[170:173], v[186:189], v[116:119]
	v_mfma_f32_16x16x32_bf16 v[112:115], v[178:181], v[186:189], v[112:115]
	v_mfma_f32_16x16x32_bf16 v[100:103], v[170:173], v[194:197], v[100:103]
	v_mfma_f32_16x16x32_bf16 v[96:99], v[178:181], v[194:197], v[96:99]
	v_mfma_f32_16x16x32_bf16 v[84:87], v[170:173], v[202:205], v[84:87]
	v_mfma_f32_16x16x32_bf16 v[80:83], v[178:181], v[202:205], v[80:83]
	v_mfma_f32_16x16x32_bf16 v[68:71], v[170:173], v[210:213], v[68:71]
	v_mfma_f32_16x16x32_bf16 v[64:67], v[178:181], v[210:213], v[64:67]
	s_setprio 0
	s_barrier
	s_add_i32 s26, s52, s33
	s_mov_b32 m0, s26
	ds_read_b128 v[182:185], v169 offset:49152
	ds_read_b128 v[186:189], v169 offset:50176
	ds_read_b128 v[190:193], v169 offset:51200
	ds_read_b128 v[194:197], v169 offset:52224
	ds_read_b128 v[198:201], v169 offset:53248
	ds_read_b128 v[202:205], v169 offset:54272
	ds_read_b128 v[206:209], v169 offset:55296
	ds_read_b128 v[210:213], v169 offset:56320
	global_load_lds_dwordx4 v146, s[98:99]
	s_add_i32 m0, s26, 0x2000
	s_add_u32 s26, s30, 0xb0080
	s_addc_u32 s27, s31, 0
	s_add_i32 s30, s53, s33
	global_load_lds_dwordx4 v150, s[98:99]
	s_mov_b32 m0, s30
	s_nop 0
	global_load_lds_dwordx4 v146, s[26:27]
	s_add_i32 m0, s30, 0x2000
	s_nop 0
	global_load_lds_dwordx4 v150, s[26:27]
	s_mov_b32 m0, s48
	s_nop 0
	global_load_lds_dwordx4 v144, s[100:101]
	s_mov_b32 m0, s49
	s_nop 0
	global_load_lds_dwordx4 v148, s[100:101]
	s_waitcnt vmcnt(8)
	s_waitcnt lgkmcnt(0)
	s_barrier
	s_setprio 1
	s_waitcnt lgkmcnt(0)
	v_mfma_f32_16x16x32_bf16 v[60:63], v[120:123], v[182:185], v[60:63]
	v_mfma_f32_16x16x32_bf16 v[56:59], v[128:131], v[182:185], v[56:59]
	v_mfma_f32_16x16x32_bf16 v[44:47], v[120:123], v[190:193], v[44:47]
	v_mfma_f32_16x16x32_bf16 v[40:43], v[128:131], v[190:193], v[40:43]
	v_mfma_f32_16x16x32_bf16 v[28:31], v[120:123], v[198:201], v[28:31]
	v_mfma_f32_16x16x32_bf16 v[24:27], v[128:131], v[198:201], v[24:27]
	v_mfma_f32_16x16x32_bf16 v[12:15], v[120:123], v[206:209], v[12:15]
	v_mfma_f32_16x16x32_bf16 v[8:11], v[128:131], v[206:209], v[8:11]
	v_mfma_f32_16x16x32_bf16 v[60:63], v[124:127], v[186:189], v[60:63]
	v_mfma_f32_16x16x32_bf16 v[56:59], v[132:135], v[186:189], v[56:59]
	v_mfma_f32_16x16x32_bf16 v[44:47], v[124:127], v[194:197], v[44:47]
	v_mfma_f32_16x16x32_bf16 v[40:43], v[132:135], v[194:197], v[40:43]
	v_mfma_f32_16x16x32_bf16 v[28:31], v[124:127], v[202:205], v[28:31]
	v_mfma_f32_16x16x32_bf16 v[24:27], v[132:135], v[202:205], v[24:27]
	v_mfma_f32_16x16x32_bf16 v[12:15], v[124:127], v[210:213], v[12:15]
	v_mfma_f32_16x16x32_bf16 v[8:11], v[132:135], v[210:213], v[8:11]
	v_mfma_f32_16x16x32_bf16 v[52:55], v[160:163], v[182:185], v[52:55]
	v_mfma_f32_16x16x32_bf16 v[48:51], v[174:177], v[182:185], v[48:51]
	v_mfma_f32_16x16x32_bf16 v[36:39], v[160:163], v[190:193], v[36:39]
	v_mfma_f32_16x16x32_bf16 v[32:35], v[174:177], v[190:193], v[32:35]
	v_mfma_f32_16x16x32_bf16 v[20:23], v[160:163], v[198:201], v[20:23]
	v_mfma_f32_16x16x32_bf16 v[16:19], v[174:177], v[198:201], v[16:19]
	v_mfma_f32_16x16x32_bf16 v[4:7], v[160:163], v[206:209], v[4:7]
	v_mfma_f32_16x16x32_bf16 v[0:3], v[174:177], v[206:209], v[0:3]
	v_mfma_f32_16x16x32_bf16 v[52:55], v[170:173], v[186:189], v[52:55]
	v_mfma_f32_16x16x32_bf16 v[48:51], v[178:181], v[186:189], v[48:51]
	v_mfma_f32_16x16x32_bf16 v[36:39], v[170:173], v[194:197], v[36:39]
	v_mfma_f32_16x16x32_bf16 v[32:35], v[178:181], v[194:197], v[32:35]
	v_mfma_f32_16x16x32_bf16 v[20:23], v[170:173], v[202:205], v[20:23]
	v_mfma_f32_16x16x32_bf16 v[16:19], v[178:181], v[202:205], v[16:19]
	v_mfma_f32_16x16x32_bf16 v[4:7], v[170:173], v[210:213], v[4:7]
	v_mfma_f32_16x16x32_bf16 v[0:3], v[178:181], v[210:213], v[0:3]
	s_setprio 0
	s_barrier
	s_add_i32 s63, s63, 2
	s_add_u32 s61, s61, 0x100
	s_addc_u32 s62, s62, 0
	s_mov_b64 s[26:27], s[28:29]
